# v12 + LDS-DMA pieces issued before the ds_reads in every bf16 load segment
# baseline (speedup 1.0000x reference)
.LBB0_642:
	s_add_i32 s18, s71, 0xffe80080
	s_cmp_eq_u32 s58, s73
	s_cselect_b32 s74, s69, s18
	s_cselect_b32 s76, s70, s72
	s_or_b32 s75, s74, 0x80
	s_add_i32 s18, s71, 0xfff80000
	s_mov_b32 m0, s59
	s_nop 0
	buffer_load_dwordx4 v137, s[12:15], s18 offen lds
	s_mov_b32 m0, s60
	s_nop 0
	buffer_load_dwordx4 v137, s[12:15], s71 offen lds
	ds_read_b128 v[148:151], v139
	ds_read_b128 v[152:155], v139 offset:1024
	ds_read_b128 v[156:159], v139 offset:2048
	ds_read_b128 v[160:163], v139 offset:3072
	ds_read_b128 v[164:167], v140
	ds_read_b128 v[168:171], v140 offset:1024
	ds_read_b128 v[172:175], v140 offset:2048
	ds_read_b128 v[176:179], v140 offset:3072
	ds_read_b128 v[180:183], v141
	ds_read_b128 v[184:187], v141 offset:1024
	ds_read_b128 v[188:191], v141 offset:2048
	ds_read_b128 v[192:195], v141 offset:3072
	ds_read_b128 v[196:199], v141 offset:4096
	ds_read_b128 v[200:203], v141 offset:5120
	ds_read_b128 v[204:207], v141 offset:6144
	ds_read_b128 v[208:211], v141 offset:7168
	s_waitcnt vmcnt(8)
	s_waitcnt lgkmcnt(0)
	s_setprio 1
	v_mfma_f32_16x16x32_bf16 v[118:121], v[148:151], v[180:183], v[118:121]
	s_barrier
	v_mfma_f32_16x16x32_bf16 v[118:121], v[152:155], v[184:187], v[118:121]
	v_mfma_f32_16x16x32_bf16 v[114:117], v[156:159], v[180:183], v[114:117]
	v_mfma_f32_16x16x32_bf16 v[114:117], v[160:163], v[184:187], v[114:117]
	v_mfma_f32_16x16x32_bf16 v[126:129], v[164:167], v[180:183], v[126:129]
	v_mfma_f32_16x16x32_bf16 v[126:129], v[168:171], v[184:187], v[126:129]
	v_mfma_f32_16x16x32_bf16 v[122:125], v[172:175], v[180:183], v[122:125]
	v_mfma_f32_16x16x32_bf16 v[122:125], v[176:179], v[184:187], v[122:125]
	v_mfma_f32_16x16x32_bf16 v[98:101], v[172:175], v[188:191], v[98:101]
	v_mfma_f32_16x16x32_bf16 v[98:101], v[176:179], v[192:195], v[98:101]
	v_mfma_f32_16x16x32_bf16 v[106:109], v[164:167], v[188:191], v[106:109]
	v_mfma_f32_16x16x32_bf16 v[106:109], v[168:171], v[192:195], v[106:109]
	v_mfma_f32_16x16x32_bf16 v[102:105], v[156:159], v[188:191], v[102:105]
	v_mfma_f32_16x16x32_bf16 v[102:105], v[160:163], v[192:195], v[102:105]
	v_mfma_f32_16x16x32_bf16 v[110:113], v[148:151], v[188:191], v[110:113]
	v_mfma_f32_16x16x32_bf16 v[110:113], v[152:155], v[192:195], v[110:113]
	v_mfma_f32_16x16x32_bf16 v[94:97], v[148:151], v[196:199], v[94:97]
	v_mfma_f32_16x16x32_bf16 v[94:97], v[152:155], v[200:203], v[94:97]
	v_mfma_f32_16x16x32_bf16 v[86:89], v[156:159], v[196:199], v[86:89]
	v_mfma_f32_16x16x32_bf16 v[86:89], v[160:163], v[200:203], v[86:89]
	v_mfma_f32_16x16x32_bf16 v[90:93], v[164:167], v[196:199], v[90:93]
	v_mfma_f32_16x16x32_bf16 v[90:93], v[168:171], v[200:203], v[90:93]
	v_mfma_f32_16x16x32_bf16 v[82:85], v[172:175], v[196:199], v[82:85]
	v_mfma_f32_16x16x32_bf16 v[82:85], v[176:179], v[200:203], v[82:85]
	v_mfma_f32_16x16x32_bf16 v[70:73], v[172:175], v[204:207], v[70:73]
	v_mfma_f32_16x16x32_bf16 v[70:73], v[176:179], v[208:211], v[70:73]
	v_mfma_f32_16x16x32_bf16 v[74:77], v[164:167], v[204:207], v[74:77]
	v_mfma_f32_16x16x32_bf16 v[74:77], v[168:171], v[208:211], v[74:77]
	v_mfma_f32_16x16x32_bf16 v[66:69], v[156:159], v[204:207], v[66:69]
	v_mfma_f32_16x16x32_bf16 v[66:69], v[160:163], v[208:211], v[66:69]
	v_mfma_f32_16x16x32_bf16 v[78:81], v[148:151], v[204:207], v[78:81]
	v_mfma_f32_16x16x32_bf16 v[78:81], v[152:155], v[208:211], v[78:81]
	s_setprio 0
	s_barrier
	s_mov_b32 m0, s30
	s_mov_b32 s18, s14
	s_mov_b32 s19, s15
	buffer_load_dwordx4 v138, s[16:19], s76 offen lds
	s_add_i32 s77, s76, 0x80000
	s_mov_b32 m0, s31
	s_nop 0
	buffer_load_dwordx4 v138, s[16:19], s77 offen lds
	s_add_i32 s77, s76, 0x100000
	s_mov_b32 m0, s44
	s_nop 0
	buffer_load_dwordx4 v138, s[16:19], s77 offen lds
	s_add_i32 s77, s76, 0x180000
	s_mov_b32 m0, s45
	s_nop 0
	buffer_load_dwordx4 v138, s[16:19], s77 offen lds
	s_mov_b32 m0, s27
	s_add_i32 s77, s74, 0x80000
	buffer_load_dwordx4 v137, s[12:15], s74 offen lds
	s_mov_b32 m0, s46
	s_nop 0
	buffer_load_dwordx4 v137, s[12:15], s77 offen lds
	ds_read_b128 v[180:183], v141 offset:16384
	ds_read_b128 v[184:187], v141 offset:17408
	ds_read_b128 v[188:191], v141 offset:18432
	ds_read_b128 v[192:195], v141 offset:19456
	ds_read_b128 v[196:199], v141 offset:20480
	ds_read_b128 v[200:203], v141 offset:21504
	ds_read_b128 v[204:207], v141 offset:22528
	ds_read_b128 v[208:211], v141 offset:23552
	s_waitcnt vmcnt(8)
	s_waitcnt lgkmcnt(0)
	s_setprio 1
	v_mfma_f32_16x16x32_bf16 v[62:65], v[148:151], v[180:183], v[62:65]
	s_barrier
	v_mfma_f32_16x16x32_bf16 v[62:65], v[152:155], v[184:187], v[62:65]
	v_mfma_f32_16x16x32_bf16 v[54:57], v[156:159], v[180:183], v[54:57]
	v_mfma_f32_16x16x32_bf16 v[54:57], v[160:163], v[184:187], v[54:57]
	v_mfma_f32_16x16x32_bf16 v[58:61], v[164:167], v[180:183], v[58:61]
	v_mfma_f32_16x16x32_bf16 v[58:61], v[168:171], v[184:187], v[58:61]
	v_mfma_f32_16x16x32_bf16 v[50:53], v[172:175], v[180:183], v[50:53]
	v_mfma_f32_16x16x32_bf16 v[50:53], v[176:179], v[184:187], v[50:53]
	v_mfma_f32_16x16x32_bf16 v[34:37], v[172:175], v[188:191], v[34:37]
	v_mfma_f32_16x16x32_bf16 v[34:37], v[176:179], v[192:195], v[34:37]
	v_mfma_f32_16x16x32_bf16 v[42:45], v[164:167], v[188:191], v[42:45]
	v_mfma_f32_16x16x32_bf16 v[42:45], v[168:171], v[192:195], v[42:45]
	v_mfma_f32_16x16x32_bf16 v[38:41], v[156:159], v[188:191], v[38:41]
	v_mfma_f32_16x16x32_bf16 v[38:41], v[160:163], v[192:195], v[38:41]
	v_mfma_f32_16x16x32_bf16 v[46:49], v[148:151], v[188:191], v[46:49]
	v_mfma_f32_16x16x32_bf16 v[46:49], v[152:155], v[192:195], v[46:49]
	v_mfma_f32_16x16x32_bf16 v[30:33], v[148:151], v[196:199], v[30:33]
	v_mfma_f32_16x16x32_bf16 v[30:33], v[152:155], v[200:203], v[30:33]
	v_mfma_f32_16x16x32_bf16 v[22:25], v[156:159], v[196:199], v[22:25]
	v_mfma_f32_16x16x32_bf16 v[22:25], v[160:163], v[200:203], v[22:25]
	v_mfma_f32_16x16x32_bf16 v[26:29], v[164:167], v[196:199], v[26:29]
	v_mfma_f32_16x16x32_bf16 v[26:29], v[168:171], v[200:203], v[26:29]
	v_mfma_f32_16x16x32_bf16 v[18:21], v[172:175], v[196:199], v[18:21]
	v_mfma_f32_16x16x32_bf16 v[18:21], v[176:179], v[200:203], v[18:21]
	v_mfma_f32_16x16x32_bf16 v[2:5], v[172:175], v[204:207], v[2:5]
	v_mfma_f32_16x16x32_bf16 v[2:5], v[176:179], v[208:211], v[2:5]
	v_mfma_f32_16x16x32_bf16 v[10:13], v[164:167], v[204:207], v[10:13]
	v_mfma_f32_16x16x32_bf16 v[10:13], v[168:171], v[208:211], v[10:13]
	v_mfma_f32_16x16x32_bf16 v[6:9], v[156:159], v[204:207], v[6:9]
	v_mfma_f32_16x16x32_bf16 v[6:9], v[160:163], v[208:211], v[6:9]
	v_mfma_f32_16x16x32_bf16 v[14:17], v[148:151], v[204:207], v[14:17]
	v_mfma_f32_16x16x32_bf16 v[14:17], v[152:155], v[208:211], v[14:17]
	s_setprio 0
	s_barrier
	s_mov_b32 m0, s47
	s_add_i32 s77, s74, 0x100000
	buffer_load_dwordx4 v137, s[12:15], s77 offen lds
	s_add_i32 s77, s74, 0x180000
	s_mov_b32 m0, s48
	s_nop 0
	buffer_load_dwordx4 v137, s[12:15], s77 offen lds
	ds_read_b128 v[148:151], v142
	ds_read_b128 v[152:155], v142 offset:1024
	ds_read_b128 v[156:159], v142 offset:2048
	ds_read_b128 v[160:163], v142 offset:3072
	ds_read_b128 v[164:167], v143
	ds_read_b128 v[168:171], v143 offset:1024
	ds_read_b128 v[172:175], v143 offset:2048
	ds_read_b128 v[176:179], v143 offset:3072
	ds_read_b128 v[180:183], v141 offset:32768
	ds_read_b128 v[184:187], v141 offset:33792
	ds_read_b128 v[188:191], v141 offset:34816
	ds_read_b128 v[192:195], v141 offset:35840
	ds_read_b128 v[196:199], v141 offset:36864
	ds_read_b128 v[200:203], v141 offset:37888
	ds_read_b128 v[204:207], v141 offset:38912
	ds_read_b128 v[208:211], v141 offset:39936
	s_waitcnt vmcnt(8)
	s_waitcnt lgkmcnt(0)
	s_setprio 1
	v_mfma_f32_16x16x32_bf16 v[118:121], v[148:151], v[180:183], v[118:121]
	s_barrier
	v_mfma_f32_16x16x32_bf16 v[118:121], v[152:155], v[184:187], v[118:121]
	v_mfma_f32_16x16x32_bf16 v[114:117], v[156:159], v[180:183], v[114:117]
	v_mfma_f32_16x16x32_bf16 v[114:117], v[160:163], v[184:187], v[114:117]
	v_mfma_f32_16x16x32_bf16 v[126:129], v[164:167], v[180:183], v[126:129]
	v_mfma_f32_16x16x32_bf16 v[126:129], v[168:171], v[184:187], v[126:129]
	v_mfma_f32_16x16x32_bf16 v[122:125], v[172:175], v[180:183], v[122:125]
	v_mfma_f32_16x16x32_bf16 v[122:125], v[176:179], v[184:187], v[122:125]
	v_mfma_f32_16x16x32_bf16 v[98:101], v[172:175], v[188:191], v[98:101]
	v_mfma_f32_16x16x32_bf16 v[98:101], v[176:179], v[192:195], v[98:101]
	v_mfma_f32_16x16x32_bf16 v[106:109], v[164:167], v[188:191], v[106:109]
	v_mfma_f32_16x16x32_bf16 v[106:109], v[168:171], v[192:195], v[106:109]
	v_mfma_f32_16x16x32_bf16 v[102:105], v[156:159], v[188:191], v[102:105]
	v_mfma_f32_16x16x32_bf16 v[102:105], v[160:163], v[192:195], v[102:105]
	v_mfma_f32_16x16x32_bf16 v[110:113], v[148:151], v[188:191], v[110:113]
	v_mfma_f32_16x16x32_bf16 v[110:113], v[152:155], v[192:195], v[110:113]
	v_mfma_f32_16x16x32_bf16 v[94:97], v[148:151], v[196:199], v[94:97]
	v_mfma_f32_16x16x32_bf16 v[94:97], v[152:155], v[200:203], v[94:97]
	v_mfma_f32_16x16x32_bf16 v[86:89], v[156:159], v[196:199], v[86:89]
	v_mfma_f32_16x16x32_bf16 v[86:89], v[160:163], v[200:203], v[86:89]
	v_mfma_f32_16x16x32_bf16 v[90:93], v[164:167], v[196:199], v[90:93]
	v_mfma_f32_16x16x32_bf16 v[90:93], v[168:171], v[200:203], v[90:93]
	v_mfma_f32_16x16x32_bf16 v[82:85], v[172:175], v[196:199], v[82:85]
	v_mfma_f32_16x16x32_bf16 v[82:85], v[176:179], v[200:203], v[82:85]
	v_mfma_f32_16x16x32_bf16 v[70:73], v[172:175], v[204:207], v[70:73]
	v_mfma_f32_16x16x32_bf16 v[70:73], v[176:179], v[208:211], v[70:73]
	v_mfma_f32_16x16x32_bf16 v[74:77], v[164:167], v[204:207], v[74:77]
	v_mfma_f32_16x16x32_bf16 v[74:77], v[168:171], v[208:211], v[74:77]
	v_mfma_f32_16x16x32_bf16 v[66:69], v[156:159], v[204:207], v[66:69]
	v_mfma_f32_16x16x32_bf16 v[66:69], v[160:163], v[208:211], v[66:69]
	v_mfma_f32_16x16x32_bf16 v[78:81], v[148:151], v[204:207], v[78:81]
	v_mfma_f32_16x16x32_bf16 v[78:81], v[152:155], v[208:211], v[78:81]
	s_setprio 0
	s_barrier
	s_mov_b32 m0, s50
	s_or_b32 s77, s76, 0x80
	buffer_load_dwordx4 v138, s[16:19], s77 offen lds
	s_add_i32 s77, s76, 0x80080
	s_mov_b32 m0, s51
	s_add_i32 s74, s74, 0x80080
	buffer_load_dwordx4 v138, s[16:19], s77 offen lds
	s_add_i32 s77, s76, 0x100080
	s_mov_b32 m0, s54
	s_add_i32 s76, s76, 0x180080
	buffer_load_dwordx4 v138, s[16:19], s77 offen lds
	s_mov_b32 m0, s55
	s_nop 0
	buffer_load_dwordx4 v138, s[16:19], s76 offen lds
	s_mov_b32 m0, s52
	s_nop 0
	buffer_load_dwordx4 v137, s[12:15], s75 offen lds
	s_mov_b32 m0, s53
	s_nop 0
	buffer_load_dwordx4 v137, s[12:15], s74 offen lds
	ds_read_b128 v[180:183], v141 offset:49152
	ds_read_b128 v[184:187], v141 offset:50176
	ds_read_b128 v[188:191], v141 offset:51200
	ds_read_b128 v[192:195], v141 offset:52224
	ds_read_b128 v[196:199], v141 offset:53248
	ds_read_b128 v[200:203], v141 offset:54272
	ds_read_b128 v[204:207], v141 offset:55296
	ds_read_b128 v[208:211], v141 offset:56320
	s_waitcnt vmcnt(8)
	s_waitcnt lgkmcnt(0)
	s_setprio 1
	v_mfma_f32_16x16x32_bf16 v[62:65], v[148:151], v[180:183], v[62:65]
	s_barrier
	v_mfma_f32_16x16x32_bf16 v[62:65], v[152:155], v[184:187], v[62:65]
	v_mfma_f32_16x16x32_bf16 v[54:57], v[156:159], v[180:183], v[54:57]
	v_mfma_f32_16x16x32_bf16 v[54:57], v[160:163], v[184:187], v[54:57]
	v_mfma_f32_16x16x32_bf16 v[58:61], v[164:167], v[180:183], v[58:61]
	v_mfma_f32_16x16x32_bf16 v[58:61], v[168:171], v[184:187], v[58:61]
	v_mfma_f32_16x16x32_bf16 v[50:53], v[172:175], v[180:183], v[50:53]
	v_mfma_f32_16x16x32_bf16 v[50:53], v[176:179], v[184:187], v[50:53]
	v_mfma_f32_16x16x32_bf16 v[34:37], v[172:175], v[188:191], v[34:37]
	v_mfma_f32_16x16x32_bf16 v[34:37], v[176:179], v[192:195], v[34:37]
	v_mfma_f32_16x16x32_bf16 v[42:45], v[164:167], v[188:191], v[42:45]
	v_mfma_f32_16x16x32_bf16 v[42:45], v[168:171], v[192:195], v[42:45]
	v_mfma_f32_16x16x32_bf16 v[38:41], v[156:159], v[188:191], v[38:41]
	v_mfma_f32_16x16x32_bf16 v[38:41], v[160:163], v[192:195], v[38:41]
	v_mfma_f32_16x16x32_bf16 v[46:49], v[148:151], v[188:191], v[46:49]
	v_mfma_f32_16x16x32_bf16 v[46:49], v[152:155], v[192:195], v[46:49]
	v_mfma_f32_16x16x32_bf16 v[30:33], v[148:151], v[196:199], v[30:33]
	v_mfma_f32_16x16x32_bf16 v[30:33], v[152:155], v[200:203], v[30:33]
	v_mfma_f32_16x16x32_bf16 v[22:25], v[156:159], v[196:199], v[22:25]
	v_mfma_f32_16x16x32_bf16 v[22:25], v[160:163], v[200:203], v[22:25]
	v_mfma_f32_16x16x32_bf16 v[26:29], v[164:167], v[196:199], v[26:29]
	v_mfma_f32_16x16x32_bf16 v[26:29], v[168:171], v[200:203], v[26:29]
	v_mfma_f32_16x16x32_bf16 v[18:21], v[172:175], v[196:199], v[18:21]
	v_mfma_f32_16x16x32_bf16 v[18:21], v[176:179], v[200:203], v[18:21]
	v_mfma_f32_16x16x32_bf16 v[2:5], v[172:175], v[204:207], v[2:5]
	v_mfma_f32_16x16x32_bf16 v[2:5], v[176:179], v[208:211], v[2:5]
	v_mfma_f32_16x16x32_bf16 v[10:13], v[164:167], v[204:207], v[10:13]
	v_mfma_f32_16x16x32_bf16 v[10:13], v[168:171], v[208:211], v[10:13]
	v_mfma_f32_16x16x32_bf16 v[6:9], v[156:159], v[204:207], v[6:9]
	v_mfma_f32_16x16x32_bf16 v[6:9], v[160:163], v[208:211], v[6:9]
	v_mfma_f32_16x16x32_bf16 v[14:17], v[148:151], v[204:207], v[14:17]
	v_mfma_f32_16x16x32_bf16 v[14:17], v[152:155], v[208:211], v[14:17]
	s_setprio 0
	s_barrier
	s_add_i32 s73, s73, 2
	s_addk_i32 s71, 0x100
	s_addk_i32 s72, 0x100
	s_cmp_ge_i32 s73, s3
	s_cbranch_scc0 .LBB0_642
	s_and_b64 vcc, exec, s[42:43]
	s_cbranch_vccz .LBB0_645

.LBB0_799:
	s_add_i32 s18, s77, 0xffbf8080
	s_cmp_eq_u32 s62, s79
	s_cselect_b32 s80, s6, s18
	s_cselect_b32 s82, s7, s78
	s_or_b32 s81, s80, 0x80
	s_add_i32 s18, s77, 0xffea8000
	s_mov_b32 m0, s63
	s_nop 0
	buffer_load_dwordx4 v208, s[12:15], s18 offen lds
	s_mov_b32 m0, s66
	s_nop 0
	buffer_load_dwordx4 v208, s[12:15], s77 offen lds
	ds_read_b128 v[134:137], v210
	ds_read_b128 v[138:141], v210 offset:1024
	ds_read_b128 v[142:145], v210 offset:2048
	ds_read_b128 v[148:151], v210 offset:3072
	ds_read_b128 v[152:155], v211
	ds_read_b128 v[156:159], v211 offset:1024
	ds_read_b128 v[160:163], v211 offset:2048
	ds_read_b128 v[164:167], v211 offset:3072
	ds_read_b128 v[168:171], v212
	ds_read_b128 v[172:175], v212 offset:1024
	ds_read_b128 v[176:179], v212 offset:2048
	ds_read_b128 v[180:183], v212 offset:3072
	ds_read_b128 v[184:187], v212 offset:4096
	ds_read_b128 v[188:191], v212 offset:5120
	ds_read_b128 v[192:195], v212 offset:6144
	ds_read_b128 v[196:199], v212 offset:7168
	s_waitcnt vmcnt(8)
	s_waitcnt lgkmcnt(0)
	s_setprio 1
	v_mfma_f32_16x16x32_bf16 v[126:129], v[134:137], v[168:171], v[126:129]
	s_barrier
	v_mfma_f32_16x16x32_bf16 v[126:129], v[138:141], v[172:175], v[126:129]
	v_mfma_f32_16x16x32_bf16 v[122:125], v[142:145], v[168:171], v[122:125]
	v_mfma_f32_16x16x32_bf16 v[122:125], v[148:151], v[172:175], v[122:125]
	v_mfma_f32_16x16x32_bf16 v[110:113], v[152:155], v[168:171], v[110:113]
	v_mfma_f32_16x16x32_bf16 v[110:113], v[156:159], v[172:175], v[110:113]
	v_mfma_f32_16x16x32_bf16 v[102:105], v[160:163], v[168:171], v[102:105]
	v_mfma_f32_16x16x32_bf16 v[102:105], v[164:167], v[172:175], v[102:105]
	v_mfma_f32_16x16x32_bf16 v[86:89], v[160:163], v[176:179], v[86:89]
	v_mfma_f32_16x16x32_bf16 v[86:89], v[164:167], v[180:183], v[86:89]
	v_mfma_f32_16x16x32_bf16 v[94:97], v[152:155], v[176:179], v[94:97]
	v_mfma_f32_16x16x32_bf16 v[94:97], v[156:159], v[180:183], v[94:97]
	v_mfma_f32_16x16x32_bf16 v[114:117], v[142:145], v[176:179], v[114:117]
	v_mfma_f32_16x16x32_bf16 v[114:117], v[148:151], v[180:183], v[114:117]
	v_mfma_f32_16x16x32_bf16 v[118:121], v[134:137], v[176:179], v[118:121]
	v_mfma_f32_16x16x32_bf16 v[118:121], v[138:141], v[180:183], v[118:121]
	v_mfma_f32_16x16x32_bf16 v[106:109], v[134:137], v[184:187], v[106:109]
	v_mfma_f32_16x16x32_bf16 v[106:109], v[138:141], v[188:191], v[106:109]
	v_mfma_f32_16x16x32_bf16 v[98:101], v[142:145], v[184:187], v[98:101]
	v_mfma_f32_16x16x32_bf16 v[98:101], v[148:151], v[188:191], v[98:101]
	v_mfma_f32_16x16x32_bf16 v[78:81], v[152:155], v[184:187], v[78:81]
	v_mfma_f32_16x16x32_bf16 v[78:81], v[156:159], v[188:191], v[78:81]
	v_mfma_f32_16x16x32_bf16 v[74:77], v[160:163], v[184:187], v[74:77]
	v_mfma_f32_16x16x32_bf16 v[74:77], v[164:167], v[188:191], v[74:77]
	v_mfma_f32_16x16x32_bf16 v[66:69], v[160:163], v[192:195], v[66:69]
	v_mfma_f32_16x16x32_bf16 v[66:69], v[164:167], v[196:199], v[66:69]
	v_mfma_f32_16x16x32_bf16 v[70:73], v[152:155], v[192:195], v[70:73]
	v_mfma_f32_16x16x32_bf16 v[70:73], v[156:159], v[196:199], v[70:73]
	v_mfma_f32_16x16x32_bf16 v[82:85], v[142:145], v[192:195], v[82:85]
	v_mfma_f32_16x16x32_bf16 v[82:85], v[148:151], v[196:199], v[82:85]
	v_mfma_f32_16x16x32_bf16 v[90:93], v[134:137], v[192:195], v[90:93]
	v_mfma_f32_16x16x32_bf16 v[90:93], v[138:141], v[196:199], v[90:93]
	s_setprio 0
	s_barrier
	s_mov_b32 m0, s25
	s_mov_b32 s18, s14
	s_mov_b32 s19, s15
	buffer_load_dwordx4 v209, s[16:19], s82 offen lds
	s_add_i32 s83, s82, 0x158000
	s_mov_b32 m0, s27
	s_nop 0
	buffer_load_dwordx4 v209, s[16:19], s83 offen lds
	s_add_i32 s83, s82, 0x2b0000
	s_mov_b32 m0, s30
	s_nop 0
	buffer_load_dwordx4 v209, s[16:19], s83 offen lds
	s_add_i32 s83, s82, 0x408000
	s_mov_b32 m0, s31
	s_nop 0
	buffer_load_dwordx4 v209, s[16:19], s83 offen lds
	s_mov_b32 m0, s21
	s_add_i32 s83, s80, 0x158000
	buffer_load_dwordx4 v208, s[12:15], s80 offen lds
	s_mov_b32 m0, s48
	s_nop 0
	buffer_load_dwordx4 v208, s[12:15], s83 offen lds
	ds_read_b128 v[168:171], v212 offset:16384
	ds_read_b128 v[172:175], v212 offset:17408
	ds_read_b128 v[176:179], v212 offset:18432
	ds_read_b128 v[180:183], v212 offset:19456
	ds_read_b128 v[184:187], v212 offset:20480
	ds_read_b128 v[188:191], v212 offset:21504
	ds_read_b128 v[192:195], v212 offset:22528
	ds_read_b128 v[196:199], v212 offset:23552
	s_waitcnt vmcnt(8)
	s_waitcnt lgkmcnt(0)
	s_setprio 1
	v_mfma_f32_16x16x32_bf16 v[62:65], v[134:137], v[168:171], v[62:65]
	s_barrier
	v_mfma_f32_16x16x32_bf16 v[62:65], v[138:141], v[172:175], v[62:65]
	v_mfma_f32_16x16x32_bf16 v[58:61], v[142:145], v[168:171], v[58:61]
	v_mfma_f32_16x16x32_bf16 v[58:61], v[148:151], v[172:175], v[58:61]
	v_mfma_f32_16x16x32_bf16 v[46:49], v[152:155], v[168:171], v[46:49]
	v_mfma_f32_16x16x32_bf16 v[46:49], v[156:159], v[172:175], v[46:49]
	v_mfma_f32_16x16x32_bf16 v[38:41], v[160:163], v[168:171], v[38:41]
	v_mfma_f32_16x16x32_bf16 v[38:41], v[164:167], v[172:175], v[38:41]
	v_mfma_f32_16x16x32_bf16 v[22:25], v[160:163], v[176:179], v[22:25]
	v_mfma_f32_16x16x32_bf16 v[22:25], v[164:167], v[180:183], v[22:25]
	v_mfma_f32_16x16x32_bf16 v[30:33], v[152:155], v[176:179], v[30:33]
	v_mfma_f32_16x16x32_bf16 v[30:33], v[156:159], v[180:183], v[30:33]
	v_mfma_f32_16x16x32_bf16 v[50:53], v[142:145], v[176:179], v[50:53]
	v_mfma_f32_16x16x32_bf16 v[50:53], v[148:151], v[180:183], v[50:53]
	v_mfma_f32_16x16x32_bf16 v[54:57], v[134:137], v[176:179], v[54:57]
	v_mfma_f32_16x16x32_bf16 v[54:57], v[138:141], v[180:183], v[54:57]
	v_mfma_f32_16x16x32_bf16 v[42:45], v[134:137], v[184:187], v[42:45]
	v_mfma_f32_16x16x32_bf16 v[42:45], v[138:141], v[188:191], v[42:45]
	v_mfma_f32_16x16x32_bf16 v[34:37], v[142:145], v[184:187], v[34:37]
	v_mfma_f32_16x16x32_bf16 v[34:37], v[148:151], v[188:191], v[34:37]
	v_mfma_f32_16x16x32_bf16 v[14:17], v[152:155], v[184:187], v[14:17]
	v_mfma_f32_16x16x32_bf16 v[14:17], v[156:159], v[188:191], v[14:17]
	v_mfma_f32_16x16x32_bf16 v[10:13], v[160:163], v[184:187], v[10:13]
	v_mfma_f32_16x16x32_bf16 v[10:13], v[164:167], v[188:191], v[10:13]
	v_mfma_f32_16x16x32_bf16 v[2:5], v[160:163], v[192:195], v[2:5]
	v_mfma_f32_16x16x32_bf16 v[2:5], v[164:167], v[196:199], v[2:5]
	v_mfma_f32_16x16x32_bf16 v[6:9], v[152:155], v[192:195], v[6:9]
	v_mfma_f32_16x16x32_bf16 v[6:9], v[156:159], v[196:199], v[6:9]
	v_mfma_f32_16x16x32_bf16 v[18:21], v[142:145], v[192:195], v[18:21]
	v_mfma_f32_16x16x32_bf16 v[18:21], v[148:151], v[196:199], v[18:21]
	v_mfma_f32_16x16x32_bf16 v[26:29], v[134:137], v[192:195], v[26:29]
	v_mfma_f32_16x16x32_bf16 v[26:29], v[138:141], v[196:199], v[26:29]
	s_setprio 0
	s_barrier
	s_mov_b32 m0, s49
	s_add_i32 s83, s80, 0x2b0000
	buffer_load_dwordx4 v208, s[12:15], s83 offen lds
	s_add_i32 s83, s80, 0x408000
	s_mov_b32 m0, s50
	s_nop 0
	buffer_load_dwordx4 v208, s[12:15], s83 offen lds
	ds_read_b128 v[134:137], v213
	ds_read_b128 v[138:141], v213 offset:1024
	ds_read_b128 v[142:145], v213 offset:2048
	ds_read_b128 v[148:151], v213 offset:3072
	ds_read_b128 v[152:155], v214
	ds_read_b128 v[156:159], v214 offset:1024
	ds_read_b128 v[160:163], v214 offset:2048
	ds_read_b128 v[164:167], v214 offset:3072
	ds_read_b128 v[168:171], v212 offset:32768
	ds_read_b128 v[172:175], v212 offset:33792
	ds_read_b128 v[176:179], v212 offset:34816
	ds_read_b128 v[180:183], v212 offset:35840
	ds_read_b128 v[184:187], v212 offset:36864
	ds_read_b128 v[188:191], v212 offset:37888
	ds_read_b128 v[192:195], v212 offset:38912
	ds_read_b128 v[196:199], v212 offset:39936
	s_waitcnt vmcnt(8)
	s_waitcnt lgkmcnt(0)
	s_setprio 1
	v_mfma_f32_16x16x32_bf16 v[126:129], v[134:137], v[168:171], v[126:129]
	s_barrier
	v_mfma_f32_16x16x32_bf16 v[126:129], v[138:141], v[172:175], v[126:129]
	v_mfma_f32_16x16x32_bf16 v[122:125], v[142:145], v[168:171], v[122:125]
	v_mfma_f32_16x16x32_bf16 v[122:125], v[148:151], v[172:175], v[122:125]
	v_mfma_f32_16x16x32_bf16 v[110:113], v[152:155], v[168:171], v[110:113]
	v_mfma_f32_16x16x32_bf16 v[110:113], v[156:159], v[172:175], v[110:113]
	v_mfma_f32_16x16x32_bf16 v[102:105], v[160:163], v[168:171], v[102:105]
	v_mfma_f32_16x16x32_bf16 v[102:105], v[164:167], v[172:175], v[102:105]
	v_mfma_f32_16x16x32_bf16 v[86:89], v[160:163], v[176:179], v[86:89]
	v_mfma_f32_16x16x32_bf16 v[86:89], v[164:167], v[180:183], v[86:89]
	v_mfma_f32_16x16x32_bf16 v[94:97], v[152:155], v[176:179], v[94:97]
	v_mfma_f32_16x16x32_bf16 v[94:97], v[156:159], v[180:183], v[94:97]
	v_mfma_f32_16x16x32_bf16 v[114:117], v[142:145], v[176:179], v[114:117]
	v_mfma_f32_16x16x32_bf16 v[114:117], v[148:151], v[180:183], v[114:117]
	v_mfma_f32_16x16x32_bf16 v[118:121], v[134:137], v[176:179], v[118:121]
	v_mfma_f32_16x16x32_bf16 v[118:121], v[138:141], v[180:183], v[118:121]
	v_mfma_f32_16x16x32_bf16 v[106:109], v[134:137], v[184:187], v[106:109]
	v_mfma_f32_16x16x32_bf16 v[106:109], v[138:141], v[188:191], v[106:109]
	v_mfma_f32_16x16x32_bf16 v[98:101], v[142:145], v[184:187], v[98:101]
	v_mfma_f32_16x16x32_bf16 v[98:101], v[148:151], v[188:191], v[98:101]
	v_mfma_f32_16x16x32_bf16 v[78:81], v[152:155], v[184:187], v[78:81]
	v_mfma_f32_16x16x32_bf16 v[78:81], v[156:159], v[188:191], v[78:81]
	v_mfma_f32_16x16x32_bf16 v[74:77], v[160:163], v[184:187], v[74:77]
	v_mfma_f32_16x16x32_bf16 v[74:77], v[164:167], v[188:191], v[74:77]
	v_mfma_f32_16x16x32_bf16 v[66:69], v[160:163], v[192:195], v[66:69]
	v_mfma_f32_16x16x32_bf16 v[66:69], v[164:167], v[196:199], v[66:69]
	v_mfma_f32_16x16x32_bf16 v[70:73], v[152:155], v[192:195], v[70:73]
	v_mfma_f32_16x16x32_bf16 v[70:73], v[156:159], v[196:199], v[70:73]
	v_mfma_f32_16x16x32_bf16 v[82:85], v[142:145], v[192:195], v[82:85]
	v_mfma_f32_16x16x32_bf16 v[82:85], v[148:151], v[196:199], v[82:85]
	v_mfma_f32_16x16x32_bf16 v[90:93], v[134:137], v[192:195], v[90:93]
	v_mfma_f32_16x16x32_bf16 v[90:93], v[138:141], v[196:199], v[90:93]
	s_setprio 0
	s_barrier
	s_mov_b32 m0, s54
	s_or_b32 s83, s82, 0x80
	buffer_load_dwordx4 v209, s[16:19], s83 offen lds
	s_add_i32 s83, s82, 0x158080
	s_mov_b32 m0, s55
	s_add_i32 s80, s80, 0x158080
	buffer_load_dwordx4 v209, s[16:19], s83 offen lds
	s_add_i32 s83, s82, 0x2b0080
	s_mov_b32 m0, s58
	s_add_i32 s82, s82, 0x408080
	buffer_load_dwordx4 v209, s[16:19], s83 offen lds
	s_mov_b32 m0, s59
	s_nop 0
	buffer_load_dwordx4 v209, s[16:19], s82 offen lds
	s_mov_b32 m0, s56
	s_nop 0
	buffer_load_dwordx4 v208, s[12:15], s81 offen lds
	s_mov_b32 m0, s57
	s_nop 0
	buffer_load_dwordx4 v208, s[12:15], s80 offen lds
	ds_read_b128 v[168:171], v212 offset:49152
	ds_read_b128 v[172:175], v212 offset:50176
	ds_read_b128 v[176:179], v212 offset:51200
	ds_read_b128 v[180:183], v212 offset:52224
	ds_read_b128 v[184:187], v212 offset:53248
	ds_read_b128 v[188:191], v212 offset:54272
	ds_read_b128 v[192:195], v212 offset:55296
	ds_read_b128 v[196:199], v212 offset:56320
	s_waitcnt vmcnt(8)
	s_waitcnt lgkmcnt(0)
	s_setprio 1
	v_mfma_f32_16x16x32_bf16 v[62:65], v[134:137], v[168:171], v[62:65]
	s_barrier
	v_mfma_f32_16x16x32_bf16 v[62:65], v[138:141], v[172:175], v[62:65]
	v_mfma_f32_16x16x32_bf16 v[58:61], v[142:145], v[168:171], v[58:61]
	v_mfma_f32_16x16x32_bf16 v[58:61], v[148:151], v[172:175], v[58:61]
	v_mfma_f32_16x16x32_bf16 v[46:49], v[152:155], v[168:171], v[46:49]
	v_mfma_f32_16x16x32_bf16 v[46:49], v[156:159], v[172:175], v[46:49]
	v_mfma_f32_16x16x32_bf16 v[38:41], v[160:163], v[168:171], v[38:41]
	v_mfma_f32_16x16x32_bf16 v[38:41], v[164:167], v[172:175], v[38:41]
	v_mfma_f32_16x16x32_bf16 v[22:25], v[160:163], v[176:179], v[22:25]
	v_mfma_f32_16x16x32_bf16 v[22:25], v[164:167], v[180:183], v[22:25]
	v_mfma_f32_16x16x32_bf16 v[30:33], v[152:155], v[176:179], v[30:33]
	v_mfma_f32_16x16x32_bf16 v[30:33], v[156:159], v[180:183], v[30:33]
	v_mfma_f32_16x16x32_bf16 v[50:53], v[142:145], v[176:179], v[50:53]
	v_mfma_f32_16x16x32_bf16 v[50:53], v[148:151], v[180:183], v[50:53]
	v_mfma_f32_16x16x32_bf16 v[54:57], v[134:137], v[176:179], v[54:57]
	v_mfma_f32_16x16x32_bf16 v[54:57], v[138:141], v[180:183], v[54:57]
	v_mfma_f32_16x16x32_bf16 v[42:45], v[134:137], v[184:187], v[42:45]
	v_mfma_f32_16x16x32_bf16 v[42:45], v[138:141], v[188:191], v[42:45]
	v_mfma_f32_16x16x32_bf16 v[34:37], v[142:145], v[184:187], v[34:37]
	v_mfma_f32_16x16x32_bf16 v[34:37], v[148:151], v[188:191], v[34:37]
	v_mfma_f32_16x16x32_bf16 v[14:17], v[152:155], v[184:187], v[14:17]
	v_mfma_f32_16x16x32_bf16 v[14:17], v[156:159], v[188:191], v[14:17]
	v_mfma_f32_16x16x32_bf16 v[10:13], v[160:163], v[184:187], v[10:13]
	v_mfma_f32_16x16x32_bf16 v[10:13], v[164:167], v[188:191], v[10:13]
	v_mfma_f32_16x16x32_bf16 v[2:5], v[160:163], v[192:195], v[2:5]
	v_mfma_f32_16x16x32_bf16 v[2:5], v[164:167], v[196:199], v[2:5]
	v_mfma_f32_16x16x32_bf16 v[6:9], v[152:155], v[192:195], v[6:9]
	v_mfma_f32_16x16x32_bf16 v[6:9], v[156:159], v[196:199], v[6:9]
	v_mfma_f32_16x16x32_bf16 v[18:21], v[142:145], v[192:195], v[18:21]
	v_mfma_f32_16x16x32_bf16 v[18:21], v[148:151], v[196:199], v[18:21]
	v_mfma_f32_16x16x32_bf16 v[26:29], v[134:137], v[192:195], v[26:29]
	v_mfma_f32_16x16x32_bf16 v[26:29], v[138:141], v[196:199], v[26:29]
	s_setprio 0
	s_barrier
	s_add_i32 s79, s79, 2
	s_addk_i32 s77, 0x100
	s_addk_i32 s78, 0x100
	s_cmp_ge_i32 s79, s3
	s_cbranch_scc0 .LBB0_799
	v_pk_mul_f32 v[184:185], v[128:129], 0.5 op_sel_hi:[1,0]
	v_pk_mul_f32 v[186:187], v[126:127], 0.5 op_sel_hi:[1,0]
	v_pk_mul_f32 v[188:189], v[124:125], 0.5 op_sel_hi:[1,0]
	v_pk_mul_f32 v[190:191], v[122:123], 0.5 op_sel_hi:[1,0]
	v_pk_mul_f32 v[198:199], v[112:113], 0.5 op_sel_hi:[1,0]
	v_pk_mul_f32 v[196:197], v[110:111], 0.5 op_sel_hi:[1,0]
	v_pk_mul_f32 v[194:195], v[104:105], 0.5 op_sel_hi:[1,0]
	v_pk_mul_f32 v[192:193], v[102:103], 0.5 op_sel_hi:[1,0]
	v_pk_mul_f32 v[182:183], v[120:121], 0.5 op_sel_hi:[1,0]
	v_pk_mul_f32 v[180:181], v[118:119], 0.5 op_sel_hi:[1,0]
	v_pk_mul_f32 v[178:179], v[116:117], 0.5 op_sel_hi:[1,0]
	v_pk_mul_f32 v[176:177], v[114:115], 0.5 op_sel_hi:[1,0]
	v_pk_mul_f32 v[172:173], v[96:97], 0.5 op_sel_hi:[1,0]
	v_pk_mul_f32 v[170:171], v[94:95], 0.5 op_sel_hi:[1,0]
	v_pk_mul_f32 v[168:169], v[88:89], 0.5 op_sel_hi:[1,0]
	v_pk_mul_f32 v[166:167], v[86:87], 0.5 op_sel_hi:[1,0]
	v_pk_mul_f32 v[164:165], v[108:109], 0.5 op_sel_hi:[1,0]
	v_pk_mul_f32 v[162:163], v[106:107], 0.5 op_sel_hi:[1,0]
	v_pk_mul_f32 v[160:161], v[100:101], 0.5 op_sel_hi:[1,0]
	v_pk_mul_f32 v[158:159], v[98:99], 0.5 op_sel_hi:[1,0]
	v_pk_mul_f32 v[156:157], v[80:81], 0.5 op_sel_hi:[1,0]
	v_pk_mul_f32 v[154:155], v[78:79], 0.5 op_sel_hi:[1,0]
	v_pk_mul_f32 v[152:153], v[76:77], 0.5 op_sel_hi:[1,0]
	v_pk_mul_f32 v[150:151], v[74:75], 0.5 op_sel_hi:[1,0]
	v_pk_mul_f32 v[144:145], v[92:93], 0.5 op_sel_hi:[1,0]
	v_pk_mul_f32 v[142:143], v[90:91], 0.5 op_sel_hi:[1,0]
	v_pk_mul_f32 v[140:141], v[84:85], 0.5 op_sel_hi:[1,0]
	v_pk_mul_f32 v[138:139], v[82:83], 0.5 op_sel_hi:[1,0]
	v_pk_mul_f32 v[136:137], v[72:73], 0.5 op_sel_hi:[1,0]
	v_pk_mul_f32 v[134:135], v[70:71], 0.5 op_sel_hi:[1,0]
	v_pk_mul_f32 v[128:129], v[68:69], 0.5 op_sel_hi:[1,0]
	v_pk_mul_f32 v[126:127], v[66:67], 0.5 op_sel_hi:[1,0]
	v_pk_mul_f32 v[122:123], v[64:65], 0.5 op_sel_hi:[1,0]
	v_pk_mul_f32 v[120:121], v[62:63], 0.5 op_sel_hi:[1,0]
	v_pk_mul_f32 v[118:119], v[60:61], 0.5 op_sel_hi:[1,0]
	v_pk_mul_f32 v[116:117], v[58:59], 0.5 op_sel_hi:[1,0]
	v_pk_mul_f32 v[112:113], v[48:49], 0.5 op_sel_hi:[1,0]
	v_pk_mul_f32 v[110:111], v[46:47], 0.5 op_sel_hi:[1,0]
	v_pk_mul_f32 v[108:109], v[40:41], 0.5 op_sel_hi:[1,0]
	v_pk_mul_f32 v[106:107], v[38:39], 0.5 op_sel_hi:[1,0]
	v_pk_mul_f32 v[104:105], v[56:57], 0.5 op_sel_hi:[1,0]
	v_pk_mul_f32 v[102:103], v[54:55], 0.5 op_sel_hi:[1,0]
	v_pk_mul_f32 v[100:101], v[52:53], 0.5 op_sel_hi:[1,0]
	v_pk_mul_f32 v[98:99], v[50:51], 0.5 op_sel_hi:[1,0]
	v_pk_mul_f32 v[96:97], v[32:33], 0.5 op_sel_hi:[1,0]
	v_pk_mul_f32 v[94:95], v[30:31], 0.5 op_sel_hi:[1,0]
	v_pk_mul_f32 v[92:93], v[24:25], 0.5 op_sel_hi:[1,0]
	v_pk_mul_f32 v[90:91], v[22:23], 0.5 op_sel_hi:[1,0]
	v_pk_mul_f32 v[88:89], v[44:45], 0.5 op_sel_hi:[1,0]
	v_pk_mul_f32 v[86:87], v[42:43], 0.5 op_sel_hi:[1,0]
	v_pk_mul_f32 v[84:85], v[36:37], 0.5 op_sel_hi:[1,0]
	v_pk_mul_f32 v[82:83], v[34:35], 0.5 op_sel_hi:[1,0]
	v_pk_mul_f32 v[80:81], v[16:17], 0.5 op_sel_hi:[1,0]
	v_pk_mul_f32 v[78:79], v[14:15], 0.5 op_sel_hi:[1,0]
	v_pk_mul_f32 v[76:77], v[12:13], 0.5 op_sel_hi:[1,0]
	v_pk_mul_f32 v[74:75], v[10:11], 0.5 op_sel_hi:[1,0]
	v_pk_mul_f32 v[72:73], v[28:29], 0.5 op_sel_hi:[1,0]
	v_pk_mul_f32 v[70:71], v[26:27], 0.5 op_sel_hi:[1,0]
	v_pk_mul_f32 v[68:69], v[20:21], 0.5 op_sel_hi:[1,0]
	v_pk_mul_f32 v[66:67], v[18:19], 0.5 op_sel_hi:[1,0]
	v_pk_mul_f32 v[64:65], v[8:9], 0.5 op_sel_hi:[1,0]
	v_pk_mul_f32 v[62:63], v[6:7], 0.5 op_sel_hi:[1,0]
	v_pk_mul_f32 v[60:61], v[4:5], 0.5 op_sel_hi:[1,0]
	v_pk_mul_f32 v[58:59], v[2:3], 0.5 op_sel_hi:[1,0]
	s_and_b64 vcc, exec, s[38:39]
	s_cbranch_vccz .LBB0_802

.LBB0_892:
	s_add_i32 s18, s8, 0xffe80080
	s_cmp_eq_u32 s77, s52
	s_cselect_b32 s53, s6, s18
	s_cselect_b32 s58, s7, s9
	s_or_b32 s57, s53, 0x80
	s_add_i32 s18, s8, 0xfff80000
	s_mov_b32 m0, s78
	s_nop 0
	buffer_load_dwordx4 v170, s[12:15], s18 offen lds
	s_mov_b32 m0, s79
	s_nop 0
	buffer_load_dwordx4 v170, s[12:15], s8 offen lds
	ds_read_b128 v[130:133], v172
	ds_read_b128 v[134:137], v172 offset:1024
	ds_read_b128 v[148:151], v172 offset:2048
	ds_read_b128 v[152:155], v172 offset:3072
	ds_read_b128 v[156:159], v173
	ds_read_b128 v[160:163], v173 offset:1024
	ds_read_b128 v[164:167], v173 offset:2048
	ds_read_b128 v[180:183], v173 offset:3072
	ds_read_b128 v[184:187], v174
	ds_read_b128 v[188:191], v174 offset:1024
	ds_read_b128 v[192:195], v174 offset:2048
	ds_read_b128 v[196:199], v174 offset:3072
	ds_read_b128 v[200:203], v174 offset:4096
	ds_read_b128 v[204:207], v174 offset:5120
	ds_read_b128 v[208:211], v174 offset:6144
	ds_read_b128 v[212:215], v174 offset:7168
	s_waitcnt vmcnt(8)
	s_waitcnt lgkmcnt(0)
	s_setprio 1
	v_mfma_f32_16x16x32_bf16 v[126:129], v[130:133], v[184:187], v[126:129]
	s_barrier
	v_mfma_f32_16x16x32_bf16 v[126:129], v[134:137], v[188:191], v[126:129]
	v_mfma_f32_16x16x32_bf16 v[118:121], v[148:151], v[184:187], v[118:121]
	v_mfma_f32_16x16x32_bf16 v[118:121], v[152:155], v[188:191], v[118:121]
	v_mfma_f32_16x16x32_bf16 v[122:125], v[156:159], v[184:187], v[122:125]
	v_mfma_f32_16x16x32_bf16 v[122:125], v[160:163], v[188:191], v[122:125]
	v_mfma_f32_16x16x32_bf16 v[114:117], v[164:167], v[184:187], v[114:117]
	v_mfma_f32_16x16x32_bf16 v[114:117], v[180:183], v[188:191], v[114:117]
	v_mfma_f32_16x16x32_bf16 v[98:101], v[164:167], v[192:195], v[98:101]
	v_mfma_f32_16x16x32_bf16 v[98:101], v[180:183], v[196:199], v[98:101]
	v_mfma_f32_16x16x32_bf16 v[106:109], v[156:159], v[192:195], v[106:109]
	v_mfma_f32_16x16x32_bf16 v[106:109], v[160:163], v[196:199], v[106:109]
	v_mfma_f32_16x16x32_bf16 v[102:105], v[148:151], v[192:195], v[102:105]
	v_mfma_f32_16x16x32_bf16 v[102:105], v[152:155], v[196:199], v[102:105]
	v_mfma_f32_16x16x32_bf16 v[110:113], v[130:133], v[192:195], v[110:113]
	v_mfma_f32_16x16x32_bf16 v[110:113], v[134:137], v[196:199], v[110:113]
	v_mfma_f32_16x16x32_bf16 v[94:97], v[130:133], v[200:203], v[94:97]
	v_mfma_f32_16x16x32_bf16 v[94:97], v[134:137], v[204:207], v[94:97]
	v_mfma_f32_16x16x32_bf16 v[90:93], v[148:151], v[200:203], v[90:93]
	v_mfma_f32_16x16x32_bf16 v[90:93], v[152:155], v[204:207], v[90:93]
	v_mfma_f32_16x16x32_bf16 v[86:89], v[156:159], v[200:203], v[86:89]
	v_mfma_f32_16x16x32_bf16 v[86:89], v[160:163], v[204:207], v[86:89]
	v_mfma_f32_16x16x32_bf16 v[82:85], v[164:167], v[200:203], v[82:85]
	v_mfma_f32_16x16x32_bf16 v[82:85], v[180:183], v[204:207], v[82:85]
	v_mfma_f32_16x16x32_bf16 v[66:69], v[164:167], v[208:211], v[66:69]
	v_mfma_f32_16x16x32_bf16 v[66:69], v[180:183], v[212:215], v[66:69]
	v_mfma_f32_16x16x32_bf16 v[74:77], v[156:159], v[208:211], v[74:77]
	v_mfma_f32_16x16x32_bf16 v[74:77], v[160:163], v[212:215], v[74:77]
	v_mfma_f32_16x16x32_bf16 v[70:73], v[148:151], v[208:211], v[70:73]
	v_mfma_f32_16x16x32_bf16 v[70:73], v[152:155], v[212:215], v[70:73]
	v_mfma_f32_16x16x32_bf16 v[78:81], v[130:133], v[208:211], v[78:81]
	v_mfma_f32_16x16x32_bf16 v[78:81], v[134:137], v[212:215], v[78:81]
	s_setprio 0
	s_barrier
	s_mov_b32 m0, s27
	s_mov_b32 s18, s14
	s_mov_b32 s19, s15
	buffer_load_dwordx4 v171, s[16:19], s58 offen lds
	s_add_i32 s59, s58, 0x80000
	s_mov_b32 m0, s60
	s_nop 0
	buffer_load_dwordx4 v171, s[16:19], s59 offen lds
	s_add_i32 s59, s58, 0x100000
	s_mov_b32 m0, s61
	s_nop 0
	buffer_load_dwordx4 v171, s[16:19], s59 offen lds
	s_add_i32 s59, s58, 0x180000
	s_mov_b32 m0, s62
	s_nop 0
	buffer_load_dwordx4 v171, s[16:19], s59 offen lds
	s_mov_b32 m0, s25
	s_add_i32 s59, s53, 0x80000
	buffer_load_dwordx4 v170, s[12:15], s53 offen lds
	s_mov_b32 m0, s63
	s_nop 0
	buffer_load_dwordx4 v170, s[12:15], s59 offen lds
	ds_read_b128 v[184:187], v174 offset:16384
	ds_read_b128 v[188:191], v174 offset:17408
	ds_read_b128 v[192:195], v174 offset:18432
	ds_read_b128 v[196:199], v174 offset:19456
	ds_read_b128 v[200:203], v174 offset:20480
	ds_read_b128 v[204:207], v174 offset:21504
	ds_read_b128 v[208:211], v174 offset:22528
	ds_read_b128 v[212:215], v174 offset:23552
	s_waitcnt vmcnt(8)
	s_waitcnt lgkmcnt(0)
	s_setprio 1
	v_mfma_f32_16x16x32_bf16 v[62:65], v[130:133], v[184:187], v[62:65]
	s_barrier
	v_mfma_f32_16x16x32_bf16 v[62:65], v[134:137], v[188:191], v[62:65]
	v_mfma_f32_16x16x32_bf16 v[54:57], v[148:151], v[184:187], v[54:57]
	v_mfma_f32_16x16x32_bf16 v[54:57], v[152:155], v[188:191], v[54:57]
	v_mfma_f32_16x16x32_bf16 v[58:61], v[156:159], v[184:187], v[58:61]
	v_mfma_f32_16x16x32_bf16 v[58:61], v[160:163], v[188:191], v[58:61]
	v_mfma_f32_16x16x32_bf16 v[50:53], v[164:167], v[184:187], v[50:53]
	v_mfma_f32_16x16x32_bf16 v[50:53], v[180:183], v[188:191], v[50:53]
	v_mfma_f32_16x16x32_bf16 v[34:37], v[164:167], v[192:195], v[34:37]
	v_mfma_f32_16x16x32_bf16 v[34:37], v[180:183], v[196:199], v[34:37]
	v_mfma_f32_16x16x32_bf16 v[42:45], v[156:159], v[192:195], v[42:45]
	v_mfma_f32_16x16x32_bf16 v[42:45], v[160:163], v[196:199], v[42:45]
	v_mfma_f32_16x16x32_bf16 v[38:41], v[148:151], v[192:195], v[38:41]
	v_mfma_f32_16x16x32_bf16 v[38:41], v[152:155], v[196:199], v[38:41]
	v_mfma_f32_16x16x32_bf16 v[46:49], v[130:133], v[192:195], v[46:49]
	v_mfma_f32_16x16x32_bf16 v[46:49], v[134:137], v[196:199], v[46:49]
	v_mfma_f32_16x16x32_bf16 v[30:33], v[130:133], v[200:203], v[30:33]
	v_mfma_f32_16x16x32_bf16 v[30:33], v[134:137], v[204:207], v[30:33]
	v_mfma_f32_16x16x32_bf16 v[22:25], v[148:151], v[200:203], v[22:25]
	v_mfma_f32_16x16x32_bf16 v[22:25], v[152:155], v[204:207], v[22:25]
	v_mfma_f32_16x16x32_bf16 v[26:29], v[156:159], v[200:203], v[26:29]
	v_mfma_f32_16x16x32_bf16 v[26:29], v[160:163], v[204:207], v[26:29]
	v_mfma_f32_16x16x32_bf16 v[18:21], v[164:167], v[200:203], v[18:21]
	v_mfma_f32_16x16x32_bf16 v[18:21], v[180:183], v[204:207], v[18:21]
	v_mfma_f32_16x16x32_bf16 v[2:5], v[164:167], v[208:211], v[2:5]
	v_mfma_f32_16x16x32_bf16 v[2:5], v[180:183], v[212:215], v[2:5]
	v_mfma_f32_16x16x32_bf16 v[10:13], v[156:159], v[208:211], v[10:13]
	v_mfma_f32_16x16x32_bf16 v[10:13], v[160:163], v[212:215], v[10:13]
	v_mfma_f32_16x16x32_bf16 v[6:9], v[148:151], v[208:211], v[6:9]
	v_mfma_f32_16x16x32_bf16 v[6:9], v[152:155], v[212:215], v[6:9]
	v_mfma_f32_16x16x32_bf16 v[14:17], v[130:133], v[208:211], v[14:17]
	v_mfma_f32_16x16x32_bf16 v[14:17], v[134:137], v[212:215], v[14:17]
	s_setprio 0
	s_barrier
	s_mov_b32 m0, s64
	s_add_i32 s59, s53, 0x100000
	buffer_load_dwordx4 v170, s[12:15], s59 offen lds
	s_add_i32 s59, s53, 0x180000
	s_mov_b32 m0, s65
	s_nop 0
	buffer_load_dwordx4 v170, s[12:15], s59 offen lds
	ds_read_b128 v[130:133], v175
	ds_read_b128 v[134:137], v175 offset:1024
	ds_read_b128 v[148:151], v175 offset:2048
	ds_read_b128 v[152:155], v175 offset:3072
	ds_read_b128 v[156:159], v176
	ds_read_b128 v[160:163], v176 offset:1024
	ds_read_b128 v[164:167], v176 offset:2048
	ds_read_b128 v[180:183], v176 offset:3072
	ds_read_b128 v[184:187], v174 offset:32768
	ds_read_b128 v[188:191], v174 offset:33792
	ds_read_b128 v[192:195], v174 offset:34816
	ds_read_b128 v[196:199], v174 offset:35840
	ds_read_b128 v[200:203], v174 offset:36864
	ds_read_b128 v[204:207], v174 offset:37888
	ds_read_b128 v[208:211], v174 offset:38912
	ds_read_b128 v[212:215], v174 offset:39936
	s_waitcnt vmcnt(8)
	s_waitcnt lgkmcnt(0)
	s_setprio 1
	v_mfma_f32_16x16x32_bf16 v[126:129], v[130:133], v[184:187], v[126:129]
	s_barrier
	v_mfma_f32_16x16x32_bf16 v[126:129], v[134:137], v[188:191], v[126:129]
	v_mfma_f32_16x16x32_bf16 v[118:121], v[148:151], v[184:187], v[118:121]
	v_mfma_f32_16x16x32_bf16 v[118:121], v[152:155], v[188:191], v[118:121]
	v_mfma_f32_16x16x32_bf16 v[122:125], v[156:159], v[184:187], v[122:125]
	v_mfma_f32_16x16x32_bf16 v[122:125], v[160:163], v[188:191], v[122:125]
	v_mfma_f32_16x16x32_bf16 v[114:117], v[164:167], v[184:187], v[114:117]
	v_mfma_f32_16x16x32_bf16 v[114:117], v[180:183], v[188:191], v[114:117]
	v_mfma_f32_16x16x32_bf16 v[98:101], v[164:167], v[192:195], v[98:101]
	v_mfma_f32_16x16x32_bf16 v[98:101], v[180:183], v[196:199], v[98:101]
	v_mfma_f32_16x16x32_bf16 v[106:109], v[156:159], v[192:195], v[106:109]
	v_mfma_f32_16x16x32_bf16 v[106:109], v[160:163], v[196:199], v[106:109]
	v_mfma_f32_16x16x32_bf16 v[102:105], v[148:151], v[192:195], v[102:105]
	v_mfma_f32_16x16x32_bf16 v[102:105], v[152:155], v[196:199], v[102:105]
	v_mfma_f32_16x16x32_bf16 v[110:113], v[130:133], v[192:195], v[110:113]
	v_mfma_f32_16x16x32_bf16 v[110:113], v[134:137], v[196:199], v[110:113]
	v_mfma_f32_16x16x32_bf16 v[94:97], v[130:133], v[200:203], v[94:97]
	v_mfma_f32_16x16x32_bf16 v[94:97], v[134:137], v[204:207], v[94:97]
	v_mfma_f32_16x16x32_bf16 v[90:93], v[148:151], v[200:203], v[90:93]
	v_mfma_f32_16x16x32_bf16 v[90:93], v[152:155], v[204:207], v[90:93]
	v_mfma_f32_16x16x32_bf16 v[86:89], v[156:159], v[200:203], v[86:89]
	v_mfma_f32_16x16x32_bf16 v[86:89], v[160:163], v[204:207], v[86:89]
	v_mfma_f32_16x16x32_bf16 v[82:85], v[164:167], v[200:203], v[82:85]
	v_mfma_f32_16x16x32_bf16 v[82:85], v[180:183], v[204:207], v[82:85]
	v_mfma_f32_16x16x32_bf16 v[66:69], v[164:167], v[208:211], v[66:69]
	v_mfma_f32_16x16x32_bf16 v[66:69], v[180:183], v[212:215], v[66:69]
	v_mfma_f32_16x16x32_bf16 v[74:77], v[156:159], v[208:211], v[74:77]
	v_mfma_f32_16x16x32_bf16 v[74:77], v[160:163], v[212:215], v[74:77]
	v_mfma_f32_16x16x32_bf16 v[70:73], v[148:151], v[208:211], v[70:73]
	v_mfma_f32_16x16x32_bf16 v[70:73], v[152:155], v[212:215], v[70:73]
	v_mfma_f32_16x16x32_bf16 v[78:81], v[130:133], v[208:211], v[78:81]
	v_mfma_f32_16x16x32_bf16 v[78:81], v[134:137], v[212:215], v[78:81]
	s_setprio 0
	s_barrier
	s_mov_b32 m0, s70
	s_or_b32 s59, s58, 0x80
	buffer_load_dwordx4 v171, s[16:19], s59 offen lds
	s_add_i32 s59, s58, 0x80080
	s_mov_b32 m0, s71
	s_add_i32 s53, s53, 0x80080
	buffer_load_dwordx4 v171, s[16:19], s59 offen lds
	s_add_i32 s59, s58, 0x100080
	s_mov_b32 m0, s74
	s_add_i32 s58, s58, 0x180080
	buffer_load_dwordx4 v171, s[16:19], s59 offen lds
	s_mov_b32 m0, s75
	s_nop 0
	buffer_load_dwordx4 v171, s[16:19], s58 offen lds
	s_mov_b32 m0, s72
	s_nop 0
	buffer_load_dwordx4 v170, s[12:15], s57 offen lds
	s_mov_b32 m0, s73
	s_nop 0
	buffer_load_dwordx4 v170, s[12:15], s53 offen lds
	ds_read_b128 v[184:187], v174 offset:49152
	ds_read_b128 v[188:191], v174 offset:50176
	ds_read_b128 v[192:195], v174 offset:51200
	ds_read_b128 v[196:199], v174 offset:52224
	ds_read_b128 v[200:203], v174 offset:53248
	ds_read_b128 v[204:207], v174 offset:54272
	ds_read_b128 v[208:211], v174 offset:55296
	ds_read_b128 v[212:215], v174 offset:56320
	s_waitcnt vmcnt(8)
	s_waitcnt lgkmcnt(0)
	s_setprio 1
	v_mfma_f32_16x16x32_bf16 v[62:65], v[130:133], v[184:187], v[62:65]
	s_barrier
	v_mfma_f32_16x16x32_bf16 v[62:65], v[134:137], v[188:191], v[62:65]
	v_mfma_f32_16x16x32_bf16 v[54:57], v[148:151], v[184:187], v[54:57]
	v_mfma_f32_16x16x32_bf16 v[54:57], v[152:155], v[188:191], v[54:57]
	v_mfma_f32_16x16x32_bf16 v[58:61], v[156:159], v[184:187], v[58:61]
	v_mfma_f32_16x16x32_bf16 v[58:61], v[160:163], v[188:191], v[58:61]
	v_mfma_f32_16x16x32_bf16 v[50:53], v[164:167], v[184:187], v[50:53]
	v_mfma_f32_16x16x32_bf16 v[50:53], v[180:183], v[188:191], v[50:53]
	v_mfma_f32_16x16x32_bf16 v[34:37], v[164:167], v[192:195], v[34:37]
	v_mfma_f32_16x16x32_bf16 v[34:37], v[180:183], v[196:199], v[34:37]
	v_mfma_f32_16x16x32_bf16 v[42:45], v[156:159], v[192:195], v[42:45]
	v_mfma_f32_16x16x32_bf16 v[42:45], v[160:163], v[196:199], v[42:45]
	v_mfma_f32_16x16x32_bf16 v[38:41], v[148:151], v[192:195], v[38:41]
	v_mfma_f32_16x16x32_bf16 v[38:41], v[152:155], v[196:199], v[38:41]
	v_mfma_f32_16x16x32_bf16 v[46:49], v[130:133], v[192:195], v[46:49]
	v_mfma_f32_16x16x32_bf16 v[46:49], v[134:137], v[196:199], v[46:49]
	v_mfma_f32_16x16x32_bf16 v[30:33], v[130:133], v[200:203], v[30:33]
	v_mfma_f32_16x16x32_bf16 v[30:33], v[134:137], v[204:207], v[30:33]
	v_mfma_f32_16x16x32_bf16 v[22:25], v[148:151], v[200:203], v[22:25]
	v_mfma_f32_16x16x32_bf16 v[22:25], v[152:155], v[204:207], v[22:25]
	v_mfma_f32_16x16x32_bf16 v[26:29], v[156:159], v[200:203], v[26:29]
	v_mfma_f32_16x16x32_bf16 v[26:29], v[160:163], v[204:207], v[26:29]
	v_mfma_f32_16x16x32_bf16 v[18:21], v[164:167], v[200:203], v[18:21]
	v_mfma_f32_16x16x32_bf16 v[18:21], v[180:183], v[204:207], v[18:21]
	v_mfma_f32_16x16x32_bf16 v[2:5], v[164:167], v[208:211], v[2:5]
	v_mfma_f32_16x16x32_bf16 v[2:5], v[180:183], v[212:215], v[2:5]
	v_mfma_f32_16x16x32_bf16 v[10:13], v[156:159], v[208:211], v[10:13]
	v_mfma_f32_16x16x32_bf16 v[10:13], v[160:163], v[212:215], v[10:13]
	v_mfma_f32_16x16x32_bf16 v[6:9], v[148:151], v[208:211], v[6:9]
	v_mfma_f32_16x16x32_bf16 v[6:9], v[152:155], v[212:215], v[6:9]
	v_mfma_f32_16x16x32_bf16 v[14:17], v[130:133], v[208:211], v[14:17]
	v_mfma_f32_16x16x32_bf16 v[14:17], v[134:137], v[212:215], v[14:17]
	s_setprio 0
	s_barrier
	s_add_i32 s52, s52, 2
	s_addk_i32 s8, 0x100
	s_addk_i32 s9, 0x100
	s_cmp_ge_i32 s52, s21
	s_cbranch_scc0 .LBB0_892
	s_and_b64 vcc, exec, s[48:49]
	s_cbranch_vccz .LBB0_895

.LBB0_1020:
	v_add_u32_e32 v142, 0x10000, v162
	v_add_u32_e32 v150, 0x14000, v162
	ds_read_b128 v[130:133], v142
	ds_read_b128 v[134:137], v142 offset:1024
	ds_read_b128 v[138:141], v142 offset:2048
	ds_read_b128 v[142:145], v142 offset:3072
	ds_read_b128 v[154:157], v150
	ds_read_b128 v[164:167], v150 offset:1024
	ds_read_b128 v[168:171], v150 offset:2048
	ds_read_b128 v[172:175], v150 offset:3072
	s_add_i32 s90, s6, 0x100
	s_add_i32 s7, s88, s6
	s_cmp_eq_u32 s81, s89
	s_cselect_b32 s91, 0, s90
	s_cselect_b32 s93, s87, s7
	s_add_i32 s91, s91, s70
	s_or_b32 s92, s91, 0x80
	s_add_i32 s6, s3, s6
	s_mov_b32 m0, s82
	s_add_i32 s7, s6, 0x20080
	ds_read_b128 v[176:179], v163
	ds_read_b128 v[180:183], v163 offset:1024
	ds_read_b128 v[184:187], v163 offset:2048
	ds_read_b128 v[188:191], v163 offset:3072
	ds_read_b128 v[192:195], v163 offset:4096
	ds_read_b128 v[196:199], v163 offset:5120
	ds_read_b128 v[200:203], v163 offset:6144
	ds_read_b128 v[204:207], v163 offset:7168
	buffer_load_dwordx4 v161, s[12:15], s7 offen lds
	s_add_i32 s6, s6, 0x30080
	s_mov_b32 m0, s83
	s_nop 0
	buffer_load_dwordx4 v161, s[12:15], s6 offen lds
	s_waitcnt vmcnt(8)
	s_waitcnt lgkmcnt(0)
	s_setprio 1
	v_mfma_f32_16x16x32_bf16 v[126:129], v[130:133], v[176:179], v[126:129]
	s_barrier
	v_mfma_f32_16x16x32_bf16 v[126:129], v[134:137], v[180:183], v[126:129]
	v_mfma_f32_16x16x32_bf16 v[122:125], v[138:141], v[176:179], v[122:125]
	v_mfma_f32_16x16x32_bf16 v[122:125], v[142:145], v[180:183], v[122:125]
	v_mfma_f32_16x16x32_bf16 v[118:121], v[154:157], v[176:179], v[118:121]
	v_mfma_f32_16x16x32_bf16 v[118:121], v[164:167], v[180:183], v[118:121]
	v_mfma_f32_16x16x32_bf16 v[114:117], v[168:171], v[176:179], v[114:117]
	v_mfma_f32_16x16x32_bf16 v[114:117], v[172:175], v[180:183], v[114:117]
	v_mfma_f32_16x16x32_bf16 v[98:101], v[168:171], v[184:187], v[98:101]
	v_mfma_f32_16x16x32_bf16 v[98:101], v[172:175], v[188:191], v[98:101]
	v_mfma_f32_16x16x32_bf16 v[102:105], v[154:157], v[184:187], v[102:105]
	v_mfma_f32_16x16x32_bf16 v[102:105], v[164:167], v[188:191], v[102:105]
	v_mfma_f32_16x16x32_bf16 v[106:109], v[138:141], v[184:187], v[106:109]
	v_mfma_f32_16x16x32_bf16 v[106:109], v[142:145], v[188:191], v[106:109]
	v_mfma_f32_16x16x32_bf16 v[110:113], v[130:133], v[184:187], v[110:113]
	v_mfma_f32_16x16x32_bf16 v[110:113], v[134:137], v[188:191], v[110:113]
	v_mfma_f32_16x16x32_bf16 v[94:97], v[130:133], v[192:195], v[94:97]
	v_mfma_f32_16x16x32_bf16 v[94:97], v[134:137], v[196:199], v[94:97]
	v_mfma_f32_16x16x32_bf16 v[90:93], v[138:141], v[192:195], v[90:93]
	v_mfma_f32_16x16x32_bf16 v[90:93], v[142:145], v[196:199], v[90:93]
	v_mfma_f32_16x16x32_bf16 v[86:89], v[154:157], v[192:195], v[86:89]
	v_mfma_f32_16x16x32_bf16 v[86:89], v[164:167], v[196:199], v[86:89]
	v_mfma_f32_16x16x32_bf16 v[82:85], v[168:171], v[192:195], v[82:85]
	v_mfma_f32_16x16x32_bf16 v[82:85], v[172:175], v[196:199], v[82:85]
	v_mfma_f32_16x16x32_bf16 v[66:69], v[168:171], v[200:203], v[66:69]
	v_mfma_f32_16x16x32_bf16 v[66:69], v[172:175], v[204:207], v[66:69]
	v_mfma_f32_16x16x32_bf16 v[70:73], v[154:157], v[200:203], v[70:73]
	v_mfma_f32_16x16x32_bf16 v[70:73], v[164:167], v[204:207], v[70:73]
	v_mfma_f32_16x16x32_bf16 v[74:77], v[138:141], v[200:203], v[74:77]
	v_mfma_f32_16x16x32_bf16 v[74:77], v[142:145], v[204:207], v[74:77]
	v_mfma_f32_16x16x32_bf16 v[78:81], v[130:133], v[200:203], v[78:81]
	v_mfma_f32_16x16x32_bf16 v[78:81], v[134:137], v[204:207], v[78:81]
	s_setprio 0
	s_barrier
	s_mov_b32 m0, s66
	s_mov_b32 s6, s14
	s_mov_b32 s7, s15
	buffer_load_dwordx4 v160, s[4:7], s93 offen lds
	s_add_i32 s94, s93, 0x10000
	s_mov_b32 m0, s67
	s_nop 0
	buffer_load_dwordx4 v160, s[4:7], s94 offen lds
	s_add_i32 s94, s93, 0x20000
	s_mov_b32 m0, s68
	s_nop 0
	buffer_load_dwordx4 v160, s[4:7], s94 offen lds
	s_add_i32 s94, s93, 0x30000
	s_mov_b32 m0, s69
	s_nop 0
	buffer_load_dwordx4 v160, s[4:7], s94 offen lds
	s_mov_b32 m0, s65
	s_add_i32 s94, s91, 0x10000
	buffer_load_dwordx4 v161, s[12:15], s91 offen lds
	s_mov_b32 m0, s71
	s_nop 0
	buffer_load_dwordx4 v161, s[12:15], s94 offen lds
	ds_read_b128 v[176:179], v163 offset:16384
	ds_read_b128 v[180:183], v163 offset:17408
	ds_read_b128 v[184:187], v163 offset:18432
	ds_read_b128 v[188:191], v163 offset:19456
	ds_read_b128 v[192:195], v163 offset:20480
	ds_read_b128 v[196:199], v163 offset:21504
	ds_read_b128 v[200:203], v163 offset:22528
	ds_read_b128 v[204:207], v163 offset:23552
	s_waitcnt vmcnt(8)
	s_waitcnt lgkmcnt(0)
	s_setprio 1
	v_mfma_f32_16x16x32_bf16 v[62:65], v[130:133], v[176:179], v[62:65]
	s_barrier
	v_mfma_f32_16x16x32_bf16 v[62:65], v[134:137], v[180:183], v[62:65]
	v_mfma_f32_16x16x32_bf16 v[58:61], v[138:141], v[176:179], v[58:61]
	v_mfma_f32_16x16x32_bf16 v[58:61], v[142:145], v[180:183], v[58:61]
	v_mfma_f32_16x16x32_bf16 v[54:57], v[154:157], v[176:179], v[54:57]
	v_mfma_f32_16x16x32_bf16 v[54:57], v[164:167], v[180:183], v[54:57]
	v_mfma_f32_16x16x32_bf16 v[50:53], v[168:171], v[176:179], v[50:53]
	v_mfma_f32_16x16x32_bf16 v[50:53], v[172:175], v[180:183], v[50:53]
	v_mfma_f32_16x16x32_bf16 v[34:37], v[168:171], v[184:187], v[34:37]
	v_mfma_f32_16x16x32_bf16 v[34:37], v[172:175], v[188:191], v[34:37]
	v_mfma_f32_16x16x32_bf16 v[38:41], v[154:157], v[184:187], v[38:41]
	v_mfma_f32_16x16x32_bf16 v[38:41], v[164:167], v[188:191], v[38:41]
	v_mfma_f32_16x16x32_bf16 v[42:45], v[138:141], v[184:187], v[42:45]
	v_mfma_f32_16x16x32_bf16 v[42:45], v[142:145], v[188:191], v[42:45]
	v_mfma_f32_16x16x32_bf16 v[46:49], v[130:133], v[184:187], v[46:49]
	v_mfma_f32_16x16x32_bf16 v[46:49], v[134:137], v[188:191], v[46:49]
	v_mfma_f32_16x16x32_bf16 v[30:33], v[130:133], v[192:195], v[30:33]
	v_mfma_f32_16x16x32_bf16 v[30:33], v[134:137], v[196:199], v[30:33]
	v_mfma_f32_16x16x32_bf16 v[26:29], v[138:141], v[192:195], v[26:29]
	v_mfma_f32_16x16x32_bf16 v[26:29], v[142:145], v[196:199], v[26:29]
	v_mfma_f32_16x16x32_bf16 v[22:25], v[154:157], v[192:195], v[22:25]
	v_mfma_f32_16x16x32_bf16 v[22:25], v[164:167], v[196:199], v[22:25]
	v_mfma_f32_16x16x32_bf16 v[18:21], v[168:171], v[192:195], v[18:21]
	v_mfma_f32_16x16x32_bf16 v[18:21], v[172:175], v[196:199], v[18:21]
	v_mfma_f32_16x16x32_bf16 v[2:5], v[168:171], v[200:203], v[2:5]
	v_mfma_f32_16x16x32_bf16 v[2:5], v[172:175], v[204:207], v[2:5]
	v_mfma_f32_16x16x32_bf16 v[6:9], v[154:157], v[200:203], v[6:9]
	v_mfma_f32_16x16x32_bf16 v[6:9], v[164:167], v[204:207], v[6:9]
	v_mfma_f32_16x16x32_bf16 v[10:13], v[138:141], v[200:203], v[10:13]
	v_mfma_f32_16x16x32_bf16 v[10:13], v[142:145], v[204:207], v[10:13]
	v_mfma_f32_16x16x32_bf16 v[14:17], v[130:133], v[200:203], v[14:17]
	v_mfma_f32_16x16x32_bf16 v[14:17], v[134:137], v[204:207], v[14:17]
	s_setprio 0
	s_barrier
	v_add_u32_e32 v142, 0x18000, v162
	v_add_u32_e32 v150, 0x1c000, v162
	ds_read_b128 v[130:133], v142
	ds_read_b128 v[134:137], v142 offset:1024
	ds_read_b128 v[138:141], v142 offset:2048
	ds_read_b128 v[142:145], v142 offset:3072
	ds_read_b128 v[154:157], v150
	ds_read_b128 v[164:167], v150 offset:1024
	ds_read_b128 v[168:171], v150 offset:2048
	ds_read_b128 v[172:175], v150 offset:3072
	s_mov_b32 m0, s72
	s_add_i32 s94, s91, 0x20000
	ds_read_b128 v[176:179], v163 offset:32768
	ds_read_b128 v[180:183], v163 offset:33792
	ds_read_b128 v[184:187], v163 offset:34816
	ds_read_b128 v[188:191], v163 offset:35840
	ds_read_b128 v[192:195], v163 offset:36864
	ds_read_b128 v[196:199], v163 offset:37888
	ds_read_b128 v[200:203], v163 offset:38912
	ds_read_b128 v[204:207], v163 offset:39936
	buffer_load_dwordx4 v161, s[12:15], s94 offen lds
	s_add_i32 s94, s91, 0x30000
	s_mov_b32 m0, s73
	s_nop 0
	buffer_load_dwordx4 v161, s[12:15], s94 offen lds
	s_waitcnt vmcnt(8)
	s_waitcnt lgkmcnt(0)
	s_setprio 1
	v_mfma_f32_16x16x32_bf16 v[126:129], v[130:133], v[176:179], v[126:129]
	s_barrier
	v_mfma_f32_16x16x32_bf16 v[126:129], v[134:137], v[180:183], v[126:129]
	v_mfma_f32_16x16x32_bf16 v[122:125], v[138:141], v[176:179], v[122:125]
	v_mfma_f32_16x16x32_bf16 v[122:125], v[142:145], v[180:183], v[122:125]
	v_mfma_f32_16x16x32_bf16 v[118:121], v[154:157], v[176:179], v[118:121]
	v_mfma_f32_16x16x32_bf16 v[118:121], v[164:167], v[180:183], v[118:121]
	v_mfma_f32_16x16x32_bf16 v[114:117], v[168:171], v[176:179], v[114:117]
	v_mfma_f32_16x16x32_bf16 v[114:117], v[172:175], v[180:183], v[114:117]
	v_mfma_f32_16x16x32_bf16 v[98:101], v[168:171], v[184:187], v[98:101]
	v_mfma_f32_16x16x32_bf16 v[98:101], v[172:175], v[188:191], v[98:101]
	v_mfma_f32_16x16x32_bf16 v[102:105], v[154:157], v[184:187], v[102:105]
	v_mfma_f32_16x16x32_bf16 v[102:105], v[164:167], v[188:191], v[102:105]
	v_mfma_f32_16x16x32_bf16 v[106:109], v[138:141], v[184:187], v[106:109]
	v_mfma_f32_16x16x32_bf16 v[106:109], v[142:145], v[188:191], v[106:109]
	v_mfma_f32_16x16x32_bf16 v[110:113], v[130:133], v[184:187], v[110:113]
	v_mfma_f32_16x16x32_bf16 v[110:113], v[134:137], v[188:191], v[110:113]
	v_mfma_f32_16x16x32_bf16 v[94:97], v[130:133], v[192:195], v[94:97]
	v_mfma_f32_16x16x32_bf16 v[94:97], v[134:137], v[196:199], v[94:97]
	v_mfma_f32_16x16x32_bf16 v[90:93], v[138:141], v[192:195], v[90:93]
	v_mfma_f32_16x16x32_bf16 v[90:93], v[142:145], v[196:199], v[90:93]
	v_mfma_f32_16x16x32_bf16 v[86:89], v[154:157], v[192:195], v[86:89]
	v_mfma_f32_16x16x32_bf16 v[86:89], v[164:167], v[196:199], v[86:89]
	v_mfma_f32_16x16x32_bf16 v[82:85], v[168:171], v[192:195], v[82:85]
	v_mfma_f32_16x16x32_bf16 v[82:85], v[172:175], v[196:199], v[82:85]
	v_mfma_f32_16x16x32_bf16 v[66:69], v[168:171], v[200:203], v[66:69]
	v_mfma_f32_16x16x32_bf16 v[66:69], v[172:175], v[204:207], v[66:69]
	v_mfma_f32_16x16x32_bf16 v[70:73], v[154:157], v[200:203], v[70:73]
	v_mfma_f32_16x16x32_bf16 v[70:73], v[164:167], v[204:207], v[70:73]
	v_mfma_f32_16x16x32_bf16 v[74:77], v[138:141], v[200:203], v[74:77]
	v_mfma_f32_16x16x32_bf16 v[74:77], v[142:145], v[204:207], v[74:77]
	v_mfma_f32_16x16x32_bf16 v[78:81], v[130:133], v[200:203], v[78:81]
	v_mfma_f32_16x16x32_bf16 v[78:81], v[134:137], v[204:207], v[78:81]
	s_setprio 0
	s_barrier
	s_mov_b32 m0, s74
	s_or_b32 s94, s93, 0x80
	buffer_load_dwordx4 v160, s[4:7], s94 offen lds
	s_add_i32 s94, s93, 0x10080
	s_mov_b32 m0, s75
	s_add_i32 s91, s91, 0x10080
	buffer_load_dwordx4 v160, s[4:7], s94 offen lds
	s_add_i32 s94, s93, 0x20080
	s_mov_b32 m0, s78
	s_add_i32 s93, s93, 0x30080
	buffer_load_dwordx4 v160, s[4:7], s94 offen lds
	s_mov_b32 m0, s79
	s_nop 0
	buffer_load_dwordx4 v160, s[4:7], s93 offen lds
	s_mov_b32 m0, s76
	s_nop 0
	buffer_load_dwordx4 v161, s[12:15], s92 offen lds
	s_mov_b32 m0, s77
	s_nop 0
	buffer_load_dwordx4 v161, s[12:15], s91 offen lds
	ds_read_b128 v[176:179], v163 offset:49152
	ds_read_b128 v[180:183], v163 offset:50176
	ds_read_b128 v[184:187], v163 offset:51200
	ds_read_b128 v[188:191], v163 offset:52224
	ds_read_b128 v[192:195], v163 offset:53248
	ds_read_b128 v[196:199], v163 offset:54272
	ds_read_b128 v[200:203], v163 offset:55296
	ds_read_b128 v[204:207], v163 offset:56320
	s_waitcnt vmcnt(8)
	s_waitcnt lgkmcnt(0)
	s_setprio 1
	v_mfma_f32_16x16x32_bf16 v[62:65], v[130:133], v[176:179], v[62:65]
	s_barrier
	v_mfma_f32_16x16x32_bf16 v[62:65], v[134:137], v[180:183], v[62:65]
	v_mfma_f32_16x16x32_bf16 v[58:61], v[138:141], v[176:179], v[58:61]
	v_mfma_f32_16x16x32_bf16 v[58:61], v[142:145], v[180:183], v[58:61]
	v_mfma_f32_16x16x32_bf16 v[54:57], v[154:157], v[176:179], v[54:57]
	v_mfma_f32_16x16x32_bf16 v[54:57], v[164:167], v[180:183], v[54:57]
	v_mfma_f32_16x16x32_bf16 v[50:53], v[168:171], v[176:179], v[50:53]
	v_mfma_f32_16x16x32_bf16 v[50:53], v[172:175], v[180:183], v[50:53]
	v_mfma_f32_16x16x32_bf16 v[34:37], v[168:171], v[184:187], v[34:37]
	v_mfma_f32_16x16x32_bf16 v[34:37], v[172:175], v[188:191], v[34:37]
	v_mfma_f32_16x16x32_bf16 v[38:41], v[154:157], v[184:187], v[38:41]
	v_mfma_f32_16x16x32_bf16 v[38:41], v[164:167], v[188:191], v[38:41]
	v_mfma_f32_16x16x32_bf16 v[42:45], v[138:141], v[184:187], v[42:45]
	v_mfma_f32_16x16x32_bf16 v[42:45], v[142:145], v[188:191], v[42:45]
	v_mfma_f32_16x16x32_bf16 v[46:49], v[130:133], v[184:187], v[46:49]
	v_mfma_f32_16x16x32_bf16 v[46:49], v[134:137], v[188:191], v[46:49]
	v_mfma_f32_16x16x32_bf16 v[30:33], v[130:133], v[192:195], v[30:33]
	v_mfma_f32_16x16x32_bf16 v[30:33], v[134:137], v[196:199], v[30:33]
	v_mfma_f32_16x16x32_bf16 v[26:29], v[138:141], v[192:195], v[26:29]
	v_mfma_f32_16x16x32_bf16 v[26:29], v[142:145], v[196:199], v[26:29]
	v_mfma_f32_16x16x32_bf16 v[22:25], v[154:157], v[192:195], v[22:25]
	v_mfma_f32_16x16x32_bf16 v[22:25], v[164:167], v[196:199], v[22:25]
	v_mfma_f32_16x16x32_bf16 v[18:21], v[168:171], v[192:195], v[18:21]
	v_mfma_f32_16x16x32_bf16 v[18:21], v[172:175], v[196:199], v[18:21]
	v_mfma_f32_16x16x32_bf16 v[2:5], v[168:171], v[200:203], v[2:5]
	v_mfma_f32_16x16x32_bf16 v[2:5], v[172:175], v[204:207], v[2:5]
	v_mfma_f32_16x16x32_bf16 v[6:9], v[154:157], v[200:203], v[6:9]
	v_mfma_f32_16x16x32_bf16 v[6:9], v[164:167], v[204:207], v[6:9]
	v_mfma_f32_16x16x32_bf16 v[10:13], v[138:141], v[200:203], v[10:13]
	v_mfma_f32_16x16x32_bf16 v[10:13], v[142:145], v[204:207], v[10:13]
	v_mfma_f32_16x16x32_bf16 v[14:17], v[130:133], v[200:203], v[14:17]
	v_mfma_f32_16x16x32_bf16 v[14:17], v[134:137], v[204:207], v[14:17]
	s_setprio 0
	s_barrier
	s_add_i32 s89, s89, 2
	s_cmp_ge_i32 s89, s63
	s_mov_b32 s6, s90
	s_cbranch_scc0 .LBB0_1020
	s_and_b64 vcc, exec, s[54:55]
	s_cbranch_vccz .LBB0_1023

.LBB0_1035:
	s_add_i32 s73, s70, 0xfffb8080
	s_cmp_eq_u32 s53, s72
	s_cselect_b32 s73, s68, s73
	s_cselect_b32 s75, s69, s71
	s_add_i32 s74, s73, 0x80
	s_add_i32 s76, s70, 0xfffe8000
	s_mov_b32 m0, s54
	s_nop 0
	buffer_load_dwordx4 v132, s[12:15], s76 offen lds
	s_mov_b32 m0, s55
	s_nop 0
	buffer_load_dwordx4 v132, s[12:15], s70 offen lds
	ds_read_b128 v[140:143], v134
	ds_read_b128 v[148:151], v134 offset:1024
	ds_read_b128 v[152:155], v134 offset:2048
	ds_read_b128 v[156:159], v134 offset:3072
	ds_read_b128 v[160:163], v135
	ds_read_b128 v[164:167], v135 offset:1024
	ds_read_b128 v[168:171], v135 offset:2048
	ds_read_b128 v[172:175], v135 offset:3072
	ds_read_b128 v[176:179], v136
	ds_read_b128 v[180:183], v136 offset:1024
	ds_read_b128 v[184:187], v136 offset:2048
	ds_read_b128 v[188:191], v136 offset:3072
	ds_read_b128 v[192:195], v136 offset:4096
	ds_read_b128 v[196:199], v136 offset:5120
	ds_read_b128 v[200:203], v136 offset:6144
	ds_read_b128 v[204:207], v136 offset:7168
	s_waitcnt vmcnt(8)
	s_waitcnt lgkmcnt(0)
	s_setprio 1
	v_mfma_f32_16x16x32_bf16 v[126:129], v[140:143], v[176:179], v[126:129]
	s_barrier
	v_mfma_f32_16x16x32_bf16 v[126:129], v[148:151], v[180:183], v[126:129]
	v_mfma_f32_16x16x32_bf16 v[122:125], v[152:155], v[176:179], v[122:125]
	v_mfma_f32_16x16x32_bf16 v[122:125], v[156:159], v[180:183], v[122:125]
	v_mfma_f32_16x16x32_bf16 v[118:121], v[160:163], v[176:179], v[118:121]
	v_mfma_f32_16x16x32_bf16 v[118:121], v[164:167], v[180:183], v[118:121]
	v_mfma_f32_16x16x32_bf16 v[114:117], v[168:171], v[176:179], v[114:117]
	v_mfma_f32_16x16x32_bf16 v[114:117], v[172:175], v[180:183], v[114:117]
	v_mfma_f32_16x16x32_bf16 v[98:101], v[168:171], v[184:187], v[98:101]
	v_mfma_f32_16x16x32_bf16 v[98:101], v[172:175], v[188:191], v[98:101]
	v_mfma_f32_16x16x32_bf16 v[102:105], v[160:163], v[184:187], v[102:105]
	v_mfma_f32_16x16x32_bf16 v[102:105], v[164:167], v[188:191], v[102:105]
	v_mfma_f32_16x16x32_bf16 v[106:109], v[152:155], v[184:187], v[106:109]
	v_mfma_f32_16x16x32_bf16 v[106:109], v[156:159], v[188:191], v[106:109]
	v_mfma_f32_16x16x32_bf16 v[110:113], v[140:143], v[184:187], v[110:113]
	v_mfma_f32_16x16x32_bf16 v[110:113], v[148:151], v[188:191], v[110:113]
	v_mfma_f32_16x16x32_bf16 v[94:97], v[140:143], v[192:195], v[94:97]
	v_mfma_f32_16x16x32_bf16 v[94:97], v[148:151], v[196:199], v[94:97]
	v_mfma_f32_16x16x32_bf16 v[90:93], v[152:155], v[192:195], v[90:93]
	v_mfma_f32_16x16x32_bf16 v[90:93], v[156:159], v[196:199], v[90:93]
	v_mfma_f32_16x16x32_bf16 v[86:89], v[160:163], v[192:195], v[86:89]
	v_mfma_f32_16x16x32_bf16 v[86:89], v[164:167], v[196:199], v[86:89]
	v_mfma_f32_16x16x32_bf16 v[82:85], v[168:171], v[192:195], v[82:85]
	v_mfma_f32_16x16x32_bf16 v[82:85], v[172:175], v[196:199], v[82:85]
	v_mfma_f32_16x16x32_bf16 v[66:69], v[168:171], v[200:203], v[66:69]
	v_mfma_f32_16x16x32_bf16 v[66:69], v[172:175], v[204:207], v[66:69]
	v_mfma_f32_16x16x32_bf16 v[70:73], v[160:163], v[200:203], v[70:73]
	v_mfma_f32_16x16x32_bf16 v[70:73], v[164:167], v[204:207], v[70:73]
	v_mfma_f32_16x16x32_bf16 v[74:77], v[152:155], v[200:203], v[74:77]
	v_mfma_f32_16x16x32_bf16 v[74:77], v[156:159], v[204:207], v[74:77]
	v_mfma_f32_16x16x32_bf16 v[78:81], v[140:143], v[200:203], v[78:81]
	v_mfma_f32_16x16x32_bf16 v[78:81], v[148:151], v[204:207], v[78:81]
	s_setprio 0
	s_barrier
	s_mov_b32 m0, s30
	s_nop 0
	buffer_load_dwordx4 v133, s[16:19], s75 offen lds
	s_add_i32 s76, s75, 0x200000
	s_mov_b32 m0, s31
	s_nop 0
	buffer_load_dwordx4 v133, s[16:19], s76 offen lds
	s_add_i32 s76, s75, 0x400000
	s_mov_b32 m0, s35
	s_nop 0
	buffer_load_dwordx4 v133, s[16:19], s76 offen lds
	s_add_i32 s76, s75, 0x600000
	s_mov_b32 m0, s42
	s_nop 0
	buffer_load_dwordx4 v133, s[16:19], s76 offen lds
	s_mov_b32 m0, s27
	s_add_i32 s76, s73, 0x18000
	buffer_load_dwordx4 v132, s[12:15], s73 offen lds
	s_mov_b32 m0, s43
	s_nop 0
	buffer_load_dwordx4 v132, s[12:15], s76 offen lds
	ds_read_b128 v[176:179], v136 offset:16384
	ds_read_b128 v[180:183], v136 offset:17408
	ds_read_b128 v[184:187], v136 offset:18432
	ds_read_b128 v[188:191], v136 offset:19456
	ds_read_b128 v[192:195], v136 offset:20480
	ds_read_b128 v[196:199], v136 offset:21504
	ds_read_b128 v[200:203], v136 offset:22528
	ds_read_b128 v[204:207], v136 offset:23552
	s_waitcnt vmcnt(8)
	s_waitcnt lgkmcnt(0)
	s_setprio 1
	v_mfma_f32_16x16x32_bf16 v[62:65], v[140:143], v[176:179], v[62:65]
	s_barrier
	v_mfma_f32_16x16x32_bf16 v[62:65], v[148:151], v[180:183], v[62:65]
	v_mfma_f32_16x16x32_bf16 v[58:61], v[152:155], v[176:179], v[58:61]
	v_mfma_f32_16x16x32_bf16 v[58:61], v[156:159], v[180:183], v[58:61]
	v_mfma_f32_16x16x32_bf16 v[54:57], v[160:163], v[176:179], v[54:57]
	v_mfma_f32_16x16x32_bf16 v[54:57], v[164:167], v[180:183], v[54:57]
	v_mfma_f32_16x16x32_bf16 v[50:53], v[168:171], v[176:179], v[50:53]
	v_mfma_f32_16x16x32_bf16 v[50:53], v[172:175], v[180:183], v[50:53]
	v_mfma_f32_16x16x32_bf16 v[34:37], v[168:171], v[184:187], v[34:37]
	v_mfma_f32_16x16x32_bf16 v[34:37], v[172:175], v[188:191], v[34:37]
	v_mfma_f32_16x16x32_bf16 v[38:41], v[160:163], v[184:187], v[38:41]
	v_mfma_f32_16x16x32_bf16 v[38:41], v[164:167], v[188:191], v[38:41]
	v_mfma_f32_16x16x32_bf16 v[42:45], v[152:155], v[184:187], v[42:45]
	v_mfma_f32_16x16x32_bf16 v[42:45], v[156:159], v[188:191], v[42:45]
	v_mfma_f32_16x16x32_bf16 v[46:49], v[140:143], v[184:187], v[46:49]
	v_mfma_f32_16x16x32_bf16 v[46:49], v[148:151], v[188:191], v[46:49]
	v_mfma_f32_16x16x32_bf16 v[30:33], v[140:143], v[192:195], v[30:33]
	v_mfma_f32_16x16x32_bf16 v[30:33], v[148:151], v[196:199], v[30:33]
	v_mfma_f32_16x16x32_bf16 v[26:29], v[152:155], v[192:195], v[26:29]
	v_mfma_f32_16x16x32_bf16 v[26:29], v[156:159], v[196:199], v[26:29]
	v_mfma_f32_16x16x32_bf16 v[22:25], v[160:163], v[192:195], v[22:25]
	v_mfma_f32_16x16x32_bf16 v[22:25], v[164:167], v[196:199], v[22:25]
	v_mfma_f32_16x16x32_bf16 v[18:21], v[168:171], v[192:195], v[18:21]
	v_mfma_f32_16x16x32_bf16 v[18:21], v[172:175], v[196:199], v[18:21]
	v_mfma_f32_16x16x32_bf16 v[2:5], v[168:171], v[200:203], v[2:5]
	v_mfma_f32_16x16x32_bf16 v[2:5], v[172:175], v[204:207], v[2:5]
	v_mfma_f32_16x16x32_bf16 v[6:9], v[160:163], v[200:203], v[6:9]
	v_mfma_f32_16x16x32_bf16 v[6:9], v[164:167], v[204:207], v[6:9]
	v_mfma_f32_16x16x32_bf16 v[10:13], v[152:155], v[200:203], v[10:13]
	v_mfma_f32_16x16x32_bf16 v[10:13], v[156:159], v[204:207], v[10:13]
	v_mfma_f32_16x16x32_bf16 v[14:17], v[140:143], v[200:203], v[14:17]
	v_mfma_f32_16x16x32_bf16 v[14:17], v[148:151], v[204:207], v[14:17]
	s_setprio 0
	s_barrier
	s_mov_b32 m0, s44
	s_add_i32 s76, s73, 0x30000
	buffer_load_dwordx4 v132, s[12:15], s76 offen lds
	s_add_i32 s76, s73, 0x48000
	s_mov_b32 m0, s45
	s_nop 0
	buffer_load_dwordx4 v132, s[12:15], s76 offen lds
	ds_read_b128 v[140:143], v137
	ds_read_b128 v[148:151], v137 offset:1024
	ds_read_b128 v[152:155], v137 offset:2048
	ds_read_b128 v[156:159], v137 offset:3072
	ds_read_b128 v[160:163], v138
	ds_read_b128 v[164:167], v138 offset:1024
	ds_read_b128 v[168:171], v138 offset:2048
	ds_read_b128 v[172:175], v138 offset:3072
	ds_read_b128 v[176:179], v136 offset:32768
	ds_read_b128 v[180:183], v136 offset:33792
	ds_read_b128 v[184:187], v136 offset:34816
	ds_read_b128 v[188:191], v136 offset:35840
	ds_read_b128 v[192:195], v136 offset:36864
	ds_read_b128 v[196:199], v136 offset:37888
	ds_read_b128 v[200:203], v136 offset:38912
	ds_read_b128 v[204:207], v136 offset:39936
	s_waitcnt vmcnt(8)
	s_waitcnt lgkmcnt(0)
	s_setprio 1
	v_mfma_f32_16x16x32_bf16 v[126:129], v[140:143], v[176:179], v[126:129]
	s_barrier
	v_mfma_f32_16x16x32_bf16 v[126:129], v[148:151], v[180:183], v[126:129]
	v_mfma_f32_16x16x32_bf16 v[122:125], v[152:155], v[176:179], v[122:125]
	v_mfma_f32_16x16x32_bf16 v[122:125], v[156:159], v[180:183], v[122:125]
	v_mfma_f32_16x16x32_bf16 v[118:121], v[160:163], v[176:179], v[118:121]
	v_mfma_f32_16x16x32_bf16 v[118:121], v[164:167], v[180:183], v[118:121]
	v_mfma_f32_16x16x32_bf16 v[114:117], v[168:171], v[176:179], v[114:117]
	v_mfma_f32_16x16x32_bf16 v[114:117], v[172:175], v[180:183], v[114:117]
	v_mfma_f32_16x16x32_bf16 v[98:101], v[168:171], v[184:187], v[98:101]
	v_mfma_f32_16x16x32_bf16 v[98:101], v[172:175], v[188:191], v[98:101]
	v_mfma_f32_16x16x32_bf16 v[102:105], v[160:163], v[184:187], v[102:105]
	v_mfma_f32_16x16x32_bf16 v[102:105], v[164:167], v[188:191], v[102:105]
	v_mfma_f32_16x16x32_bf16 v[106:109], v[152:155], v[184:187], v[106:109]
	v_mfma_f32_16x16x32_bf16 v[106:109], v[156:159], v[188:191], v[106:109]
	v_mfma_f32_16x16x32_bf16 v[110:113], v[140:143], v[184:187], v[110:113]
	v_mfma_f32_16x16x32_bf16 v[110:113], v[148:151], v[188:191], v[110:113]
	v_mfma_f32_16x16x32_bf16 v[94:97], v[140:143], v[192:195], v[94:97]
	v_mfma_f32_16x16x32_bf16 v[94:97], v[148:151], v[196:199], v[94:97]
	v_mfma_f32_16x16x32_bf16 v[90:93], v[152:155], v[192:195], v[90:93]
	v_mfma_f32_16x16x32_bf16 v[90:93], v[156:159], v[196:199], v[90:93]
	v_mfma_f32_16x16x32_bf16 v[86:89], v[160:163], v[192:195], v[86:89]
	v_mfma_f32_16x16x32_bf16 v[86:89], v[164:167], v[196:199], v[86:89]
	v_mfma_f32_16x16x32_bf16 v[82:85], v[168:171], v[192:195], v[82:85]
	v_mfma_f32_16x16x32_bf16 v[82:85], v[172:175], v[196:199], v[82:85]
	v_mfma_f32_16x16x32_bf16 v[66:69], v[168:171], v[200:203], v[66:69]
	v_mfma_f32_16x16x32_bf16 v[66:69], v[172:175], v[204:207], v[66:69]
	v_mfma_f32_16x16x32_bf16 v[70:73], v[160:163], v[200:203], v[70:73]
	v_mfma_f32_16x16x32_bf16 v[70:73], v[164:167], v[204:207], v[70:73]
	v_mfma_f32_16x16x32_bf16 v[74:77], v[152:155], v[200:203], v[74:77]
	v_mfma_f32_16x16x32_bf16 v[74:77], v[156:159], v[204:207], v[74:77]
	v_mfma_f32_16x16x32_bf16 v[78:81], v[140:143], v[200:203], v[78:81]
	v_mfma_f32_16x16x32_bf16 v[78:81], v[148:151], v[204:207], v[78:81]
	s_setprio 0
	s_barrier
	s_mov_b32 m0, s46
	s_add_i32 s76, s75, 0x80
	buffer_load_dwordx4 v133, s[16:19], s76 offen lds
	s_add_i32 s76, s75, 0x200080
	s_mov_b32 m0, s47
	s_add_i32 s73, s73, 0x18080
	buffer_load_dwordx4 v133, s[16:19], s76 offen lds
	s_add_i32 s76, s75, 0x400080
	s_mov_b32 m0, s50
	s_add_i32 s75, s75, 0x600080
	buffer_load_dwordx4 v133, s[16:19], s76 offen lds
	s_mov_b32 m0, s51
	s_nop 0
	buffer_load_dwordx4 v133, s[16:19], s75 offen lds
	s_mov_b32 m0, s48
	s_nop 0
	buffer_load_dwordx4 v132, s[12:15], s74 offen lds
	s_mov_b32 m0, s49
	s_nop 0
	buffer_load_dwordx4 v132, s[12:15], s73 offen lds
	ds_read_b128 v[176:179], v136 offset:49152
	ds_read_b128 v[180:183], v136 offset:50176
	ds_read_b128 v[184:187], v136 offset:51200
	ds_read_b128 v[188:191], v136 offset:52224
	ds_read_b128 v[192:195], v136 offset:53248
	ds_read_b128 v[196:199], v136 offset:54272
	ds_read_b128 v[200:203], v136 offset:55296
	ds_read_b128 v[204:207], v136 offset:56320
	s_waitcnt vmcnt(8)
	s_waitcnt lgkmcnt(0)
	s_setprio 1
	v_mfma_f32_16x16x32_bf16 v[62:65], v[140:143], v[176:179], v[62:65]
	s_barrier
	v_mfma_f32_16x16x32_bf16 v[62:65], v[148:151], v[180:183], v[62:65]
	v_mfma_f32_16x16x32_bf16 v[58:61], v[152:155], v[176:179], v[58:61]
	v_mfma_f32_16x16x32_bf16 v[58:61], v[156:159], v[180:183], v[58:61]
	v_mfma_f32_16x16x32_bf16 v[54:57], v[160:163], v[176:179], v[54:57]
	v_mfma_f32_16x16x32_bf16 v[54:57], v[164:167], v[180:183], v[54:57]
	v_mfma_f32_16x16x32_bf16 v[50:53], v[168:171], v[176:179], v[50:53]
	v_mfma_f32_16x16x32_bf16 v[50:53], v[172:175], v[180:183], v[50:53]
	v_mfma_f32_16x16x32_bf16 v[34:37], v[168:171], v[184:187], v[34:37]
	v_mfma_f32_16x16x32_bf16 v[34:37], v[172:175], v[188:191], v[34:37]
	v_mfma_f32_16x16x32_bf16 v[38:41], v[160:163], v[184:187], v[38:41]
	v_mfma_f32_16x16x32_bf16 v[38:41], v[164:167], v[188:191], v[38:41]
	v_mfma_f32_16x16x32_bf16 v[42:45], v[152:155], v[184:187], v[42:45]
	v_mfma_f32_16x16x32_bf16 v[42:45], v[156:159], v[188:191], v[42:45]
	v_mfma_f32_16x16x32_bf16 v[46:49], v[140:143], v[184:187], v[46:49]
	v_mfma_f32_16x16x32_bf16 v[46:49], v[148:151], v[188:191], v[46:49]
	v_mfma_f32_16x16x32_bf16 v[30:33], v[140:143], v[192:195], v[30:33]
	v_mfma_f32_16x16x32_bf16 v[30:33], v[148:151], v[196:199], v[30:33]
	v_mfma_f32_16x16x32_bf16 v[26:29], v[152:155], v[192:195], v[26:29]
	v_mfma_f32_16x16x32_bf16 v[26:29], v[156:159], v[196:199], v[26:29]
	v_mfma_f32_16x16x32_bf16 v[22:25], v[160:163], v[192:195], v[22:25]
	v_mfma_f32_16x16x32_bf16 v[22:25], v[164:167], v[196:199], v[22:25]
	v_mfma_f32_16x16x32_bf16 v[18:21], v[168:171], v[192:195], v[18:21]
	v_mfma_f32_16x16x32_bf16 v[18:21], v[172:175], v[196:199], v[18:21]
	v_mfma_f32_16x16x32_bf16 v[2:5], v[168:171], v[200:203], v[2:5]
	v_mfma_f32_16x16x32_bf16 v[2:5], v[172:175], v[204:207], v[2:5]
	v_mfma_f32_16x16x32_bf16 v[6:9], v[160:163], v[200:203], v[6:9]
	v_mfma_f32_16x16x32_bf16 v[6:9], v[164:167], v[204:207], v[6:9]
	v_mfma_f32_16x16x32_bf16 v[10:13], v[152:155], v[200:203], v[10:13]
	v_mfma_f32_16x16x32_bf16 v[10:13], v[156:159], v[204:207], v[10:13]
	v_mfma_f32_16x16x32_bf16 v[14:17], v[140:143], v[200:203], v[14:17]
	v_mfma_f32_16x16x32_bf16 v[14:17], v[148:151], v[204:207], v[14:17]
	s_setprio 0
	s_barrier
	s_add_i32 s72, s72, 2
	s_addk_i32 s70, 0x100
	s_addk_i32 s71, 0x100
	s_cmp_ge_i32 s72, s21
	s_cbranch_scc0 .LBB0_1035

.LBB0_1050:
	s_add_i32 s18, s61, 0xfff40080
	s_cmp_eq_u32 s54, s62
	s_cselect_b32 s64, s35, s18
	s_add_i32 s63, s64, 0x80
	s_add_i32 s18, s61, 0xfffc0000
	s_mov_b32 m0, s55
	s_nop 0
	buffer_load_dwordx4 v140, s[12:15], s18 offen lds
	s_mov_b32 m0, s56
	s_nop 0
	buffer_load_dwordx4 v140, s[12:15], s61 offen lds
	ds_read_b128 v[132:135], v142
	ds_read_b128 v[136:139], v142 offset:1024
	ds_read_b128 v[148:151], v142 offset:2048
	ds_read_b128 v[152:155], v142 offset:3072
	ds_read_b128 v[156:159], v143
	ds_read_b128 v[160:163], v143 offset:1024
	ds_read_b128 v[164:167], v143 offset:2048
	ds_read_b128 v[168:171], v143 offset:3072
	ds_read_b128 v[172:175], v144
	ds_read_b128 v[176:179], v144 offset:1024
	ds_read_b128 v[180:183], v144 offset:2048
	ds_read_b128 v[184:187], v144 offset:3072
	ds_read_b128 v[188:191], v144 offset:4096
	ds_read_b128 v[192:195], v144 offset:5120
	ds_read_b128 v[196:199], v144 offset:6144
	ds_read_b128 v[200:203], v144 offset:7168
	s_waitcnt vmcnt(8)
	s_waitcnt lgkmcnt(0)
	s_setprio 1
	v_mfma_f32_16x16x32_bf16 v[126:129], v[132:135], v[172:175], v[126:129]
	s_barrier
	v_mfma_f32_16x16x32_bf16 v[126:129], v[136:139], v[176:179], v[126:129]
	v_mfma_f32_16x16x32_bf16 v[122:125], v[148:151], v[172:175], v[122:125]
	v_mfma_f32_16x16x32_bf16 v[122:125], v[152:155], v[176:179], v[122:125]
	v_mfma_f32_16x16x32_bf16 v[118:121], v[156:159], v[172:175], v[118:121]
	v_mfma_f32_16x16x32_bf16 v[118:121], v[160:163], v[176:179], v[118:121]
	v_mfma_f32_16x16x32_bf16 v[114:117], v[164:167], v[172:175], v[114:117]
	v_mfma_f32_16x16x32_bf16 v[114:117], v[168:171], v[176:179], v[114:117]
	v_mfma_f32_16x16x32_bf16 v[98:101], v[164:167], v[180:183], v[98:101]
	v_mfma_f32_16x16x32_bf16 v[98:101], v[168:171], v[184:187], v[98:101]
	v_mfma_f32_16x16x32_bf16 v[102:105], v[156:159], v[180:183], v[102:105]
	v_mfma_f32_16x16x32_bf16 v[102:105], v[160:163], v[184:187], v[102:105]
	v_mfma_f32_16x16x32_bf16 v[106:109], v[148:151], v[180:183], v[106:109]
	v_mfma_f32_16x16x32_bf16 v[106:109], v[152:155], v[184:187], v[106:109]
	v_mfma_f32_16x16x32_bf16 v[110:113], v[132:135], v[180:183], v[110:113]
	v_mfma_f32_16x16x32_bf16 v[110:113], v[136:139], v[184:187], v[110:113]
	v_mfma_f32_16x16x32_bf16 v[94:97], v[132:135], v[188:191], v[94:97]
	v_mfma_f32_16x16x32_bf16 v[94:97], v[136:139], v[192:195], v[94:97]
	v_mfma_f32_16x16x32_bf16 v[90:93], v[148:151], v[188:191], v[90:93]
	v_mfma_f32_16x16x32_bf16 v[90:93], v[152:155], v[192:195], v[90:93]
	v_mfma_f32_16x16x32_bf16 v[86:89], v[156:159], v[188:191], v[86:89]
	v_mfma_f32_16x16x32_bf16 v[86:89], v[160:163], v[192:195], v[86:89]
	v_mfma_f32_16x16x32_bf16 v[82:85], v[164:167], v[188:191], v[82:85]
	v_mfma_f32_16x16x32_bf16 v[82:85], v[168:171], v[192:195], v[82:85]
	v_mfma_f32_16x16x32_bf16 v[66:69], v[164:167], v[196:199], v[66:69]
	v_mfma_f32_16x16x32_bf16 v[66:69], v[168:171], v[200:203], v[66:69]
	v_mfma_f32_16x16x32_bf16 v[70:73], v[156:159], v[196:199], v[70:73]
	v_mfma_f32_16x16x32_bf16 v[70:73], v[160:163], v[200:203], v[70:73]
	v_mfma_f32_16x16x32_bf16 v[74:77], v[148:151], v[196:199], v[74:77]
	v_mfma_f32_16x16x32_bf16 v[74:77], v[152:155], v[200:203], v[74:77]
	v_mfma_f32_16x16x32_bf16 v[78:81], v[132:135], v[196:199], v[78:81]
	v_mfma_f32_16x16x32_bf16 v[78:81], v[136:139], v[200:203], v[78:81]
	s_setprio 0
	s_barrier
	s_mov_b32 m0, s25
	s_mov_b32 s18, s14
	s_mov_b32 s19, s15
	buffer_load_dwordx4 v141, s[16:19], s64 offen lds
	s_add_i32 s65, s64, 0x40000
	s_mov_b32 m0, s27
	s_add_i32 s66, s64, 0x80000
	buffer_load_dwordx4 v141, s[16:19], s65 offen lds
	s_mov_b32 m0, s30
	s_add_i32 s67, s64, 0xc0000
	buffer_load_dwordx4 v141, s[16:19], s66 offen lds
	s_mov_b32 m0, s31
	s_nop 0
	buffer_load_dwordx4 v141, s[16:19], s67 offen lds
	s_mov_b32 m0, s21
	s_nop 0
	buffer_load_dwordx4 v140, s[12:15], s64 offen lds
	s_mov_b32 m0, s38
	s_nop 0
	buffer_load_dwordx4 v140, s[12:15], s65 offen lds
	ds_read_b128 v[172:175], v144 offset:16384
	ds_read_b128 v[176:179], v144 offset:17408
	ds_read_b128 v[180:183], v144 offset:18432
	ds_read_b128 v[184:187], v144 offset:19456
	ds_read_b128 v[188:191], v144 offset:20480
	ds_read_b128 v[192:195], v144 offset:21504
	ds_read_b128 v[196:199], v144 offset:22528
	ds_read_b128 v[200:203], v144 offset:23552
	s_waitcnt vmcnt(8)
	s_waitcnt lgkmcnt(0)
	s_setprio 1
	v_mfma_f32_16x16x32_bf16 v[62:65], v[132:135], v[172:175], v[62:65]
	s_barrier
	v_mfma_f32_16x16x32_bf16 v[62:65], v[136:139], v[176:179], v[62:65]
	v_mfma_f32_16x16x32_bf16 v[58:61], v[148:151], v[172:175], v[58:61]
	v_mfma_f32_16x16x32_bf16 v[58:61], v[152:155], v[176:179], v[58:61]
	v_mfma_f32_16x16x32_bf16 v[54:57], v[156:159], v[172:175], v[54:57]
	v_mfma_f32_16x16x32_bf16 v[54:57], v[160:163], v[176:179], v[54:57]
	v_mfma_f32_16x16x32_bf16 v[50:53], v[164:167], v[172:175], v[50:53]
	v_mfma_f32_16x16x32_bf16 v[50:53], v[168:171], v[176:179], v[50:53]
	v_mfma_f32_16x16x32_bf16 v[34:37], v[164:167], v[180:183], v[34:37]
	v_mfma_f32_16x16x32_bf16 v[34:37], v[168:171], v[184:187], v[34:37]
	v_mfma_f32_16x16x32_bf16 v[38:41], v[156:159], v[180:183], v[38:41]
	v_mfma_f32_16x16x32_bf16 v[38:41], v[160:163], v[184:187], v[38:41]
	v_mfma_f32_16x16x32_bf16 v[42:45], v[148:151], v[180:183], v[42:45]
	v_mfma_f32_16x16x32_bf16 v[42:45], v[152:155], v[184:187], v[42:45]
	v_mfma_f32_16x16x32_bf16 v[46:49], v[132:135], v[180:183], v[46:49]
	v_mfma_f32_16x16x32_bf16 v[46:49], v[136:139], v[184:187], v[46:49]
	v_mfma_f32_16x16x32_bf16 v[30:33], v[132:135], v[188:191], v[30:33]
	v_mfma_f32_16x16x32_bf16 v[30:33], v[136:139], v[192:195], v[30:33]
	v_mfma_f32_16x16x32_bf16 v[26:29], v[148:151], v[188:191], v[26:29]
	v_mfma_f32_16x16x32_bf16 v[26:29], v[152:155], v[192:195], v[26:29]
	v_mfma_f32_16x16x32_bf16 v[22:25], v[156:159], v[188:191], v[22:25]
	v_mfma_f32_16x16x32_bf16 v[22:25], v[160:163], v[192:195], v[22:25]
	v_mfma_f32_16x16x32_bf16 v[18:21], v[164:167], v[188:191], v[18:21]
	v_mfma_f32_16x16x32_bf16 v[18:21], v[168:171], v[192:195], v[18:21]
	v_mfma_f32_16x16x32_bf16 v[2:5], v[164:167], v[196:199], v[2:5]
	v_mfma_f32_16x16x32_bf16 v[2:5], v[168:171], v[200:203], v[2:5]
	v_mfma_f32_16x16x32_bf16 v[6:9], v[156:159], v[196:199], v[6:9]
	v_mfma_f32_16x16x32_bf16 v[6:9], v[160:163], v[200:203], v[6:9]
	v_mfma_f32_16x16x32_bf16 v[10:13], v[148:151], v[196:199], v[10:13]
	v_mfma_f32_16x16x32_bf16 v[10:13], v[152:155], v[200:203], v[10:13]
	v_mfma_f32_16x16x32_bf16 v[14:17], v[132:135], v[196:199], v[14:17]
	v_mfma_f32_16x16x32_bf16 v[14:17], v[136:139], v[200:203], v[14:17]
	s_setprio 0
	s_barrier
	s_mov_b32 m0, s39
	s_nop 0
	buffer_load_dwordx4 v140, s[12:15], s66 offen lds
	s_mov_b32 m0, s40
	s_nop 0
	buffer_load_dwordx4 v140, s[12:15], s67 offen lds
	ds_read_b128 v[132:135], v145
	ds_read_b128 v[136:139], v145 offset:1024
	ds_read_b128 v[148:151], v145 offset:2048
	ds_read_b128 v[152:155], v145 offset:3072
	ds_read_b128 v[156:159], v147
	ds_read_b128 v[160:163], v147 offset:1024
	ds_read_b128 v[164:167], v147 offset:2048
	ds_read_b128 v[168:171], v147 offset:3072
	ds_read_b128 v[172:175], v144 offset:32768
	ds_read_b128 v[176:179], v144 offset:33792
	ds_read_b128 v[180:183], v144 offset:34816
	ds_read_b128 v[184:187], v144 offset:35840
	ds_read_b128 v[188:191], v144 offset:36864
	ds_read_b128 v[192:195], v144 offset:37888
	ds_read_b128 v[196:199], v144 offset:38912
	ds_read_b128 v[200:203], v144 offset:39936
	s_waitcnt vmcnt(8)
	s_waitcnt lgkmcnt(0)
	s_setprio 1
	v_mfma_f32_16x16x32_bf16 v[126:129], v[132:135], v[172:175], v[126:129]
	s_barrier
	v_mfma_f32_16x16x32_bf16 v[126:129], v[136:139], v[176:179], v[126:129]
	v_mfma_f32_16x16x32_bf16 v[122:125], v[148:151], v[172:175], v[122:125]
	v_mfma_f32_16x16x32_bf16 v[122:125], v[152:155], v[176:179], v[122:125]
	v_mfma_f32_16x16x32_bf16 v[118:121], v[156:159], v[172:175], v[118:121]
	v_mfma_f32_16x16x32_bf16 v[118:121], v[160:163], v[176:179], v[118:121]
	v_mfma_f32_16x16x32_bf16 v[114:117], v[164:167], v[172:175], v[114:117]
	v_mfma_f32_16x16x32_bf16 v[114:117], v[168:171], v[176:179], v[114:117]
	v_mfma_f32_16x16x32_bf16 v[98:101], v[164:167], v[180:183], v[98:101]
	v_mfma_f32_16x16x32_bf16 v[98:101], v[168:171], v[184:187], v[98:101]
	v_mfma_f32_16x16x32_bf16 v[102:105], v[156:159], v[180:183], v[102:105]
	v_mfma_f32_16x16x32_bf16 v[102:105], v[160:163], v[184:187], v[102:105]
	v_mfma_f32_16x16x32_bf16 v[106:109], v[148:151], v[180:183], v[106:109]
	v_mfma_f32_16x16x32_bf16 v[106:109], v[152:155], v[184:187], v[106:109]
	v_mfma_f32_16x16x32_bf16 v[110:113], v[132:135], v[180:183], v[110:113]
	v_mfma_f32_16x16x32_bf16 v[110:113], v[136:139], v[184:187], v[110:113]
	v_mfma_f32_16x16x32_bf16 v[94:97], v[132:135], v[188:191], v[94:97]
	v_mfma_f32_16x16x32_bf16 v[94:97], v[136:139], v[192:195], v[94:97]
	v_mfma_f32_16x16x32_bf16 v[90:93], v[148:151], v[188:191], v[90:93]
	v_mfma_f32_16x16x32_bf16 v[90:93], v[152:155], v[192:195], v[90:93]
	v_mfma_f32_16x16x32_bf16 v[86:89], v[156:159], v[188:191], v[86:89]
	v_mfma_f32_16x16x32_bf16 v[86:89], v[160:163], v[192:195], v[86:89]
	v_mfma_f32_16x16x32_bf16 v[82:85], v[164:167], v[188:191], v[82:85]
	v_mfma_f32_16x16x32_bf16 v[82:85], v[168:171], v[192:195], v[82:85]
	v_mfma_f32_16x16x32_bf16 v[66:69], v[164:167], v[196:199], v[66:69]
	v_mfma_f32_16x16x32_bf16 v[66:69], v[168:171], v[200:203], v[66:69]
	v_mfma_f32_16x16x32_bf16 v[70:73], v[156:159], v[196:199], v[70:73]
	v_mfma_f32_16x16x32_bf16 v[70:73], v[160:163], v[200:203], v[70:73]
	v_mfma_f32_16x16x32_bf16 v[74:77], v[148:151], v[196:199], v[74:77]
	v_mfma_f32_16x16x32_bf16 v[74:77], v[152:155], v[200:203], v[74:77]
	v_mfma_f32_16x16x32_bf16 v[78:81], v[132:135], v[196:199], v[78:81]
	v_mfma_f32_16x16x32_bf16 v[78:81], v[136:139], v[200:203], v[78:81]
	s_setprio 0
	s_barrier
	s_mov_b32 m0, s48
	s_nop 0
	buffer_load_dwordx4 v141, s[16:19], s63 offen lds
	s_add_i32 s65, s64, 0x40080
	s_mov_b32 m0, s49
	s_add_i32 s66, s64, 0x80080
	buffer_load_dwordx4 v141, s[16:19], s65 offen lds
	s_mov_b32 m0, s52
	s_add_i32 s64, s64, 0xc0080
	buffer_load_dwordx4 v141, s[16:19], s66 offen lds
	s_mov_b32 m0, s53
	s_nop 0
	buffer_load_dwordx4 v141, s[16:19], s64 offen lds
	s_mov_b32 m0, s50
	s_nop 0
	buffer_load_dwordx4 v140, s[12:15], s63 offen lds
	s_mov_b32 m0, s51
	s_nop 0
	buffer_load_dwordx4 v140, s[12:15], s65 offen lds
	ds_read_b128 v[172:175], v144 offset:49152
	ds_read_b128 v[176:179], v144 offset:50176
	ds_read_b128 v[180:183], v144 offset:51200
	ds_read_b128 v[184:187], v144 offset:52224
	ds_read_b128 v[188:191], v144 offset:53248
	ds_read_b128 v[192:195], v144 offset:54272
	ds_read_b128 v[196:199], v144 offset:55296
	ds_read_b128 v[200:203], v144 offset:56320
	s_waitcnt vmcnt(8)
	s_waitcnt lgkmcnt(0)
	s_setprio 1
	v_mfma_f32_16x16x32_bf16 v[62:65], v[132:135], v[172:175], v[62:65]
	s_barrier
	v_mfma_f32_16x16x32_bf16 v[62:65], v[136:139], v[176:179], v[62:65]
	v_mfma_f32_16x16x32_bf16 v[58:61], v[148:151], v[172:175], v[58:61]
	v_mfma_f32_16x16x32_bf16 v[58:61], v[152:155], v[176:179], v[58:61]
	v_mfma_f32_16x16x32_bf16 v[54:57], v[156:159], v[172:175], v[54:57]
	v_mfma_f32_16x16x32_bf16 v[54:57], v[160:163], v[176:179], v[54:57]
	v_mfma_f32_16x16x32_bf16 v[50:53], v[164:167], v[172:175], v[50:53]
	v_mfma_f32_16x16x32_bf16 v[50:53], v[168:171], v[176:179], v[50:53]
	v_mfma_f32_16x16x32_bf16 v[34:37], v[164:167], v[180:183], v[34:37]
	v_mfma_f32_16x16x32_bf16 v[34:37], v[168:171], v[184:187], v[34:37]
	v_mfma_f32_16x16x32_bf16 v[38:41], v[156:159], v[180:183], v[38:41]
	v_mfma_f32_16x16x32_bf16 v[38:41], v[160:163], v[184:187], v[38:41]
	v_mfma_f32_16x16x32_bf16 v[42:45], v[148:151], v[180:183], v[42:45]
	v_mfma_f32_16x16x32_bf16 v[42:45], v[152:155], v[184:187], v[42:45]
	v_mfma_f32_16x16x32_bf16 v[46:49], v[132:135], v[180:183], v[46:49]
	v_mfma_f32_16x16x32_bf16 v[46:49], v[136:139], v[184:187], v[46:49]
	v_mfma_f32_16x16x32_bf16 v[30:33], v[132:135], v[188:191], v[30:33]
	v_mfma_f32_16x16x32_bf16 v[30:33], v[136:139], v[192:195], v[30:33]
	v_mfma_f32_16x16x32_bf16 v[26:29], v[148:151], v[188:191], v[26:29]
	v_mfma_f32_16x16x32_bf16 v[26:29], v[152:155], v[192:195], v[26:29]
	v_mfma_f32_16x16x32_bf16 v[22:25], v[156:159], v[188:191], v[22:25]
	v_mfma_f32_16x16x32_bf16 v[22:25], v[160:163], v[192:195], v[22:25]
	v_mfma_f32_16x16x32_bf16 v[18:21], v[164:167], v[188:191], v[18:21]
	v_mfma_f32_16x16x32_bf16 v[18:21], v[168:171], v[192:195], v[18:21]
	v_mfma_f32_16x16x32_bf16 v[2:5], v[164:167], v[196:199], v[2:5]
	v_mfma_f32_16x16x32_bf16 v[2:5], v[168:171], v[200:203], v[2:5]
	v_mfma_f32_16x16x32_bf16 v[6:9], v[156:159], v[196:199], v[6:9]
	v_mfma_f32_16x16x32_bf16 v[6:9], v[160:163], v[200:203], v[6:9]
	v_mfma_f32_16x16x32_bf16 v[10:13], v[148:151], v[196:199], v[10:13]
	v_mfma_f32_16x16x32_bf16 v[10:13], v[152:155], v[200:203], v[10:13]
	v_mfma_f32_16x16x32_bf16 v[14:17], v[132:135], v[196:199], v[14:17]
	v_mfma_f32_16x16x32_bf16 v[14:17], v[136:139], v[200:203], v[14:17]
	s_setprio 0
	s_barrier
	s_add_i32 s62, s62, 2
	s_addk_i32 s61, 0x100
	s_cmp_ge_i32 s62, s3
	s_cbranch_scc0 .LBB0_1050

.LBB0_1181:
	v_add_u32_e32 v2, 0x10000, v232
	ds_read_b128 v[134:137], v2
	ds_read_b128 v[138:141], v2 offset:1024
	ds_read_b128 v[142:145], v2 offset:2048
	ds_read_b128 v[146:149], v2 offset:3072
	v_add_u32_e32 v2, 0x14000, v232
	ds_read_b128 v[150:153], v2
	ds_read_b128 v[154:157], v2 offset:1024
	ds_read_b128 v[158:161], v2 offset:2048
	ds_read_b128 v[162:165], v2 offset:3072
	s_add_i32 s50, s47, s90
	s_and_b64 s[18:19], exec, s[18:19]
	s_cselect_b32 s51, s88, s50
	s_add_i32 s50, s92, 0x80
	s_or_b32 s52, s51, 0x80
	s_add_i32 s18, s89, s93
	s_add_i32 s94, s94, 0x1bfffc80
	s_cmp_lt_u32 s91, 8
	s_cselect_b32 s18, s18, s94
	s_mov_b32 m0, s74
	s_add_i32 s19, s18, 0x80000
	ds_read_b128 v[166:169], v233
	ds_read_b128 v[170:173], v233 offset:1024
	ds_read_b128 v[174:177], v233 offset:2048
	ds_read_b128 v[178:181], v233 offset:3072
	ds_read_b128 v[182:185], v233 offset:4096
	ds_read_b128 v[186:189], v233 offset:5120
	ds_read_b128 v[190:193], v233 offset:6144
	ds_read_b128 v[194:197], v233 offset:7168
	buffer_load_dwordx4 v230, s[12:15], s19 offen lds
	s_add_i32 s18, s18, 0xc0000
	s_mov_b32 m0, s75
	s_nop 0
	buffer_load_dwordx4 v230, s[12:15], s18 offen lds
	s_waitcnt vmcnt(8)
	s_waitcnt lgkmcnt(0)
	s_setprio 1
	v_mfma_f32_16x16x32_bf16 v[130:133], v[134:137], v[166:169], v[130:133]
	s_barrier
	v_mfma_f32_16x16x32_bf16 v[130:133], v[138:141], v[170:173], v[130:133]
	v_mfma_f32_16x16x32_bf16 v[126:129], v[142:145], v[166:169], v[126:129]
	v_mfma_f32_16x16x32_bf16 v[126:129], v[146:149], v[170:173], v[126:129]
	v_mfma_f32_16x16x32_bf16 v[122:125], v[150:153], v[166:169], v[122:125]
	v_mfma_f32_16x16x32_bf16 v[122:125], v[154:157], v[170:173], v[122:125]
	v_mfma_f32_16x16x32_bf16 v[118:121], v[158:161], v[166:169], v[118:121]
	v_mfma_f32_16x16x32_bf16 v[118:121], v[162:165], v[170:173], v[118:121]
	v_mfma_f32_16x16x32_bf16 v[102:105], v[158:161], v[174:177], v[102:105]
	v_mfma_f32_16x16x32_bf16 v[102:105], v[162:165], v[178:181], v[102:105]
	v_mfma_f32_16x16x32_bf16 v[106:109], v[150:153], v[174:177], v[106:109]
	v_mfma_f32_16x16x32_bf16 v[106:109], v[154:157], v[178:181], v[106:109]
	v_mfma_f32_16x16x32_bf16 v[110:113], v[142:145], v[174:177], v[110:113]
	v_mfma_f32_16x16x32_bf16 v[110:113], v[146:149], v[178:181], v[110:113]
	v_mfma_f32_16x16x32_bf16 v[114:117], v[134:137], v[174:177], v[114:117]
	v_mfma_f32_16x16x32_bf16 v[114:117], v[138:141], v[178:181], v[114:117]
	v_mfma_f32_16x16x32_bf16 v[98:101], v[134:137], v[182:185], v[98:101]
	v_mfma_f32_16x16x32_bf16 v[98:101], v[138:141], v[186:189], v[98:101]
	v_mfma_f32_16x16x32_bf16 v[94:97], v[142:145], v[182:185], v[94:97]
	v_mfma_f32_16x16x32_bf16 v[94:97], v[146:149], v[186:189], v[94:97]
	v_mfma_f32_16x16x32_bf16 v[90:93], v[150:153], v[182:185], v[90:93]
	v_mfma_f32_16x16x32_bf16 v[90:93], v[154:157], v[186:189], v[90:93]
	v_mfma_f32_16x16x32_bf16 v[86:89], v[158:161], v[182:185], v[86:89]
	v_mfma_f32_16x16x32_bf16 v[86:89], v[162:165], v[186:189], v[86:89]
	v_mfma_f32_16x16x32_bf16 v[70:73], v[158:161], v[190:193], v[70:73]
	v_mfma_f32_16x16x32_bf16 v[70:73], v[162:165], v[194:197], v[70:73]
	v_mfma_f32_16x16x32_bf16 v[74:77], v[150:153], v[190:193], v[74:77]
	v_mfma_f32_16x16x32_bf16 v[74:77], v[154:157], v[194:197], v[74:77]
	v_mfma_f32_16x16x32_bf16 v[78:81], v[142:145], v[190:193], v[78:81]
	v_mfma_f32_16x16x32_bf16 v[78:81], v[146:149], v[194:197], v[78:81]
	v_mfma_f32_16x16x32_bf16 v[82:85], v[134:137], v[190:193], v[82:85]
	v_mfma_f32_16x16x32_bf16 v[82:85], v[138:141], v[194:197], v[82:85]
	s_setprio 0
	s_barrier
	s_mov_b32 m0, s27
	s_mov_b32 s18, s14
	s_mov_b32 s19, s15
	buffer_load_dwordx4 v231, s[16:19], s51 offen lds
	s_add_i32 s53, s51, 0x18000
	s_mov_b32 m0, s30
	s_nop 0
	buffer_load_dwordx4 v231, s[16:19], s53 offen lds
	s_add_i32 s53, s51, 0x30000
	s_mov_b32 m0, s31
	s_nop 0
	buffer_load_dwordx4 v231, s[16:19], s53 offen lds
	s_add_i32 s53, s51, 0x48000
	s_mov_b32 m0, s54
	s_nop 0
	buffer_load_dwordx4 v231, s[16:19], s53 offen lds
	s_mov_b32 m0, s25
	s_add_i32 s53, s92, 0x40000
	buffer_load_dwordx4 v230, s[12:15], s92 offen lds
	s_mov_b32 m0, s55
	s_nop 0
	buffer_load_dwordx4 v230, s[12:15], s53 offen lds
	ds_read_b128 v[166:169], v233 offset:16384
	ds_read_b128 v[170:173], v233 offset:17408
	ds_read_b128 v[174:177], v233 offset:18432
	ds_read_b128 v[178:181], v233 offset:19456
	ds_read_b128 v[182:185], v233 offset:20480
	ds_read_b128 v[186:189], v233 offset:21504
	ds_read_b128 v[190:193], v233 offset:22528
	ds_read_b128 v[194:197], v233 offset:23552
	s_waitcnt vmcnt(8)
	s_waitcnt lgkmcnt(0)
	s_setprio 1
	v_mfma_f32_16x16x32_bf16 v[66:69], v[134:137], v[166:169], v[66:69]
	s_barrier
	v_mfma_f32_16x16x32_bf16 v[62:65], v[142:145], v[166:169], v[62:65]
	v_mfma_f32_16x16x32_bf16 v[50:53], v[134:137], v[174:177], v[50:53]
	v_mfma_f32_16x16x32_bf16 v[46:49], v[142:145], v[174:177], v[46:49]
	v_mfma_f32_16x16x32_bf16 v[34:37], v[134:137], v[182:185], v[34:37]
	v_mfma_f32_16x16x32_bf16 v[30:33], v[142:145], v[182:185], v[30:33]
	v_mfma_f32_16x16x32_bf16 v[18:21], v[134:137], v[190:193], v[18:21]
	v_mfma_f32_16x16x32_bf16 v[14:17], v[142:145], v[190:193], v[14:17]
	v_mfma_f32_16x16x32_bf16 v[58:61], v[150:153], v[166:169], v[58:61]
	v_mfma_f32_16x16x32_bf16 v[54:57], v[158:161], v[166:169], v[54:57]
	v_mfma_f32_16x16x32_bf16 v[42:45], v[150:153], v[174:177], v[42:45]
	v_mfma_f32_16x16x32_bf16 v[38:41], v[158:161], v[174:177], v[38:41]
	v_mfma_f32_16x16x32_bf16 v[26:29], v[150:153], v[182:185], v[26:29]
	v_mfma_f32_16x16x32_bf16 v[22:25], v[158:161], v[182:185], v[22:25]
	v_mfma_f32_16x16x32_bf16 v[10:13], v[150:153], v[190:193], v[10:13]
	v_mfma_f32_16x16x32_bf16 v[4:7], v[158:161], v[190:193], v[6:9]
	v_mfma_f32_16x16x32_bf16 v[66:69], v[138:141], v[170:173], v[66:69]
	v_mfma_f32_16x16x32_bf16 v[62:65], v[146:149], v[170:173], v[62:65]
	v_mfma_f32_16x16x32_bf16 v[50:53], v[138:141], v[178:181], v[50:53]
	v_mfma_f32_16x16x32_bf16 v[46:49], v[146:149], v[178:181], v[46:49]
	v_mfma_f32_16x16x32_bf16 v[34:37], v[138:141], v[186:189], v[34:37]
	v_mfma_f32_16x16x32_bf16 v[30:33], v[146:149], v[186:189], v[30:33]
	v_mfma_f32_16x16x32_bf16 v[18:21], v[138:141], v[194:197], v[18:21]
	v_mfma_f32_16x16x32_bf16 v[14:17], v[146:149], v[194:197], v[14:17]
	v_mfma_f32_16x16x32_bf16 v[58:61], v[154:157], v[170:173], v[58:61]
	v_mfma_f32_16x16x32_bf16 v[54:57], v[162:165], v[170:173], v[54:57]
	v_mfma_f32_16x16x32_bf16 v[42:45], v[154:157], v[178:181], v[42:45]
	v_mfma_f32_16x16x32_bf16 v[38:41], v[162:165], v[178:181], v[38:41]
	v_mfma_f32_16x16x32_bf16 v[26:29], v[154:157], v[186:189], v[26:29]
	v_mfma_f32_16x16x32_bf16 v[22:25], v[162:165], v[186:189], v[22:25]
	v_mfma_f32_16x16x32_bf16 v[10:13], v[154:157], v[194:197], v[10:13]
	v_mfma_f32_16x16x32_bf16 v[4:7], v[162:165], v[194:197], v[4:7]
	s_setprio 0
	s_barrier
	v_add_u32_e32 v2, 0x18000, v232
	ds_read_b128 v[134:137], v2
	ds_read_b128 v[138:141], v2 offset:1024
	ds_read_b128 v[142:145], v2 offset:2048
	ds_read_b128 v[146:149], v2 offset:3072
	v_add_u32_e32 v2, 0x1c000, v232
	ds_read_b128 v[150:153], v2
	ds_read_b128 v[154:157], v2 offset:1024
	ds_read_b128 v[158:161], v2 offset:2048
	ds_read_b128 v[162:165], v2 offset:3072
	s_mov_b32 m0, s56
	s_add_i32 s53, s92, 0x80000
	ds_read_b128 v[166:169], v233 offset:32768
	ds_read_b128 v[170:173], v233 offset:33792
	ds_read_b128 v[174:177], v233 offset:34816
	ds_read_b128 v[178:181], v233 offset:35840
	ds_read_b128 v[182:185], v233 offset:36864
	ds_read_b128 v[186:189], v233 offset:37888
	ds_read_b128 v[190:193], v233 offset:38912
	ds_read_b128 v[194:197], v233 offset:39936
	buffer_load_dwordx4 v230, s[12:15], s53 offen lds
	s_add_i32 s53, s92, 0xc0000
	s_mov_b32 m0, s57
	s_nop 0
	buffer_load_dwordx4 v230, s[12:15], s53 offen lds
	s_waitcnt vmcnt(8)
	s_waitcnt lgkmcnt(0)
	s_setprio 1
	v_mfma_f32_16x16x32_bf16 v[130:133], v[134:137], v[166:169], v[130:133]
	s_barrier
	v_mfma_f32_16x16x32_bf16 v[130:133], v[138:141], v[170:173], v[130:133]
	v_mfma_f32_16x16x32_bf16 v[126:129], v[142:145], v[166:169], v[126:129]
	v_mfma_f32_16x16x32_bf16 v[126:129], v[146:149], v[170:173], v[126:129]
	v_mfma_f32_16x16x32_bf16 v[122:125], v[150:153], v[166:169], v[122:125]
	v_mfma_f32_16x16x32_bf16 v[122:125], v[154:157], v[170:173], v[122:125]
	v_mfma_f32_16x16x32_bf16 v[118:121], v[158:161], v[166:169], v[118:121]
	v_mfma_f32_16x16x32_bf16 v[118:121], v[162:165], v[170:173], v[118:121]
	v_mfma_f32_16x16x32_bf16 v[102:105], v[158:161], v[174:177], v[102:105]
	v_mfma_f32_16x16x32_bf16 v[102:105], v[162:165], v[178:181], v[102:105]
	v_mfma_f32_16x16x32_bf16 v[106:109], v[150:153], v[174:177], v[106:109]
	v_mfma_f32_16x16x32_bf16 v[106:109], v[154:157], v[178:181], v[106:109]
	v_mfma_f32_16x16x32_bf16 v[110:113], v[142:145], v[174:177], v[110:113]
	v_mfma_f32_16x16x32_bf16 v[110:113], v[146:149], v[178:181], v[110:113]
	v_mfma_f32_16x16x32_bf16 v[114:117], v[134:137], v[174:177], v[114:117]
	v_mfma_f32_16x16x32_bf16 v[114:117], v[138:141], v[178:181], v[114:117]
	v_mfma_f32_16x16x32_bf16 v[98:101], v[134:137], v[182:185], v[98:101]
	v_mfma_f32_16x16x32_bf16 v[98:101], v[138:141], v[186:189], v[98:101]
	v_mfma_f32_16x16x32_bf16 v[94:97], v[142:145], v[182:185], v[94:97]
	v_mfma_f32_16x16x32_bf16 v[94:97], v[146:149], v[186:189], v[94:97]
	v_mfma_f32_16x16x32_bf16 v[90:93], v[150:153], v[182:185], v[90:93]
	v_mfma_f32_16x16x32_bf16 v[90:93], v[154:157], v[186:189], v[90:93]
	v_mfma_f32_16x16x32_bf16 v[86:89], v[158:161], v[182:185], v[86:89]
	v_mfma_f32_16x16x32_bf16 v[86:89], v[162:165], v[186:189], v[86:89]
	v_mfma_f32_16x16x32_bf16 v[70:73], v[158:161], v[190:193], v[70:73]
	v_mfma_f32_16x16x32_bf16 v[70:73], v[162:165], v[194:197], v[70:73]
	v_mfma_f32_16x16x32_bf16 v[74:77], v[150:153], v[190:193], v[74:77]
	v_mfma_f32_16x16x32_bf16 v[74:77], v[154:157], v[194:197], v[74:77]
	v_mfma_f32_16x16x32_bf16 v[78:81], v[142:145], v[190:193], v[78:81]
	v_mfma_f32_16x16x32_bf16 v[78:81], v[146:149], v[194:197], v[78:81]
	v_mfma_f32_16x16x32_bf16 v[82:85], v[134:137], v[190:193], v[82:85]
	v_mfma_f32_16x16x32_bf16 v[82:85], v[138:141], v[194:197], v[82:85]
	s_setprio 0
	s_barrier
	s_mov_b32 m0, s64
	s_nop 0
	buffer_load_dwordx4 v231, s[16:19], s52 offen lds
	s_add_i32 s52, s51, 0x18080
	s_mov_b32 m0, s65
	s_nop 0
	buffer_load_dwordx4 v231, s[16:19], s52 offen lds
	s_add_i32 s52, s51, 0x30080
	s_mov_b32 m0, s68
	s_add_i32 s51, s51, 0x48080
	buffer_load_dwordx4 v231, s[16:19], s52 offen lds
	s_mov_b32 m0, s69
	s_nop 0
	buffer_load_dwordx4 v231, s[16:19], s51 offen lds
	s_mov_b32 m0, s66
	s_add_i32 s18, s92, 0x40080
	buffer_load_dwordx4 v230, s[12:15], s50 offen lds
	s_mov_b32 m0, s67
	s_nop 0
	buffer_load_dwordx4 v230, s[12:15], s18 offen lds
	ds_read_b128 v[166:169], v233 offset:49152
	ds_read_b128 v[170:173], v233 offset:50176
	ds_read_b128 v[174:177], v233 offset:51200
	ds_read_b128 v[178:181], v233 offset:52224
	ds_read_b128 v[182:185], v233 offset:53248
	ds_read_b128 v[186:189], v233 offset:54272
	ds_read_b128 v[190:193], v233 offset:55296
	ds_read_b128 v[194:197], v233 offset:56320
	s_waitcnt vmcnt(8)
	s_waitcnt lgkmcnt(0)
	s_setprio 1
	v_mfma_f32_16x16x32_bf16 v[66:69], v[134:137], v[166:169], v[66:69]
	s_barrier
	v_mfma_f32_16x16x32_bf16 v[62:65], v[142:145], v[166:169], v[62:65]
	v_mfma_f32_16x16x32_bf16 v[50:53], v[134:137], v[174:177], v[50:53]
	v_mfma_f32_16x16x32_bf16 v[46:49], v[142:145], v[174:177], v[46:49]
	v_mfma_f32_16x16x32_bf16 v[34:37], v[134:137], v[182:185], v[34:37]
	v_mfma_f32_16x16x32_bf16 v[30:33], v[142:145], v[182:185], v[30:33]
	v_mfma_f32_16x16x32_bf16 v[18:21], v[134:137], v[190:193], v[18:21]
	v_mfma_f32_16x16x32_bf16 v[14:17], v[142:145], v[190:193], v[14:17]
	v_mfma_f32_16x16x32_bf16 v[58:61], v[150:153], v[166:169], v[58:61]
	v_mfma_f32_16x16x32_bf16 v[54:57], v[158:161], v[166:169], v[54:57]
	v_mfma_f32_16x16x32_bf16 v[42:45], v[150:153], v[174:177], v[42:45]
	v_mfma_f32_16x16x32_bf16 v[38:41], v[158:161], v[174:177], v[38:41]
	v_mfma_f32_16x16x32_bf16 v[26:29], v[150:153], v[182:185], v[26:29]
	v_mfma_f32_16x16x32_bf16 v[22:25], v[158:161], v[182:185], v[22:25]
	v_mfma_f32_16x16x32_bf16 v[8:11], v[150:153], v[190:193], v[10:13]
	v_mfma_f32_16x16x32_bf16 v[4:7], v[158:161], v[190:193], v[4:7]
	v_mfma_f32_16x16x32_bf16 v[66:69], v[138:141], v[170:173], v[66:69]
	v_mfma_f32_16x16x32_bf16 v[62:65], v[146:149], v[170:173], v[62:65]
	v_mfma_f32_16x16x32_bf16 v[50:53], v[138:141], v[178:181], v[50:53]
	v_mfma_f32_16x16x32_bf16 v[46:49], v[146:149], v[178:181], v[46:49]
	v_mfma_f32_16x16x32_bf16 v[34:37], v[138:141], v[186:189], v[34:37]
	v_mfma_f32_16x16x32_bf16 v[30:33], v[146:149], v[186:189], v[30:33]
	v_mfma_f32_16x16x32_bf16 v[18:21], v[138:141], v[194:197], v[18:21]
	v_mfma_f32_16x16x32_bf16 v[14:17], v[146:149], v[194:197], v[14:17]
	v_mfma_f32_16x16x32_bf16 v[58:61], v[154:157], v[170:173], v[58:61]
	v_mfma_f32_16x16x32_bf16 v[54:57], v[162:165], v[170:173], v[54:57]
	v_mfma_f32_16x16x32_bf16 v[42:45], v[154:157], v[178:181], v[42:45]
	v_mfma_f32_16x16x32_bf16 v[38:41], v[162:165], v[178:181], v[38:41]
	v_mfma_f32_16x16x32_bf16 v[26:29], v[154:157], v[186:189], v[26:29]
	v_mfma_f32_16x16x32_bf16 v[22:25], v[162:165], v[186:189], v[22:25]
	v_mfma_f32_16x16x32_bf16 v[10:13], v[154:157], v[194:197], v[8:11]
	v_mfma_f32_16x16x32_bf16 v[6:9], v[162:165], v[194:197], v[4:7]
	s_setprio 0
	s_barrier
	s_add_i32 s91, s91, 2
	s_addk_i32 s90, 0x100
	s_cmp_ge_i32 s91, s3
	s_cbranch_scc1 .LBB0_1193

.LBB0_1290:
	s_add_i32 s18, s72, 0xffe80080
	s_cmp_eq_u32 s56, s74
	s_cselect_b32 s75, s6, s18
	s_cselect_b32 s77, s7, s73
	s_or_b32 s76, s75, 0x80
	s_add_i32 s18, s72, 0xfff80000
	s_mov_b32 m0, s57
	s_nop 0
	buffer_load_dwordx4 v222, s[12:15], s18 offen lds
	s_mov_b32 m0, s60
	s_nop 0
	buffer_load_dwordx4 v222, s[12:15], s72 offen lds
	ds_read_b128 v[106:109], v224
	ds_read_b128 v[118:121], v224 offset:1024
	ds_read_b128 v[130:133], v224 offset:2048
	ds_read_b128 v[138:141], v224 offset:3072
	ds_read_b128 v[146:149], v225
	ds_read_b128 v[150:153], v225 offset:1024
	ds_read_b128 v[154:157], v225 offset:2048
	ds_read_b128 v[158:161], v225 offset:3072
	ds_read_b128 v[162:165], v226
	ds_read_b128 v[166:169], v226 offset:1024
	ds_read_b128 v[170:173], v226 offset:2048
	ds_read_b128 v[174:177], v226 offset:3072
	ds_read_b128 v[178:181], v226 offset:4096
	ds_read_b128 v[182:185], v226 offset:5120
	ds_read_b128 v[190:193], v226 offset:6144
	ds_read_b128 v[194:197], v226 offset:7168
	s_waitcnt vmcnt(8)
	s_waitcnt lgkmcnt(0)
	s_setprio 1
	v_mfma_f32_16x16x32_bf16 v[142:145], v[106:109], v[162:165], v[142:145]
	s_barrier
	v_mfma_f32_16x16x32_bf16 v[142:145], v[118:121], v[166:169], v[142:145]
	v_mfma_f32_16x16x32_bf16 v[134:137], v[130:133], v[162:165], v[134:137]
	v_mfma_f32_16x16x32_bf16 v[134:137], v[138:141], v[166:169], v[134:137]
	v_mfma_f32_16x16x32_bf16 v[126:129], v[146:149], v[162:165], v[126:129]
	v_mfma_f32_16x16x32_bf16 v[126:129], v[150:153], v[166:169], v[126:129]
	v_mfma_f32_16x16x32_bf16 v[122:125], v[154:157], v[162:165], v[122:125]
	v_mfma_f32_16x16x32_bf16 v[122:125], v[158:161], v[166:169], v[122:125]
	v_mfma_f32_16x16x32_bf16 v[98:101], v[154:157], v[170:173], v[98:101]
	v_mfma_f32_16x16x32_bf16 v[98:101], v[158:161], v[174:177], v[98:101]
	v_mfma_f32_16x16x32_bf16 v[102:105], v[146:149], v[170:173], v[102:105]
	v_mfma_f32_16x16x32_bf16 v[102:105], v[150:153], v[174:177], v[102:105]
	v_mfma_f32_16x16x32_bf16 v[110:113], v[130:133], v[170:173], v[110:113]
	v_mfma_f32_16x16x32_bf16 v[110:113], v[138:141], v[174:177], v[110:113]
	v_mfma_f32_16x16x32_bf16 v[114:117], v[106:109], v[170:173], v[114:117]
	v_mfma_f32_16x16x32_bf16 v[114:117], v[118:121], v[174:177], v[114:117]
	v_mfma_f32_16x16x32_bf16 v[94:97], v[106:109], v[178:181], v[94:97]
	v_mfma_f32_16x16x32_bf16 v[94:97], v[118:121], v[182:185], v[94:97]
	v_mfma_f32_16x16x32_bf16 v[90:93], v[130:133], v[178:181], v[90:93]
	v_mfma_f32_16x16x32_bf16 v[90:93], v[138:141], v[182:185], v[90:93]
	v_mfma_f32_16x16x32_bf16 v[86:89], v[146:149], v[178:181], v[86:89]
	v_mfma_f32_16x16x32_bf16 v[86:89], v[150:153], v[182:185], v[86:89]
	v_mfma_f32_16x16x32_bf16 v[82:85], v[154:157], v[178:181], v[82:85]
	v_mfma_f32_16x16x32_bf16 v[82:85], v[158:161], v[182:185], v[82:85]
	v_mfma_f32_16x16x32_bf16 v[66:69], v[154:157], v[190:193], v[66:69]
	v_mfma_f32_16x16x32_bf16 v[66:69], v[158:161], v[194:197], v[66:69]
	v_mfma_f32_16x16x32_bf16 v[70:73], v[146:149], v[190:193], v[70:73]
	v_mfma_f32_16x16x32_bf16 v[70:73], v[150:153], v[194:197], v[70:73]
	v_mfma_f32_16x16x32_bf16 v[74:77], v[130:133], v[190:193], v[74:77]
	v_mfma_f32_16x16x32_bf16 v[74:77], v[138:141], v[194:197], v[74:77]
	v_mfma_f32_16x16x32_bf16 v[78:81], v[106:109], v[190:193], v[78:81]
	v_mfma_f32_16x16x32_bf16 v[78:81], v[118:121], v[194:197], v[78:81]
	s_setprio 0
	s_barrier
	s_mov_b32 m0, s27
	s_mov_b32 s18, s14
	s_mov_b32 s19, s15
	buffer_load_dwordx4 v223, s[16:19], s77 offen lds
	s_add_i32 s78, s77, 0x80000
	s_mov_b32 m0, s30
	s_nop 0
	buffer_load_dwordx4 v223, s[16:19], s78 offen lds
	s_add_i32 s78, s77, 0x100000
	s_mov_b32 m0, s31
	s_nop 0
	buffer_load_dwordx4 v223, s[16:19], s78 offen lds
	s_add_i32 s78, s77, 0x180000
	s_mov_b32 m0, s41
	s_nop 0
	buffer_load_dwordx4 v223, s[16:19], s78 offen lds
	s_mov_b32 m0, s25
	s_add_i32 s78, s75, 0x80000
	buffer_load_dwordx4 v222, s[12:15], s75 offen lds
	s_mov_b32 m0, s42
	s_nop 0
	buffer_load_dwordx4 v222, s[12:15], s78 offen lds
	ds_read_b128 v[162:165], v226 offset:16384
	ds_read_b128 v[166:169], v226 offset:17408
	ds_read_b128 v[170:173], v226 offset:18432
	ds_read_b128 v[174:177], v226 offset:19456
	ds_read_b128 v[178:181], v226 offset:20480
	ds_read_b128 v[182:185], v226 offset:21504
	ds_read_b128 v[190:193], v226 offset:22528
	ds_read_b128 v[194:197], v226 offset:23552
	s_waitcnt vmcnt(8)
	s_waitcnt lgkmcnt(0)
	s_setprio 1
	v_mfma_f32_16x16x32_bf16 v[62:65], v[106:109], v[162:165], v[62:65]
	s_barrier
	v_mfma_f32_16x16x32_bf16 v[62:65], v[118:121], v[166:169], v[62:65]
	v_mfma_f32_16x16x32_bf16 v[58:61], v[130:133], v[162:165], v[58:61]
	v_mfma_f32_16x16x32_bf16 v[58:61], v[138:141], v[166:169], v[58:61]
	v_mfma_f32_16x16x32_bf16 v[54:57], v[146:149], v[162:165], v[54:57]
	v_mfma_f32_16x16x32_bf16 v[54:57], v[150:153], v[166:169], v[54:57]
	v_mfma_f32_16x16x32_bf16 v[50:53], v[154:157], v[162:165], v[50:53]
	v_mfma_f32_16x16x32_bf16 v[50:53], v[158:161], v[166:169], v[50:53]
	v_mfma_f32_16x16x32_bf16 v[34:37], v[154:157], v[170:173], v[34:37]
	v_mfma_f32_16x16x32_bf16 v[34:37], v[158:161], v[174:177], v[34:37]
	v_mfma_f32_16x16x32_bf16 v[38:41], v[146:149], v[170:173], v[38:41]
	v_mfma_f32_16x16x32_bf16 v[38:41], v[150:153], v[174:177], v[38:41]
	v_mfma_f32_16x16x32_bf16 v[42:45], v[130:133], v[170:173], v[42:45]
	v_mfma_f32_16x16x32_bf16 v[42:45], v[138:141], v[174:177], v[42:45]
	v_mfma_f32_16x16x32_bf16 v[46:49], v[106:109], v[170:173], v[46:49]
	v_mfma_f32_16x16x32_bf16 v[46:49], v[118:121], v[174:177], v[46:49]
	v_mfma_f32_16x16x32_bf16 v[30:33], v[106:109], v[178:181], v[30:33]
	v_mfma_f32_16x16x32_bf16 v[30:33], v[118:121], v[182:185], v[30:33]
	v_mfma_f32_16x16x32_bf16 v[26:29], v[130:133], v[178:181], v[26:29]
	v_mfma_f32_16x16x32_bf16 v[26:29], v[138:141], v[182:185], v[26:29]
	v_mfma_f32_16x16x32_bf16 v[22:25], v[146:149], v[178:181], v[22:25]
	v_mfma_f32_16x16x32_bf16 v[22:25], v[150:153], v[182:185], v[22:25]
	v_mfma_f32_16x16x32_bf16 v[18:21], v[154:157], v[178:181], v[18:21]
	v_mfma_f32_16x16x32_bf16 v[18:21], v[158:161], v[182:185], v[18:21]
	v_mfma_f32_16x16x32_bf16 v[2:5], v[154:157], v[190:193], v[2:5]
	v_mfma_f32_16x16x32_bf16 v[2:5], v[158:161], v[194:197], v[2:5]
	v_mfma_f32_16x16x32_bf16 v[6:9], v[146:149], v[190:193], v[6:9]
	v_mfma_f32_16x16x32_bf16 v[6:9], v[150:153], v[194:197], v[6:9]
	v_mfma_f32_16x16x32_bf16 v[10:13], v[130:133], v[190:193], v[10:13]
	v_mfma_f32_16x16x32_bf16 v[10:13], v[138:141], v[194:197], v[10:13]
	v_mfma_f32_16x16x32_bf16 v[14:17], v[106:109], v[190:193], v[14:17]
	v_mfma_f32_16x16x32_bf16 v[14:17], v[118:121], v[194:197], v[14:17]
	s_setprio 0
	s_barrier
	s_mov_b32 m0, s43
	s_add_i32 s78, s75, 0x100000
	buffer_load_dwordx4 v222, s[12:15], s78 offen lds
	s_add_i32 s78, s75, 0x180000
	s_mov_b32 m0, s44
	s_nop 0
	buffer_load_dwordx4 v222, s[12:15], s78 offen lds
	ds_read_b128 v[106:109], v227
	ds_read_b128 v[118:121], v227 offset:1024
	ds_read_b128 v[130:133], v227 offset:2048
	ds_read_b128 v[138:141], v227 offset:3072
	ds_read_b128 v[146:149], v228
	ds_read_b128 v[150:153], v228 offset:1024
	ds_read_b128 v[154:157], v228 offset:2048
	ds_read_b128 v[158:161], v228 offset:3072
	ds_read_b128 v[162:165], v226 offset:32768
	ds_read_b128 v[166:169], v226 offset:33792
	ds_read_b128 v[170:173], v226 offset:34816
	ds_read_b128 v[174:177], v226 offset:35840
	ds_read_b128 v[178:181], v226 offset:36864
	ds_read_b128 v[182:185], v226 offset:37888
	ds_read_b128 v[190:193], v226 offset:38912
	ds_read_b128 v[194:197], v226 offset:39936
	s_waitcnt vmcnt(8)
	s_waitcnt lgkmcnt(0)
	s_setprio 1
	v_mfma_f32_16x16x32_bf16 v[142:145], v[106:109], v[162:165], v[142:145]
	s_barrier
	v_mfma_f32_16x16x32_bf16 v[142:145], v[118:121], v[166:169], v[142:145]
	v_mfma_f32_16x16x32_bf16 v[134:137], v[130:133], v[162:165], v[134:137]
	v_mfma_f32_16x16x32_bf16 v[134:137], v[138:141], v[166:169], v[134:137]
	v_mfma_f32_16x16x32_bf16 v[126:129], v[146:149], v[162:165], v[126:129]
	v_mfma_f32_16x16x32_bf16 v[126:129], v[150:153], v[166:169], v[126:129]
	v_mfma_f32_16x16x32_bf16 v[122:125], v[154:157], v[162:165], v[122:125]
	v_mfma_f32_16x16x32_bf16 v[122:125], v[158:161], v[166:169], v[122:125]
	v_mfma_f32_16x16x32_bf16 v[98:101], v[154:157], v[170:173], v[98:101]
	v_mfma_f32_16x16x32_bf16 v[98:101], v[158:161], v[174:177], v[98:101]
	v_mfma_f32_16x16x32_bf16 v[102:105], v[146:149], v[170:173], v[102:105]
	v_mfma_f32_16x16x32_bf16 v[102:105], v[150:153], v[174:177], v[102:105]
	v_mfma_f32_16x16x32_bf16 v[110:113], v[130:133], v[170:173], v[110:113]
	v_mfma_f32_16x16x32_bf16 v[110:113], v[138:141], v[174:177], v[110:113]
	v_mfma_f32_16x16x32_bf16 v[114:117], v[106:109], v[170:173], v[114:117]
	v_mfma_f32_16x16x32_bf16 v[114:117], v[118:121], v[174:177], v[114:117]
	v_mfma_f32_16x16x32_bf16 v[94:97], v[106:109], v[178:181], v[94:97]
	v_mfma_f32_16x16x32_bf16 v[94:97], v[118:121], v[182:185], v[94:97]
	v_mfma_f32_16x16x32_bf16 v[90:93], v[130:133], v[178:181], v[90:93]
	v_mfma_f32_16x16x32_bf16 v[90:93], v[138:141], v[182:185], v[90:93]
	v_mfma_f32_16x16x32_bf16 v[86:89], v[146:149], v[178:181], v[86:89]
	v_mfma_f32_16x16x32_bf16 v[86:89], v[150:153], v[182:185], v[86:89]
	v_mfma_f32_16x16x32_bf16 v[82:85], v[154:157], v[178:181], v[82:85]
	v_mfma_f32_16x16x32_bf16 v[82:85], v[158:161], v[182:185], v[82:85]
	v_mfma_f32_16x16x32_bf16 v[66:69], v[154:157], v[190:193], v[66:69]
	v_mfma_f32_16x16x32_bf16 v[66:69], v[158:161], v[194:197], v[66:69]
	v_mfma_f32_16x16x32_bf16 v[70:73], v[146:149], v[190:193], v[70:73]
	v_mfma_f32_16x16x32_bf16 v[70:73], v[150:153], v[194:197], v[70:73]
	v_mfma_f32_16x16x32_bf16 v[74:77], v[130:133], v[190:193], v[74:77]
	v_mfma_f32_16x16x32_bf16 v[74:77], v[138:141], v[194:197], v[74:77]
	v_mfma_f32_16x16x32_bf16 v[78:81], v[106:109], v[190:193], v[78:81]
	v_mfma_f32_16x16x32_bf16 v[78:81], v[118:121], v[194:197], v[78:81]
	s_setprio 0
	s_barrier
	s_mov_b32 m0, s48
	s_or_b32 s78, s77, 0x80
	buffer_load_dwordx4 v223, s[16:19], s78 offen lds
	s_add_i32 s78, s77, 0x80080
	s_mov_b32 m0, s49
	s_add_i32 s75, s75, 0x80080
	buffer_load_dwordx4 v223, s[16:19], s78 offen lds
	s_add_i32 s78, s77, 0x100080
	s_mov_b32 m0, s52
	s_add_i32 s77, s77, 0x180080
	buffer_load_dwordx4 v223, s[16:19], s78 offen lds
	s_mov_b32 m0, s53
	s_nop 0
	buffer_load_dwordx4 v223, s[16:19], s77 offen lds
	s_mov_b32 m0, s50
	s_nop 0
	buffer_load_dwordx4 v222, s[12:15], s76 offen lds
	s_mov_b32 m0, s51
	s_nop 0
	buffer_load_dwordx4 v222, s[12:15], s75 offen lds
	ds_read_b128 v[162:165], v226 offset:49152
	ds_read_b128 v[166:169], v226 offset:50176
	ds_read_b128 v[170:173], v226 offset:51200
	ds_read_b128 v[174:177], v226 offset:52224
	ds_read_b128 v[178:181], v226 offset:53248
	ds_read_b128 v[182:185], v226 offset:54272
	ds_read_b128 v[190:193], v226 offset:55296
	ds_read_b128 v[194:197], v226 offset:56320
	s_waitcnt vmcnt(8)
	s_waitcnt lgkmcnt(0)
	s_setprio 1
	v_mfma_f32_16x16x32_bf16 v[62:65], v[106:109], v[162:165], v[62:65]
	s_barrier
	v_mfma_f32_16x16x32_bf16 v[62:65], v[118:121], v[166:169], v[62:65]
	v_mfma_f32_16x16x32_bf16 v[58:61], v[130:133], v[162:165], v[58:61]
	v_mfma_f32_16x16x32_bf16 v[58:61], v[138:141], v[166:169], v[58:61]
	v_mfma_f32_16x16x32_bf16 v[54:57], v[146:149], v[162:165], v[54:57]
	v_mfma_f32_16x16x32_bf16 v[54:57], v[150:153], v[166:169], v[54:57]
	v_mfma_f32_16x16x32_bf16 v[50:53], v[154:157], v[162:165], v[50:53]
	v_mfma_f32_16x16x32_bf16 v[50:53], v[158:161], v[166:169], v[50:53]
	v_mfma_f32_16x16x32_bf16 v[34:37], v[154:157], v[170:173], v[34:37]
	v_mfma_f32_16x16x32_bf16 v[34:37], v[158:161], v[174:177], v[34:37]
	v_mfma_f32_16x16x32_bf16 v[38:41], v[146:149], v[170:173], v[38:41]
	v_mfma_f32_16x16x32_bf16 v[38:41], v[150:153], v[174:177], v[38:41]
	v_mfma_f32_16x16x32_bf16 v[42:45], v[130:133], v[170:173], v[42:45]
	v_mfma_f32_16x16x32_bf16 v[42:45], v[138:141], v[174:177], v[42:45]
	v_mfma_f32_16x16x32_bf16 v[46:49], v[106:109], v[170:173], v[46:49]
	v_mfma_f32_16x16x32_bf16 v[46:49], v[118:121], v[174:177], v[46:49]
	v_mfma_f32_16x16x32_bf16 v[30:33], v[106:109], v[178:181], v[30:33]
	v_mfma_f32_16x16x32_bf16 v[30:33], v[118:121], v[182:185], v[30:33]
	v_mfma_f32_16x16x32_bf16 v[26:29], v[130:133], v[178:181], v[26:29]
	v_mfma_f32_16x16x32_bf16 v[26:29], v[138:141], v[182:185], v[26:29]
	v_mfma_f32_16x16x32_bf16 v[22:25], v[146:149], v[178:181], v[22:25]
	v_mfma_f32_16x16x32_bf16 v[22:25], v[150:153], v[182:185], v[22:25]
	v_mfma_f32_16x16x32_bf16 v[18:21], v[154:157], v[178:181], v[18:21]
	v_mfma_f32_16x16x32_bf16 v[18:21], v[158:161], v[182:185], v[18:21]
	v_mfma_f32_16x16x32_bf16 v[2:5], v[154:157], v[190:193], v[2:5]
	v_mfma_f32_16x16x32_bf16 v[2:5], v[158:161], v[194:197], v[2:5]
	v_mfma_f32_16x16x32_bf16 v[6:9], v[146:149], v[190:193], v[6:9]
	v_mfma_f32_16x16x32_bf16 v[6:9], v[150:153], v[194:197], v[6:9]
	v_mfma_f32_16x16x32_bf16 v[10:13], v[130:133], v[190:193], v[10:13]
	v_mfma_f32_16x16x32_bf16 v[10:13], v[138:141], v[194:197], v[10:13]
	v_mfma_f32_16x16x32_bf16 v[14:17], v[106:109], v[190:193], v[14:17]
	v_mfma_f32_16x16x32_bf16 v[14:17], v[118:121], v[194:197], v[14:17]
	s_setprio 0
	s_barrier
	s_add_i32 s74, s74, 2
	s_addk_i32 s72, 0x100
	s_addk_i32 s73, 0x100
	s_cmp_ge_i32 s74, s3
	s_cbranch_scc0 .LBB0_1290
	s_and_b64 vcc, exec, s[38:39]
	s_cbranch_vccz .LBB0_1293

.LBB0_1382:
	s_add_i32 s14, s74, 0xffe80080
	s_cmp_eq_u32 s61, s76
	s_cselect_b32 s77, s72, s14
	s_cselect_b32 s79, s73, s75
	s_or_b32 s78, s77, 0x80
	s_add_i32 s14, s74, 0xfff80000
	s_mov_b32 m0, s62
	s_nop 0
	buffer_load_dwordx4 v136, s[16:19], s14 offen lds
	s_mov_b32 m0, s63
	s_nop 0
	buffer_load_dwordx4 v136, s[16:19], s74 offen lds
	ds_read_b128 v[144:147], v138
	ds_read_b128 v[148:151], v138 offset:1024
	ds_read_b128 v[152:155], v138 offset:2048
	ds_read_b128 v[156:159], v138 offset:3072
	ds_read_b128 v[160:163], v139
	ds_read_b128 v[164:167], v139 offset:1024
	ds_read_b128 v[168:171], v139 offset:2048
	ds_read_b128 v[172:175], v139 offset:3072
	ds_read_b128 v[176:179], v140
	ds_read_b128 v[180:183], v140 offset:1024
	ds_read_b128 v[184:187], v140 offset:2048
	ds_read_b128 v[188:191], v140 offset:3072
	ds_read_b128 v[192:195], v140 offset:4096
	ds_read_b128 v[196:199], v140 offset:5120
	ds_read_b128 v[200:203], v140 offset:6144
	ds_read_b128 v[204:207], v140 offset:7168
	s_waitcnt vmcnt(8)
	s_waitcnt lgkmcnt(0)
	s_setprio 1
	v_mfma_f32_16x16x32_bf16 v[118:121], v[144:147], v[176:179], v[118:121]
	s_barrier
	v_mfma_f32_16x16x32_bf16 v[118:121], v[148:151], v[180:183], v[118:121]
	v_mfma_f32_16x16x32_bf16 v[114:117], v[152:155], v[176:179], v[114:117]
	v_mfma_f32_16x16x32_bf16 v[114:117], v[156:159], v[180:183], v[114:117]
	v_mfma_f32_16x16x32_bf16 v[126:129], v[160:163], v[176:179], v[126:129]
	v_mfma_f32_16x16x32_bf16 v[126:129], v[164:167], v[180:183], v[126:129]
	v_mfma_f32_16x16x32_bf16 v[122:125], v[168:171], v[176:179], v[122:125]
	v_mfma_f32_16x16x32_bf16 v[122:125], v[172:175], v[180:183], v[122:125]
	v_mfma_f32_16x16x32_bf16 v[98:101], v[168:171], v[184:187], v[98:101]
	v_mfma_f32_16x16x32_bf16 v[98:101], v[172:175], v[188:191], v[98:101]
	v_mfma_f32_16x16x32_bf16 v[106:109], v[160:163], v[184:187], v[106:109]
	v_mfma_f32_16x16x32_bf16 v[106:109], v[164:167], v[188:191], v[106:109]
	v_mfma_f32_16x16x32_bf16 v[102:105], v[152:155], v[184:187], v[102:105]
	v_mfma_f32_16x16x32_bf16 v[102:105], v[156:159], v[188:191], v[102:105]
	v_mfma_f32_16x16x32_bf16 v[110:113], v[144:147], v[184:187], v[110:113]
	v_mfma_f32_16x16x32_bf16 v[110:113], v[148:151], v[188:191], v[110:113]
	v_mfma_f32_16x16x32_bf16 v[94:97], v[144:147], v[192:195], v[94:97]
	v_mfma_f32_16x16x32_bf16 v[94:97], v[148:151], v[196:199], v[94:97]
	v_mfma_f32_16x16x32_bf16 v[86:89], v[152:155], v[192:195], v[86:89]
	v_mfma_f32_16x16x32_bf16 v[86:89], v[156:159], v[196:199], v[86:89]
	v_mfma_f32_16x16x32_bf16 v[90:93], v[160:163], v[192:195], v[90:93]
	v_mfma_f32_16x16x32_bf16 v[90:93], v[164:167], v[196:199], v[90:93]
	v_mfma_f32_16x16x32_bf16 v[82:85], v[168:171], v[192:195], v[82:85]
	v_mfma_f32_16x16x32_bf16 v[82:85], v[172:175], v[196:199], v[82:85]
	v_mfma_f32_16x16x32_bf16 v[70:73], v[168:171], v[200:203], v[70:73]
	v_mfma_f32_16x16x32_bf16 v[70:73], v[172:175], v[204:207], v[70:73]
	v_mfma_f32_16x16x32_bf16 v[74:77], v[160:163], v[200:203], v[74:77]
	v_mfma_f32_16x16x32_bf16 v[74:77], v[164:167], v[204:207], v[74:77]
	v_mfma_f32_16x16x32_bf16 v[66:69], v[152:155], v[200:203], v[66:69]
	v_mfma_f32_16x16x32_bf16 v[66:69], v[156:159], v[204:207], v[66:69]
	v_mfma_f32_16x16x32_bf16 v[78:81], v[144:147], v[200:203], v[78:81]
	v_mfma_f32_16x16x32_bf16 v[78:81], v[148:151], v[204:207], v[78:81]
	s_setprio 0
	s_barrier
	s_mov_b32 m0, s45
	s_mov_b32 s14, s18
	s_mov_b32 s15, s19
	buffer_load_dwordx4 v137, s[12:15], s79 offen lds
	s_add_i32 s80, s79, 0x80000
	s_mov_b32 m0, s46
	s_nop 0
	buffer_load_dwordx4 v137, s[12:15], s80 offen lds
	s_add_i32 s80, s79, 0x100000
	s_mov_b32 m0, s47
	s_nop 0
	buffer_load_dwordx4 v137, s[12:15], s80 offen lds
	s_add_i32 s80, s79, 0x180000
	s_mov_b32 m0, s48
	s_nop 0
	buffer_load_dwordx4 v137, s[12:15], s80 offen lds
	s_mov_b32 m0, s44
	s_add_i32 s80, s77, 0x80000
	buffer_load_dwordx4 v136, s[16:19], s77 offen lds
	s_mov_b32 m0, s49
	s_nop 0
	buffer_load_dwordx4 v136, s[16:19], s80 offen lds
	ds_read_b128 v[176:179], v140 offset:16384
	ds_read_b128 v[180:183], v140 offset:17408
	ds_read_b128 v[184:187], v140 offset:18432
	ds_read_b128 v[188:191], v140 offset:19456
	ds_read_b128 v[192:195], v140 offset:20480
	ds_read_b128 v[196:199], v140 offset:21504
	ds_read_b128 v[200:203], v140 offset:22528
	ds_read_b128 v[204:207], v140 offset:23552
	s_waitcnt vmcnt(8)
	s_waitcnt lgkmcnt(0)
	s_setprio 1
	v_mfma_f32_16x16x32_bf16 v[62:65], v[144:147], v[176:179], v[62:65]
	s_barrier
	v_mfma_f32_16x16x32_bf16 v[62:65], v[148:151], v[180:183], v[62:65]
	v_mfma_f32_16x16x32_bf16 v[54:57], v[152:155], v[176:179], v[54:57]
	v_mfma_f32_16x16x32_bf16 v[54:57], v[156:159], v[180:183], v[54:57]
	v_mfma_f32_16x16x32_bf16 v[58:61], v[160:163], v[176:179], v[58:61]
	v_mfma_f32_16x16x32_bf16 v[58:61], v[164:167], v[180:183], v[58:61]
	v_mfma_f32_16x16x32_bf16 v[50:53], v[168:171], v[176:179], v[50:53]
	v_mfma_f32_16x16x32_bf16 v[50:53], v[172:175], v[180:183], v[50:53]
	v_mfma_f32_16x16x32_bf16 v[34:37], v[168:171], v[184:187], v[34:37]
	v_mfma_f32_16x16x32_bf16 v[34:37], v[172:175], v[188:191], v[34:37]
	v_mfma_f32_16x16x32_bf16 v[42:45], v[160:163], v[184:187], v[42:45]
	v_mfma_f32_16x16x32_bf16 v[42:45], v[164:167], v[188:191], v[42:45]
	v_mfma_f32_16x16x32_bf16 v[38:41], v[152:155], v[184:187], v[38:41]
	v_mfma_f32_16x16x32_bf16 v[38:41], v[156:159], v[188:191], v[38:41]
	v_mfma_f32_16x16x32_bf16 v[46:49], v[144:147], v[184:187], v[46:49]
	v_mfma_f32_16x16x32_bf16 v[46:49], v[148:151], v[188:191], v[46:49]
	v_mfma_f32_16x16x32_bf16 v[30:33], v[144:147], v[192:195], v[30:33]
	v_mfma_f32_16x16x32_bf16 v[30:33], v[148:151], v[196:199], v[30:33]
	v_mfma_f32_16x16x32_bf16 v[22:25], v[152:155], v[192:195], v[22:25]
	v_mfma_f32_16x16x32_bf16 v[22:25], v[156:159], v[196:199], v[22:25]
	v_mfma_f32_16x16x32_bf16 v[26:29], v[160:163], v[192:195], v[26:29]
	v_mfma_f32_16x16x32_bf16 v[26:29], v[164:167], v[196:199], v[26:29]
	v_mfma_f32_16x16x32_bf16 v[18:21], v[168:171], v[192:195], v[18:21]
	v_mfma_f32_16x16x32_bf16 v[18:21], v[172:175], v[196:199], v[18:21]
	v_mfma_f32_16x16x32_bf16 v[2:5], v[168:171], v[200:203], v[2:5]
	v_mfma_f32_16x16x32_bf16 v[2:5], v[172:175], v[204:207], v[2:5]
	v_mfma_f32_16x16x32_bf16 v[10:13], v[160:163], v[200:203], v[10:13]
	v_mfma_f32_16x16x32_bf16 v[10:13], v[164:167], v[204:207], v[10:13]
	v_mfma_f32_16x16x32_bf16 v[6:9], v[152:155], v[200:203], v[6:9]
	v_mfma_f32_16x16x32_bf16 v[6:9], v[156:159], v[204:207], v[6:9]
	v_mfma_f32_16x16x32_bf16 v[14:17], v[144:147], v[200:203], v[14:17]
	v_mfma_f32_16x16x32_bf16 v[14:17], v[148:151], v[204:207], v[14:17]
	s_setprio 0
	s_barrier
	s_mov_b32 m0, s50
	s_add_i32 s80, s77, 0x100000
	buffer_load_dwordx4 v136, s[16:19], s80 offen lds
	s_add_i32 s80, s77, 0x180000
	s_mov_b32 m0, s51
	s_nop 0
	buffer_load_dwordx4 v136, s[16:19], s80 offen lds
	ds_read_b128 v[144:147], v141
	ds_read_b128 v[148:151], v141 offset:1024
	ds_read_b128 v[152:155], v141 offset:2048
	ds_read_b128 v[156:159], v141 offset:3072
	ds_read_b128 v[160:163], v142
	ds_read_b128 v[164:167], v142 offset:1024
	ds_read_b128 v[168:171], v142 offset:2048
	ds_read_b128 v[172:175], v142 offset:3072
	ds_read_b128 v[176:179], v140 offset:32768
	ds_read_b128 v[180:183], v140 offset:33792
	ds_read_b128 v[184:187], v140 offset:34816
	ds_read_b128 v[188:191], v140 offset:35840
	ds_read_b128 v[192:195], v140 offset:36864
	ds_read_b128 v[196:199], v140 offset:37888
	ds_read_b128 v[200:203], v140 offset:38912
	ds_read_b128 v[204:207], v140 offset:39936
	s_waitcnt vmcnt(8)
	s_waitcnt lgkmcnt(0)
	s_setprio 1
	v_mfma_f32_16x16x32_bf16 v[118:121], v[144:147], v[176:179], v[118:121]
	s_barrier
	v_mfma_f32_16x16x32_bf16 v[118:121], v[148:151], v[180:183], v[118:121]
	v_mfma_f32_16x16x32_bf16 v[114:117], v[152:155], v[176:179], v[114:117]
	v_mfma_f32_16x16x32_bf16 v[114:117], v[156:159], v[180:183], v[114:117]
	v_mfma_f32_16x16x32_bf16 v[126:129], v[160:163], v[176:179], v[126:129]
	v_mfma_f32_16x16x32_bf16 v[126:129], v[164:167], v[180:183], v[126:129]
	v_mfma_f32_16x16x32_bf16 v[122:125], v[168:171], v[176:179], v[122:125]
	v_mfma_f32_16x16x32_bf16 v[122:125], v[172:175], v[180:183], v[122:125]
	v_mfma_f32_16x16x32_bf16 v[98:101], v[168:171], v[184:187], v[98:101]
	v_mfma_f32_16x16x32_bf16 v[98:101], v[172:175], v[188:191], v[98:101]
	v_mfma_f32_16x16x32_bf16 v[106:109], v[160:163], v[184:187], v[106:109]
	v_mfma_f32_16x16x32_bf16 v[106:109], v[164:167], v[188:191], v[106:109]
	v_mfma_f32_16x16x32_bf16 v[102:105], v[152:155], v[184:187], v[102:105]
	v_mfma_f32_16x16x32_bf16 v[102:105], v[156:159], v[188:191], v[102:105]
	v_mfma_f32_16x16x32_bf16 v[110:113], v[144:147], v[184:187], v[110:113]
	v_mfma_f32_16x16x32_bf16 v[110:113], v[148:151], v[188:191], v[110:113]
	v_mfma_f32_16x16x32_bf16 v[94:97], v[144:147], v[192:195], v[94:97]
	v_mfma_f32_16x16x32_bf16 v[94:97], v[148:151], v[196:199], v[94:97]
	v_mfma_f32_16x16x32_bf16 v[86:89], v[152:155], v[192:195], v[86:89]
	v_mfma_f32_16x16x32_bf16 v[86:89], v[156:159], v[196:199], v[86:89]
	v_mfma_f32_16x16x32_bf16 v[90:93], v[160:163], v[192:195], v[90:93]
	v_mfma_f32_16x16x32_bf16 v[90:93], v[164:167], v[196:199], v[90:93]
	v_mfma_f32_16x16x32_bf16 v[82:85], v[168:171], v[192:195], v[82:85]
	v_mfma_f32_16x16x32_bf16 v[82:85], v[172:175], v[196:199], v[82:85]
	v_mfma_f32_16x16x32_bf16 v[70:73], v[168:171], v[200:203], v[70:73]
	v_mfma_f32_16x16x32_bf16 v[70:73], v[172:175], v[204:207], v[70:73]
	v_mfma_f32_16x16x32_bf16 v[74:77], v[160:163], v[200:203], v[74:77]
	v_mfma_f32_16x16x32_bf16 v[74:77], v[164:167], v[204:207], v[74:77]
	v_mfma_f32_16x16x32_bf16 v[66:69], v[152:155], v[200:203], v[66:69]
	v_mfma_f32_16x16x32_bf16 v[66:69], v[156:159], v[204:207], v[66:69]
	v_mfma_f32_16x16x32_bf16 v[78:81], v[144:147], v[200:203], v[78:81]
	v_mfma_f32_16x16x32_bf16 v[78:81], v[148:151], v[204:207], v[78:81]
	s_setprio 0
	s_barrier
	s_mov_b32 m0, s53
	s_or_b32 s80, s79, 0x80
	buffer_load_dwordx4 v137, s[12:15], s80 offen lds
	s_add_i32 s80, s79, 0x80080
	s_mov_b32 m0, s54
	s_add_i32 s77, s77, 0x80080
	buffer_load_dwordx4 v137, s[12:15], s80 offen lds
	s_add_i32 s80, s79, 0x100080
	s_mov_b32 m0, s57
	s_add_i32 s79, s79, 0x180080
	buffer_load_dwordx4 v137, s[12:15], s80 offen lds
	s_mov_b32 m0, s58
	s_nop 0
	buffer_load_dwordx4 v137, s[12:15], s79 offen lds
	s_mov_b32 m0, s55
	s_nop 0
	buffer_load_dwordx4 v136, s[16:19], s78 offen lds
	s_mov_b32 m0, s56
	s_nop 0
	buffer_load_dwordx4 v136, s[16:19], s77 offen lds
	ds_read_b128 v[176:179], v140 offset:49152
	ds_read_b128 v[180:183], v140 offset:50176
	ds_read_b128 v[184:187], v140 offset:51200
	ds_read_b128 v[188:191], v140 offset:52224
	ds_read_b128 v[192:195], v140 offset:53248
	ds_read_b128 v[196:199], v140 offset:54272
	ds_read_b128 v[200:203], v140 offset:55296
	ds_read_b128 v[204:207], v140 offset:56320
	s_waitcnt vmcnt(8)
	s_waitcnt lgkmcnt(0)
	s_setprio 1
	v_mfma_f32_16x16x32_bf16 v[62:65], v[144:147], v[176:179], v[62:65]
	s_barrier
	v_mfma_f32_16x16x32_bf16 v[62:65], v[148:151], v[180:183], v[62:65]
	v_mfma_f32_16x16x32_bf16 v[54:57], v[152:155], v[176:179], v[54:57]
	v_mfma_f32_16x16x32_bf16 v[54:57], v[156:159], v[180:183], v[54:57]
	v_mfma_f32_16x16x32_bf16 v[58:61], v[160:163], v[176:179], v[58:61]
	v_mfma_f32_16x16x32_bf16 v[58:61], v[164:167], v[180:183], v[58:61]
	v_mfma_f32_16x16x32_bf16 v[50:53], v[168:171], v[176:179], v[50:53]
	v_mfma_f32_16x16x32_bf16 v[50:53], v[172:175], v[180:183], v[50:53]
	v_mfma_f32_16x16x32_bf16 v[34:37], v[168:171], v[184:187], v[34:37]
	v_mfma_f32_16x16x32_bf16 v[34:37], v[172:175], v[188:191], v[34:37]
	v_mfma_f32_16x16x32_bf16 v[42:45], v[160:163], v[184:187], v[42:45]
	v_mfma_f32_16x16x32_bf16 v[42:45], v[164:167], v[188:191], v[42:45]
	v_mfma_f32_16x16x32_bf16 v[38:41], v[152:155], v[184:187], v[38:41]
	v_mfma_f32_16x16x32_bf16 v[38:41], v[156:159], v[188:191], v[38:41]
	v_mfma_f32_16x16x32_bf16 v[46:49], v[144:147], v[184:187], v[46:49]
	v_mfma_f32_16x16x32_bf16 v[46:49], v[148:151], v[188:191], v[46:49]
	v_mfma_f32_16x16x32_bf16 v[30:33], v[144:147], v[192:195], v[30:33]
	v_mfma_f32_16x16x32_bf16 v[30:33], v[148:151], v[196:199], v[30:33]
	v_mfma_f32_16x16x32_bf16 v[22:25], v[152:155], v[192:195], v[22:25]
	v_mfma_f32_16x16x32_bf16 v[22:25], v[156:159], v[196:199], v[22:25]
	v_mfma_f32_16x16x32_bf16 v[26:29], v[160:163], v[192:195], v[26:29]
	v_mfma_f32_16x16x32_bf16 v[26:29], v[164:167], v[196:199], v[26:29]
	v_mfma_f32_16x16x32_bf16 v[18:21], v[168:171], v[192:195], v[18:21]
	v_mfma_f32_16x16x32_bf16 v[18:21], v[172:175], v[196:199], v[18:21]
	v_mfma_f32_16x16x32_bf16 v[2:5], v[168:171], v[200:203], v[2:5]
	v_mfma_f32_16x16x32_bf16 v[2:5], v[172:175], v[204:207], v[2:5]
	v_mfma_f32_16x16x32_bf16 v[10:13], v[160:163], v[200:203], v[10:13]
	v_mfma_f32_16x16x32_bf16 v[10:13], v[164:167], v[204:207], v[10:13]
	v_mfma_f32_16x16x32_bf16 v[6:9], v[152:155], v[200:203], v[6:9]
	v_mfma_f32_16x16x32_bf16 v[6:9], v[156:159], v[204:207], v[6:9]
	v_mfma_f32_16x16x32_bf16 v[14:17], v[144:147], v[200:203], v[14:17]
	v_mfma_f32_16x16x32_bf16 v[14:17], v[148:151], v[204:207], v[14:17]
	s_setprio 0
	s_barrier
	s_add_i32 s76, s76, 2
	s_addk_i32 s74, 0x100
	s_addk_i32 s75, 0x100
	s_cmp_ge_i32 s76, s27
	s_cbranch_scc0 .LBB0_1382
	s_and_b64 vcc, exec, s[42:43]
	s_cbranch_vccz .LBB0_1385

.LBB0_1402:
	s_add_i32 s22, s75, 0xffe80080
	s_cmp_eq_u32 s62, s77
	s_cselect_b32 s78, s73, s22
	s_cselect_b32 s80, s74, s76
	s_or_b32 s79, s78, 0x80
	s_add_i32 s22, s75, 0xfff80000
	s_mov_b32 m0, s63
	s_nop 0
	buffer_load_dwordx4 v136, s[16:19], s22 offen lds
	s_mov_b32 m0, s64
	s_nop 0
	buffer_load_dwordx4 v136, s[16:19], s75 offen lds
	ds_read_b128 v[146:149], v138
	ds_read_b128 v[150:153], v138 offset:1024
	ds_read_b128 v[154:157], v138 offset:2048
	ds_read_b128 v[158:161], v138 offset:3072
	ds_read_b128 v[162:165], v139
	ds_read_b128 v[166:169], v139 offset:1024
	ds_read_b128 v[170:173], v139 offset:2048
	ds_read_b128 v[174:177], v139 offset:3072
	ds_read_b128 v[178:181], v140
	ds_read_b128 v[182:185], v140 offset:1024
	ds_read_b128 v[186:189], v140 offset:2048
	ds_read_b128 v[190:193], v140 offset:3072
	ds_read_b128 v[194:197], v140 offset:4096
	ds_read_b128 v[198:201], v140 offset:5120
	ds_read_b128 v[202:205], v140 offset:6144
	ds_read_b128 v[206:209], v140 offset:7168
	s_waitcnt vmcnt(8)
	s_waitcnt lgkmcnt(0)
	s_setprio 1
	v_mfma_f32_16x16x32_bf16 v[118:121], v[146:149], v[178:181], v[118:121]
	s_barrier
	v_mfma_f32_16x16x32_bf16 v[118:121], v[150:153], v[182:185], v[118:121]
	v_mfma_f32_16x16x32_bf16 v[114:117], v[154:157], v[178:181], v[114:117]
	v_mfma_f32_16x16x32_bf16 v[114:117], v[158:161], v[182:185], v[114:117]
	v_mfma_f32_16x16x32_bf16 v[126:129], v[162:165], v[178:181], v[126:129]
	v_mfma_f32_16x16x32_bf16 v[126:129], v[166:169], v[182:185], v[126:129]
	v_mfma_f32_16x16x32_bf16 v[122:125], v[170:173], v[178:181], v[122:125]
	v_mfma_f32_16x16x32_bf16 v[122:125], v[174:177], v[182:185], v[122:125]
	v_mfma_f32_16x16x32_bf16 v[98:101], v[170:173], v[186:189], v[98:101]
	v_mfma_f32_16x16x32_bf16 v[98:101], v[174:177], v[190:193], v[98:101]
	v_mfma_f32_16x16x32_bf16 v[106:109], v[162:165], v[186:189], v[106:109]
	v_mfma_f32_16x16x32_bf16 v[106:109], v[166:169], v[190:193], v[106:109]
	v_mfma_f32_16x16x32_bf16 v[102:105], v[154:157], v[186:189], v[102:105]
	v_mfma_f32_16x16x32_bf16 v[102:105], v[158:161], v[190:193], v[102:105]
	v_mfma_f32_16x16x32_bf16 v[110:113], v[146:149], v[186:189], v[110:113]
	v_mfma_f32_16x16x32_bf16 v[110:113], v[150:153], v[190:193], v[110:113]
	v_mfma_f32_16x16x32_bf16 v[94:97], v[146:149], v[194:197], v[94:97]
	v_mfma_f32_16x16x32_bf16 v[94:97], v[150:153], v[198:201], v[94:97]
	v_mfma_f32_16x16x32_bf16 v[86:89], v[154:157], v[194:197], v[86:89]
	v_mfma_f32_16x16x32_bf16 v[86:89], v[158:161], v[198:201], v[86:89]
	v_mfma_f32_16x16x32_bf16 v[90:93], v[162:165], v[194:197], v[90:93]
	v_mfma_f32_16x16x32_bf16 v[90:93], v[166:169], v[198:201], v[90:93]
	v_mfma_f32_16x16x32_bf16 v[82:85], v[170:173], v[194:197], v[82:85]
	v_mfma_f32_16x16x32_bf16 v[82:85], v[174:177], v[198:201], v[82:85]
	v_mfma_f32_16x16x32_bf16 v[70:73], v[170:173], v[202:205], v[70:73]
	v_mfma_f32_16x16x32_bf16 v[70:73], v[174:177], v[206:209], v[70:73]
	v_mfma_f32_16x16x32_bf16 v[74:77], v[162:165], v[202:205], v[74:77]
	v_mfma_f32_16x16x32_bf16 v[74:77], v[166:169], v[206:209], v[74:77]
	v_mfma_f32_16x16x32_bf16 v[66:69], v[154:157], v[202:205], v[66:69]
	v_mfma_f32_16x16x32_bf16 v[66:69], v[158:161], v[206:209], v[66:69]
	v_mfma_f32_16x16x32_bf16 v[78:81], v[146:149], v[202:205], v[78:81]
	v_mfma_f32_16x16x32_bf16 v[78:81], v[150:153], v[206:209], v[78:81]
	s_setprio 0
	s_barrier
	s_mov_b32 m0, s31
	s_mov_b32 s22, s18
	s_mov_b32 s23, s19
	buffer_load_dwordx4 v137, s[20:23], s80 offen lds
	s_add_i32 s81, s80, 0x80000
	s_mov_b32 m0, s48
	s_nop 0
	buffer_load_dwordx4 v137, s[20:23], s81 offen lds
	s_add_i32 s81, s80, 0x100000
	s_mov_b32 m0, s49
	s_nop 0
	buffer_load_dwordx4 v137, s[20:23], s81 offen lds
	s_add_i32 s81, s80, 0x180000
	s_mov_b32 m0, s50
	s_nop 0
	buffer_load_dwordx4 v137, s[20:23], s81 offen lds
	s_mov_b32 m0, s30
	s_add_i32 s81, s78, 0x80000
	buffer_load_dwordx4 v136, s[16:19], s78 offen lds
	s_mov_b32 m0, s51
	s_nop 0
	buffer_load_dwordx4 v136, s[16:19], s81 offen lds
	ds_read_b128 v[178:181], v140 offset:16384
	ds_read_b128 v[182:185], v140 offset:17408
	ds_read_b128 v[186:189], v140 offset:18432
	ds_read_b128 v[190:193], v140 offset:19456
	ds_read_b128 v[194:197], v140 offset:20480
	ds_read_b128 v[198:201], v140 offset:21504
	ds_read_b128 v[202:205], v140 offset:22528
	ds_read_b128 v[206:209], v140 offset:23552
	s_waitcnt vmcnt(8)
	s_waitcnt lgkmcnt(0)
	s_setprio 1
	v_mfma_f32_16x16x32_bf16 v[62:65], v[146:149], v[178:181], v[62:65]
	s_barrier
	v_mfma_f32_16x16x32_bf16 v[62:65], v[150:153], v[182:185], v[62:65]
	v_mfma_f32_16x16x32_bf16 v[54:57], v[154:157], v[178:181], v[54:57]
	v_mfma_f32_16x16x32_bf16 v[54:57], v[158:161], v[182:185], v[54:57]
	v_mfma_f32_16x16x32_bf16 v[58:61], v[162:165], v[178:181], v[58:61]
	v_mfma_f32_16x16x32_bf16 v[58:61], v[166:169], v[182:185], v[58:61]
	v_mfma_f32_16x16x32_bf16 v[50:53], v[170:173], v[178:181], v[50:53]
	v_mfma_f32_16x16x32_bf16 v[50:53], v[174:177], v[182:185], v[50:53]
	v_mfma_f32_16x16x32_bf16 v[34:37], v[170:173], v[186:189], v[34:37]
	v_mfma_f32_16x16x32_bf16 v[34:37], v[174:177], v[190:193], v[34:37]
	v_mfma_f32_16x16x32_bf16 v[42:45], v[162:165], v[186:189], v[42:45]
	v_mfma_f32_16x16x32_bf16 v[42:45], v[166:169], v[190:193], v[42:45]
	v_mfma_f32_16x16x32_bf16 v[38:41], v[154:157], v[186:189], v[38:41]
	v_mfma_f32_16x16x32_bf16 v[38:41], v[158:161], v[190:193], v[38:41]
	v_mfma_f32_16x16x32_bf16 v[46:49], v[146:149], v[186:189], v[46:49]
	v_mfma_f32_16x16x32_bf16 v[46:49], v[150:153], v[190:193], v[46:49]
	v_mfma_f32_16x16x32_bf16 v[30:33], v[146:149], v[194:197], v[30:33]
	v_mfma_f32_16x16x32_bf16 v[30:33], v[150:153], v[198:201], v[30:33]
	v_mfma_f32_16x16x32_bf16 v[22:25], v[154:157], v[194:197], v[22:25]
	v_mfma_f32_16x16x32_bf16 v[22:25], v[158:161], v[198:201], v[22:25]
	v_mfma_f32_16x16x32_bf16 v[26:29], v[162:165], v[194:197], v[26:29]
	v_mfma_f32_16x16x32_bf16 v[26:29], v[166:169], v[198:201], v[26:29]
	v_mfma_f32_16x16x32_bf16 v[18:21], v[170:173], v[194:197], v[18:21]
	v_mfma_f32_16x16x32_bf16 v[18:21], v[174:177], v[198:201], v[18:21]
	v_mfma_f32_16x16x32_bf16 v[2:5], v[170:173], v[202:205], v[2:5]
	v_mfma_f32_16x16x32_bf16 v[2:5], v[174:177], v[206:209], v[2:5]
	v_mfma_f32_16x16x32_bf16 v[10:13], v[162:165], v[202:205], v[10:13]
	v_mfma_f32_16x16x32_bf16 v[10:13], v[166:169], v[206:209], v[10:13]
	v_mfma_f32_16x16x32_bf16 v[6:9], v[154:157], v[202:205], v[6:9]
	v_mfma_f32_16x16x32_bf16 v[6:9], v[158:161], v[206:209], v[6:9]
	v_mfma_f32_16x16x32_bf16 v[14:17], v[146:149], v[202:205], v[14:17]
	v_mfma_f32_16x16x32_bf16 v[14:17], v[150:153], v[206:209], v[14:17]
	s_setprio 0
	s_barrier
	s_mov_b32 m0, s52
	s_add_i32 s81, s78, 0x100000
	buffer_load_dwordx4 v136, s[16:19], s81 offen lds
	s_add_i32 s81, s78, 0x180000
	s_mov_b32 m0, s53
	s_nop 0
	buffer_load_dwordx4 v136, s[16:19], s81 offen lds
	ds_read_b128 v[146:149], v141
	ds_read_b128 v[150:153], v141 offset:1024
	ds_read_b128 v[154:157], v141 offset:2048
	ds_read_b128 v[158:161], v141 offset:3072
	ds_read_b128 v[162:165], v142
	ds_read_b128 v[166:169], v142 offset:1024
	ds_read_b128 v[170:173], v142 offset:2048
	ds_read_b128 v[174:177], v142 offset:3072
	ds_read_b128 v[178:181], v140 offset:32768
	ds_read_b128 v[182:185], v140 offset:33792
	ds_read_b128 v[186:189], v140 offset:34816
	ds_read_b128 v[190:193], v140 offset:35840
	ds_read_b128 v[194:197], v140 offset:36864
	ds_read_b128 v[198:201], v140 offset:37888
	ds_read_b128 v[202:205], v140 offset:38912
	ds_read_b128 v[206:209], v140 offset:39936
	s_waitcnt vmcnt(8)
	s_waitcnt lgkmcnt(0)
	s_setprio 1
	v_mfma_f32_16x16x32_bf16 v[118:121], v[146:149], v[178:181], v[118:121]
	s_barrier
	v_mfma_f32_16x16x32_bf16 v[118:121], v[150:153], v[182:185], v[118:121]
	v_mfma_f32_16x16x32_bf16 v[114:117], v[154:157], v[178:181], v[114:117]
	v_mfma_f32_16x16x32_bf16 v[114:117], v[158:161], v[182:185], v[114:117]
	v_mfma_f32_16x16x32_bf16 v[126:129], v[162:165], v[178:181], v[126:129]
	v_mfma_f32_16x16x32_bf16 v[126:129], v[166:169], v[182:185], v[126:129]
	v_mfma_f32_16x16x32_bf16 v[122:125], v[170:173], v[178:181], v[122:125]
	v_mfma_f32_16x16x32_bf16 v[122:125], v[174:177], v[182:185], v[122:125]
	v_mfma_f32_16x16x32_bf16 v[98:101], v[170:173], v[186:189], v[98:101]
	v_mfma_f32_16x16x32_bf16 v[98:101], v[174:177], v[190:193], v[98:101]
	v_mfma_f32_16x16x32_bf16 v[106:109], v[162:165], v[186:189], v[106:109]
	v_mfma_f32_16x16x32_bf16 v[106:109], v[166:169], v[190:193], v[106:109]
	v_mfma_f32_16x16x32_bf16 v[102:105], v[154:157], v[186:189], v[102:105]
	v_mfma_f32_16x16x32_bf16 v[102:105], v[158:161], v[190:193], v[102:105]
	v_mfma_f32_16x16x32_bf16 v[110:113], v[146:149], v[186:189], v[110:113]
	v_mfma_f32_16x16x32_bf16 v[110:113], v[150:153], v[190:193], v[110:113]
	v_mfma_f32_16x16x32_bf16 v[94:97], v[146:149], v[194:197], v[94:97]
	v_mfma_f32_16x16x32_bf16 v[94:97], v[150:153], v[198:201], v[94:97]
	v_mfma_f32_16x16x32_bf16 v[86:89], v[154:157], v[194:197], v[86:89]
	v_mfma_f32_16x16x32_bf16 v[86:89], v[158:161], v[198:201], v[86:89]
	v_mfma_f32_16x16x32_bf16 v[90:93], v[162:165], v[194:197], v[90:93]
	v_mfma_f32_16x16x32_bf16 v[90:93], v[166:169], v[198:201], v[90:93]
	v_mfma_f32_16x16x32_bf16 v[82:85], v[170:173], v[194:197], v[82:85]
	v_mfma_f32_16x16x32_bf16 v[82:85], v[174:177], v[198:201], v[82:85]
	v_mfma_f32_16x16x32_bf16 v[70:73], v[170:173], v[202:205], v[70:73]
	v_mfma_f32_16x16x32_bf16 v[70:73], v[174:177], v[206:209], v[70:73]
	v_mfma_f32_16x16x32_bf16 v[74:77], v[162:165], v[202:205], v[74:77]
	v_mfma_f32_16x16x32_bf16 v[74:77], v[166:169], v[206:209], v[74:77]
	v_mfma_f32_16x16x32_bf16 v[66:69], v[154:157], v[202:205], v[66:69]
	v_mfma_f32_16x16x32_bf16 v[66:69], v[158:161], v[206:209], v[66:69]
	v_mfma_f32_16x16x32_bf16 v[78:81], v[146:149], v[202:205], v[78:81]
	v_mfma_f32_16x16x32_bf16 v[78:81], v[150:153], v[206:209], v[78:81]
	s_setprio 0
	s_barrier
	s_mov_b32 m0, s54
	s_or_b32 s81, s80, 0x80
	buffer_load_dwordx4 v137, s[20:23], s81 offen lds
	s_add_i32 s81, s80, 0x80080
	s_mov_b32 m0, s55
	s_add_i32 s78, s78, 0x80080
	buffer_load_dwordx4 v137, s[20:23], s81 offen lds
	s_add_i32 s81, s80, 0x100080
	s_mov_b32 m0, s58
	s_add_i32 s80, s80, 0x180080
	buffer_load_dwordx4 v137, s[20:23], s81 offen lds
	s_mov_b32 m0, s59
	s_nop 0
	buffer_load_dwordx4 v137, s[20:23], s80 offen lds
	s_mov_b32 m0, s56
	s_nop 0
	buffer_load_dwordx4 v136, s[16:19], s79 offen lds
	s_mov_b32 m0, s57
	s_nop 0
	buffer_load_dwordx4 v136, s[16:19], s78 offen lds
	ds_read_b128 v[178:181], v140 offset:49152
	ds_read_b128 v[182:185], v140 offset:50176
	ds_read_b128 v[186:189], v140 offset:51200
	ds_read_b128 v[190:193], v140 offset:52224
	ds_read_b128 v[194:197], v140 offset:53248
	ds_read_b128 v[198:201], v140 offset:54272
	ds_read_b128 v[202:205], v140 offset:55296
	ds_read_b128 v[206:209], v140 offset:56320
	s_waitcnt vmcnt(8)
	s_waitcnt lgkmcnt(0)
	s_setprio 1
	v_mfma_f32_16x16x32_bf16 v[62:65], v[146:149], v[178:181], v[62:65]
	s_barrier
	v_mfma_f32_16x16x32_bf16 v[62:65], v[150:153], v[182:185], v[62:65]
	v_mfma_f32_16x16x32_bf16 v[54:57], v[154:157], v[178:181], v[54:57]
	v_mfma_f32_16x16x32_bf16 v[54:57], v[158:161], v[182:185], v[54:57]
	v_mfma_f32_16x16x32_bf16 v[58:61], v[162:165], v[178:181], v[58:61]
	v_mfma_f32_16x16x32_bf16 v[58:61], v[166:169], v[182:185], v[58:61]
	v_mfma_f32_16x16x32_bf16 v[50:53], v[170:173], v[178:181], v[50:53]
	v_mfma_f32_16x16x32_bf16 v[50:53], v[174:177], v[182:185], v[50:53]
	v_mfma_f32_16x16x32_bf16 v[34:37], v[170:173], v[186:189], v[34:37]
	v_mfma_f32_16x16x32_bf16 v[34:37], v[174:177], v[190:193], v[34:37]
	v_mfma_f32_16x16x32_bf16 v[42:45], v[162:165], v[186:189], v[42:45]
	v_mfma_f32_16x16x32_bf16 v[42:45], v[166:169], v[190:193], v[42:45]
	v_mfma_f32_16x16x32_bf16 v[38:41], v[154:157], v[186:189], v[38:41]
	v_mfma_f32_16x16x32_bf16 v[38:41], v[158:161], v[190:193], v[38:41]
	v_mfma_f32_16x16x32_bf16 v[46:49], v[146:149], v[186:189], v[46:49]
	v_mfma_f32_16x16x32_bf16 v[46:49], v[150:153], v[190:193], v[46:49]
	v_mfma_f32_16x16x32_bf16 v[30:33], v[146:149], v[194:197], v[30:33]
	v_mfma_f32_16x16x32_bf16 v[30:33], v[150:153], v[198:201], v[30:33]
	v_mfma_f32_16x16x32_bf16 v[22:25], v[154:157], v[194:197], v[22:25]
	v_mfma_f32_16x16x32_bf16 v[22:25], v[158:161], v[198:201], v[22:25]
	v_mfma_f32_16x16x32_bf16 v[26:29], v[162:165], v[194:197], v[26:29]
	v_mfma_f32_16x16x32_bf16 v[26:29], v[166:169], v[198:201], v[26:29]
	v_mfma_f32_16x16x32_bf16 v[18:21], v[170:173], v[194:197], v[18:21]
	v_mfma_f32_16x16x32_bf16 v[18:21], v[174:177], v[198:201], v[18:21]
	v_mfma_f32_16x16x32_bf16 v[2:5], v[170:173], v[202:205], v[2:5]
	v_mfma_f32_16x16x32_bf16 v[2:5], v[174:177], v[206:209], v[2:5]
	v_mfma_f32_16x16x32_bf16 v[10:13], v[162:165], v[202:205], v[10:13]
	v_mfma_f32_16x16x32_bf16 v[10:13], v[166:169], v[206:209], v[10:13]
	v_mfma_f32_16x16x32_bf16 v[6:9], v[154:157], v[202:205], v[6:9]
	v_mfma_f32_16x16x32_bf16 v[6:9], v[158:161], v[206:209], v[6:9]
	v_mfma_f32_16x16x32_bf16 v[14:17], v[146:149], v[202:205], v[14:17]
	v_mfma_f32_16x16x32_bf16 v[14:17], v[150:153], v[206:209], v[14:17]
	s_setprio 0
	s_barrier
	s_add_i32 s77, s77, 2
	s_addk_i32 s75, 0x100
	s_addk_i32 s76, 0x100
	s_cmp_ge_i32 s77, s13
	s_cbranch_scc0 .LBB0_1402
	s_and_b64 vcc, exec, s[46:47]
	s_cbranch_vccz .LBB0_1405

.LBB0_1519:
	s_add_i32 s18, s80, 0xffbf8080
	s_cmp_eq_u32 s65, s82
	s_cselect_b32 s83, s6, s18
	s_cselect_b32 s85, s7, s81
	s_or_b32 s84, s83, 0x80
	s_add_i32 s18, s80, 0xffea8000
	s_mov_b32 m0, s66
	s_nop 0
	buffer_load_dwordx4 v206, s[12:15], s18 offen lds
	s_mov_b32 m0, s69
	s_nop 0
	buffer_load_dwordx4 v206, s[12:15], s80 offen lds
	ds_read_b128 v[134:137], v208
	ds_read_b128 v[138:141], v208 offset:1024
	ds_read_b128 v[142:145], v208 offset:2048
	ds_read_b128 v[146:149], v208 offset:3072
	ds_read_b128 v[150:153], v209
	ds_read_b128 v[154:157], v209 offset:1024
	ds_read_b128 v[158:161], v209 offset:2048
	ds_read_b128 v[162:165], v209 offset:3072
	ds_read_b128 v[166:169], v210
	ds_read_b128 v[170:173], v210 offset:1024
	ds_read_b128 v[174:177], v210 offset:2048
	ds_read_b128 v[178:181], v210 offset:3072
	ds_read_b128 v[182:185], v210 offset:4096
	ds_read_b128 v[186:189], v210 offset:5120
	ds_read_b128 v[190:193], v210 offset:6144
	ds_read_b128 v[194:197], v210 offset:7168
	s_waitcnt vmcnt(8)
	s_waitcnt lgkmcnt(0)
	s_setprio 1
	v_mfma_f32_16x16x32_bf16 v[126:129], v[134:137], v[166:169], v[126:129]
	s_barrier
	v_mfma_f32_16x16x32_bf16 v[126:129], v[138:141], v[170:173], v[126:129]
	v_mfma_f32_16x16x32_bf16 v[122:125], v[142:145], v[166:169], v[122:125]
	v_mfma_f32_16x16x32_bf16 v[122:125], v[146:149], v[170:173], v[122:125]
	v_mfma_f32_16x16x32_bf16 v[110:113], v[150:153], v[166:169], v[110:113]
	v_mfma_f32_16x16x32_bf16 v[110:113], v[154:157], v[170:173], v[110:113]
	v_mfma_f32_16x16x32_bf16 v[102:105], v[158:161], v[166:169], v[102:105]
	v_mfma_f32_16x16x32_bf16 v[102:105], v[162:165], v[170:173], v[102:105]
	v_mfma_f32_16x16x32_bf16 v[86:89], v[158:161], v[174:177], v[86:89]
	v_mfma_f32_16x16x32_bf16 v[86:89], v[162:165], v[178:181], v[86:89]
	v_mfma_f32_16x16x32_bf16 v[94:97], v[150:153], v[174:177], v[94:97]
	v_mfma_f32_16x16x32_bf16 v[94:97], v[154:157], v[178:181], v[94:97]
	v_mfma_f32_16x16x32_bf16 v[114:117], v[142:145], v[174:177], v[114:117]
	v_mfma_f32_16x16x32_bf16 v[114:117], v[146:149], v[178:181], v[114:117]
	v_mfma_f32_16x16x32_bf16 v[118:121], v[134:137], v[174:177], v[118:121]
	v_mfma_f32_16x16x32_bf16 v[118:121], v[138:141], v[178:181], v[118:121]
	v_mfma_f32_16x16x32_bf16 v[106:109], v[134:137], v[182:185], v[106:109]
	v_mfma_f32_16x16x32_bf16 v[106:109], v[138:141], v[186:189], v[106:109]
	v_mfma_f32_16x16x32_bf16 v[98:101], v[142:145], v[182:185], v[98:101]
	v_mfma_f32_16x16x32_bf16 v[98:101], v[146:149], v[186:189], v[98:101]
	v_mfma_f32_16x16x32_bf16 v[78:81], v[150:153], v[182:185], v[78:81]
	v_mfma_f32_16x16x32_bf16 v[78:81], v[154:157], v[186:189], v[78:81]
	v_mfma_f32_16x16x32_bf16 v[74:77], v[158:161], v[182:185], v[74:77]
	v_mfma_f32_16x16x32_bf16 v[74:77], v[162:165], v[186:189], v[74:77]
	v_mfma_f32_16x16x32_bf16 v[66:69], v[158:161], v[190:193], v[66:69]
	v_mfma_f32_16x16x32_bf16 v[66:69], v[162:165], v[194:197], v[66:69]
	v_mfma_f32_16x16x32_bf16 v[70:73], v[150:153], v[190:193], v[70:73]
	v_mfma_f32_16x16x32_bf16 v[70:73], v[154:157], v[194:197], v[70:73]
	v_mfma_f32_16x16x32_bf16 v[82:85], v[142:145], v[190:193], v[82:85]
	v_mfma_f32_16x16x32_bf16 v[82:85], v[146:149], v[194:197], v[82:85]
	v_mfma_f32_16x16x32_bf16 v[90:93], v[134:137], v[190:193], v[90:93]
	v_mfma_f32_16x16x32_bf16 v[90:93], v[138:141], v[194:197], v[90:93]
	s_setprio 0
	s_barrier
	s_mov_b32 m0, s27
	s_mov_b32 s18, s14
	s_mov_b32 s19, s15
	buffer_load_dwordx4 v207, s[16:19], s85 offen lds
	s_add_i32 s86, s85, 0x158000
	s_mov_b32 m0, s30
	s_nop 0
	buffer_load_dwordx4 v207, s[16:19], s86 offen lds
	s_add_i32 s86, s85, 0x2b0000
	s_mov_b32 m0, s31
	s_nop 0
	buffer_load_dwordx4 v207, s[16:19], s86 offen lds
	s_add_i32 s86, s85, 0x408000
	s_mov_b32 m0, s50
	s_nop 0
	buffer_load_dwordx4 v207, s[16:19], s86 offen lds
	s_mov_b32 m0, s25
	s_add_i32 s86, s83, 0x158000
	buffer_load_dwordx4 v206, s[12:15], s83 offen lds
	s_mov_b32 m0, s51
	s_nop 0
	buffer_load_dwordx4 v206, s[12:15], s86 offen lds
	ds_read_b128 v[166:169], v210 offset:16384
	ds_read_b128 v[170:173], v210 offset:17408
	ds_read_b128 v[174:177], v210 offset:18432
	ds_read_b128 v[178:181], v210 offset:19456
	ds_read_b128 v[182:185], v210 offset:20480
	ds_read_b128 v[186:189], v210 offset:21504
	ds_read_b128 v[190:193], v210 offset:22528
	ds_read_b128 v[194:197], v210 offset:23552
	s_waitcnt vmcnt(8)
	s_waitcnt lgkmcnt(0)
	s_setprio 1
	v_mfma_f32_16x16x32_bf16 v[62:65], v[134:137], v[166:169], v[62:65]
	s_barrier
	v_mfma_f32_16x16x32_bf16 v[62:65], v[138:141], v[170:173], v[62:65]
	v_mfma_f32_16x16x32_bf16 v[58:61], v[142:145], v[166:169], v[58:61]
	v_mfma_f32_16x16x32_bf16 v[58:61], v[146:149], v[170:173], v[58:61]
	v_mfma_f32_16x16x32_bf16 v[46:49], v[150:153], v[166:169], v[46:49]
	v_mfma_f32_16x16x32_bf16 v[46:49], v[154:157], v[170:173], v[46:49]
	v_mfma_f32_16x16x32_bf16 v[38:41], v[158:161], v[166:169], v[38:41]
	v_mfma_f32_16x16x32_bf16 v[38:41], v[162:165], v[170:173], v[38:41]
	v_mfma_f32_16x16x32_bf16 v[22:25], v[158:161], v[174:177], v[22:25]
	v_mfma_f32_16x16x32_bf16 v[22:25], v[162:165], v[178:181], v[22:25]
	v_mfma_f32_16x16x32_bf16 v[30:33], v[150:153], v[174:177], v[30:33]
	v_mfma_f32_16x16x32_bf16 v[30:33], v[154:157], v[178:181], v[30:33]
	v_mfma_f32_16x16x32_bf16 v[50:53], v[142:145], v[174:177], v[50:53]
	v_mfma_f32_16x16x32_bf16 v[50:53], v[146:149], v[178:181], v[50:53]
	v_mfma_f32_16x16x32_bf16 v[54:57], v[134:137], v[174:177], v[54:57]
	v_mfma_f32_16x16x32_bf16 v[54:57], v[138:141], v[178:181], v[54:57]
	v_mfma_f32_16x16x32_bf16 v[42:45], v[134:137], v[182:185], v[42:45]
	v_mfma_f32_16x16x32_bf16 v[42:45], v[138:141], v[186:189], v[42:45]
	v_mfma_f32_16x16x32_bf16 v[34:37], v[142:145], v[182:185], v[34:37]
	v_mfma_f32_16x16x32_bf16 v[34:37], v[146:149], v[186:189], v[34:37]
	v_mfma_f32_16x16x32_bf16 v[14:17], v[150:153], v[182:185], v[14:17]
	v_mfma_f32_16x16x32_bf16 v[14:17], v[154:157], v[186:189], v[14:17]
	v_mfma_f32_16x16x32_bf16 v[10:13], v[158:161], v[182:185], v[10:13]
	v_mfma_f32_16x16x32_bf16 v[10:13], v[162:165], v[186:189], v[10:13]
	v_mfma_f32_16x16x32_bf16 v[2:5], v[158:161], v[190:193], v[2:5]
	v_mfma_f32_16x16x32_bf16 v[2:5], v[162:165], v[194:197], v[2:5]
	v_mfma_f32_16x16x32_bf16 v[6:9], v[150:153], v[190:193], v[6:9]
	v_mfma_f32_16x16x32_bf16 v[6:9], v[154:157], v[194:197], v[6:9]
	v_mfma_f32_16x16x32_bf16 v[18:21], v[142:145], v[190:193], v[18:21]
	v_mfma_f32_16x16x32_bf16 v[18:21], v[146:149], v[194:197], v[18:21]
	v_mfma_f32_16x16x32_bf16 v[26:29], v[134:137], v[190:193], v[26:29]
	v_mfma_f32_16x16x32_bf16 v[26:29], v[138:141], v[194:197], v[26:29]
	s_setprio 0
	s_barrier
	s_mov_b32 m0, s52
	s_add_i32 s86, s83, 0x2b0000
	buffer_load_dwordx4 v206, s[12:15], s86 offen lds
	s_add_i32 s86, s83, 0x408000
	s_mov_b32 m0, s53
	s_nop 0
	buffer_load_dwordx4 v206, s[12:15], s86 offen lds
	ds_read_b128 v[134:137], v211
	ds_read_b128 v[138:141], v211 offset:1024
	ds_read_b128 v[142:145], v211 offset:2048
	ds_read_b128 v[146:149], v211 offset:3072
	ds_read_b128 v[150:153], v212
	ds_read_b128 v[154:157], v212 offset:1024
	ds_read_b128 v[158:161], v212 offset:2048
	ds_read_b128 v[162:165], v212 offset:3072
	ds_read_b128 v[166:169], v210 offset:32768
	ds_read_b128 v[170:173], v210 offset:33792
	ds_read_b128 v[174:177], v210 offset:34816
	ds_read_b128 v[178:181], v210 offset:35840
	ds_read_b128 v[182:185], v210 offset:36864
	ds_read_b128 v[186:189], v210 offset:37888
	ds_read_b128 v[190:193], v210 offset:38912
	ds_read_b128 v[194:197], v210 offset:39936
	s_waitcnt vmcnt(8)
	s_waitcnt lgkmcnt(0)
	s_setprio 1
	v_mfma_f32_16x16x32_bf16 v[126:129], v[134:137], v[166:169], v[126:129]
	s_barrier
	v_mfma_f32_16x16x32_bf16 v[126:129], v[138:141], v[170:173], v[126:129]
	v_mfma_f32_16x16x32_bf16 v[122:125], v[142:145], v[166:169], v[122:125]
	v_mfma_f32_16x16x32_bf16 v[122:125], v[146:149], v[170:173], v[122:125]
	v_mfma_f32_16x16x32_bf16 v[110:113], v[150:153], v[166:169], v[110:113]
	v_mfma_f32_16x16x32_bf16 v[110:113], v[154:157], v[170:173], v[110:113]
	v_mfma_f32_16x16x32_bf16 v[102:105], v[158:161], v[166:169], v[102:105]
	v_mfma_f32_16x16x32_bf16 v[102:105], v[162:165], v[170:173], v[102:105]
	v_mfma_f32_16x16x32_bf16 v[86:89], v[158:161], v[174:177], v[86:89]
	v_mfma_f32_16x16x32_bf16 v[86:89], v[162:165], v[178:181], v[86:89]
	v_mfma_f32_16x16x32_bf16 v[94:97], v[150:153], v[174:177], v[94:97]
	v_mfma_f32_16x16x32_bf16 v[94:97], v[154:157], v[178:181], v[94:97]
	v_mfma_f32_16x16x32_bf16 v[114:117], v[142:145], v[174:177], v[114:117]
	v_mfma_f32_16x16x32_bf16 v[114:117], v[146:149], v[178:181], v[114:117]
	v_mfma_f32_16x16x32_bf16 v[118:121], v[134:137], v[174:177], v[118:121]
	v_mfma_f32_16x16x32_bf16 v[118:121], v[138:141], v[178:181], v[118:121]
	v_mfma_f32_16x16x32_bf16 v[106:109], v[134:137], v[182:185], v[106:109]
	v_mfma_f32_16x16x32_bf16 v[106:109], v[138:141], v[186:189], v[106:109]
	v_mfma_f32_16x16x32_bf16 v[98:101], v[142:145], v[182:185], v[98:101]
	v_mfma_f32_16x16x32_bf16 v[98:101], v[146:149], v[186:189], v[98:101]
	v_mfma_f32_16x16x32_bf16 v[78:81], v[150:153], v[182:185], v[78:81]
	v_mfma_f32_16x16x32_bf16 v[78:81], v[154:157], v[186:189], v[78:81]
	v_mfma_f32_16x16x32_bf16 v[74:77], v[158:161], v[182:185], v[74:77]
	v_mfma_f32_16x16x32_bf16 v[74:77], v[162:165], v[186:189], v[74:77]
	v_mfma_f32_16x16x32_bf16 v[66:69], v[158:161], v[190:193], v[66:69]
	v_mfma_f32_16x16x32_bf16 v[66:69], v[162:165], v[194:197], v[66:69]
	v_mfma_f32_16x16x32_bf16 v[70:73], v[150:153], v[190:193], v[70:73]
	v_mfma_f32_16x16x32_bf16 v[70:73], v[154:157], v[194:197], v[70:73]
	v_mfma_f32_16x16x32_bf16 v[82:85], v[142:145], v[190:193], v[82:85]
	v_mfma_f32_16x16x32_bf16 v[82:85], v[146:149], v[194:197], v[82:85]
	v_mfma_f32_16x16x32_bf16 v[90:93], v[134:137], v[190:193], v[90:93]
	v_mfma_f32_16x16x32_bf16 v[90:93], v[138:141], v[194:197], v[90:93]
	s_setprio 0
	s_barrier
	s_mov_b32 m0, s57
	s_or_b32 s86, s85, 0x80
	buffer_load_dwordx4 v207, s[16:19], s86 offen lds
	s_add_i32 s86, s85, 0x158080
	s_mov_b32 m0, s58
	s_add_i32 s83, s83, 0x158080
	buffer_load_dwordx4 v207, s[16:19], s86 offen lds
	s_add_i32 s86, s85, 0x2b0080
	s_mov_b32 m0, s61
	s_add_i32 s85, s85, 0x408080
	buffer_load_dwordx4 v207, s[16:19], s86 offen lds
	s_mov_b32 m0, s62
	s_nop 0
	buffer_load_dwordx4 v207, s[16:19], s85 offen lds
	s_mov_b32 m0, s59
	s_nop 0
	buffer_load_dwordx4 v206, s[12:15], s84 offen lds
	s_mov_b32 m0, s60
	s_nop 0
	buffer_load_dwordx4 v206, s[12:15], s83 offen lds
	ds_read_b128 v[166:169], v210 offset:49152
	ds_read_b128 v[170:173], v210 offset:50176
	ds_read_b128 v[174:177], v210 offset:51200
	ds_read_b128 v[178:181], v210 offset:52224
	ds_read_b128 v[182:185], v210 offset:53248
	ds_read_b128 v[186:189], v210 offset:54272
	ds_read_b128 v[190:193], v210 offset:55296
	ds_read_b128 v[194:197], v210 offset:56320
	s_waitcnt vmcnt(8)
	s_waitcnt lgkmcnt(0)
	s_setprio 1
	v_mfma_f32_16x16x32_bf16 v[62:65], v[134:137], v[166:169], v[62:65]
	s_barrier
	v_mfma_f32_16x16x32_bf16 v[62:65], v[138:141], v[170:173], v[62:65]
	v_mfma_f32_16x16x32_bf16 v[58:61], v[142:145], v[166:169], v[58:61]
	v_mfma_f32_16x16x32_bf16 v[58:61], v[146:149], v[170:173], v[58:61]
	v_mfma_f32_16x16x32_bf16 v[46:49], v[150:153], v[166:169], v[46:49]
	v_mfma_f32_16x16x32_bf16 v[46:49], v[154:157], v[170:173], v[46:49]
	v_mfma_f32_16x16x32_bf16 v[38:41], v[158:161], v[166:169], v[38:41]
	v_mfma_f32_16x16x32_bf16 v[38:41], v[162:165], v[170:173], v[38:41]
	v_mfma_f32_16x16x32_bf16 v[22:25], v[158:161], v[174:177], v[22:25]
	v_mfma_f32_16x16x32_bf16 v[22:25], v[162:165], v[178:181], v[22:25]
	v_mfma_f32_16x16x32_bf16 v[30:33], v[150:153], v[174:177], v[30:33]
	v_mfma_f32_16x16x32_bf16 v[30:33], v[154:157], v[178:181], v[30:33]
	v_mfma_f32_16x16x32_bf16 v[50:53], v[142:145], v[174:177], v[50:53]
	v_mfma_f32_16x16x32_bf16 v[50:53], v[146:149], v[178:181], v[50:53]
	v_mfma_f32_16x16x32_bf16 v[54:57], v[134:137], v[174:177], v[54:57]
	v_mfma_f32_16x16x32_bf16 v[54:57], v[138:141], v[178:181], v[54:57]
	v_mfma_f32_16x16x32_bf16 v[42:45], v[134:137], v[182:185], v[42:45]
	v_mfma_f32_16x16x32_bf16 v[42:45], v[138:141], v[186:189], v[42:45]
	v_mfma_f32_16x16x32_bf16 v[34:37], v[142:145], v[182:185], v[34:37]
	v_mfma_f32_16x16x32_bf16 v[34:37], v[146:149], v[186:189], v[34:37]
	v_mfma_f32_16x16x32_bf16 v[14:17], v[150:153], v[182:185], v[14:17]
	v_mfma_f32_16x16x32_bf16 v[14:17], v[154:157], v[186:189], v[14:17]
	v_mfma_f32_16x16x32_bf16 v[10:13], v[158:161], v[182:185], v[10:13]
	v_mfma_f32_16x16x32_bf16 v[10:13], v[162:165], v[186:189], v[10:13]
	v_mfma_f32_16x16x32_bf16 v[2:5], v[158:161], v[190:193], v[2:5]
	v_mfma_f32_16x16x32_bf16 v[2:5], v[162:165], v[194:197], v[2:5]
	v_mfma_f32_16x16x32_bf16 v[6:9], v[150:153], v[190:193], v[6:9]
	v_mfma_f32_16x16x32_bf16 v[6:9], v[154:157], v[194:197], v[6:9]
	v_mfma_f32_16x16x32_bf16 v[18:21], v[142:145], v[190:193], v[18:21]
	v_mfma_f32_16x16x32_bf16 v[18:21], v[146:149], v[194:197], v[18:21]
	v_mfma_f32_16x16x32_bf16 v[26:29], v[134:137], v[190:193], v[26:29]
	v_mfma_f32_16x16x32_bf16 v[26:29], v[138:141], v[194:197], v[26:29]
	s_setprio 0
	s_barrier
	s_add_i32 s82, s82, 2
	s_addk_i32 s80, 0x100
	s_addk_i32 s81, 0x100
	s_cmp_ge_i32 s82, s3
	s_cbranch_scc0 .LBB0_1519
	v_pk_mul_f32 v[182:183], v[128:129], 0.5 op_sel_hi:[1,0]
	v_pk_mul_f32 v[184:185], v[126:127], 0.5 op_sel_hi:[1,0]
	v_pk_mul_f32 v[186:187], v[124:125], 0.5 op_sel_hi:[1,0]
	v_pk_mul_f32 v[188:189], v[122:123], 0.5 op_sel_hi:[1,0]
	v_pk_mul_f32 v[196:197], v[112:113], 0.5 op_sel_hi:[1,0]
	v_pk_mul_f32 v[194:195], v[110:111], 0.5 op_sel_hi:[1,0]
	v_pk_mul_f32 v[192:193], v[104:105], 0.5 op_sel_hi:[1,0]
	v_pk_mul_f32 v[190:191], v[102:103], 0.5 op_sel_hi:[1,0]
	v_pk_mul_f32 v[180:181], v[120:121], 0.5 op_sel_hi:[1,0]
	v_pk_mul_f32 v[178:179], v[118:119], 0.5 op_sel_hi:[1,0]
	v_pk_mul_f32 v[176:177], v[116:117], 0.5 op_sel_hi:[1,0]
	v_pk_mul_f32 v[174:175], v[114:115], 0.5 op_sel_hi:[1,0]
	v_pk_mul_f32 v[170:171], v[96:97], 0.5 op_sel_hi:[1,0]
	v_pk_mul_f32 v[168:169], v[94:95], 0.5 op_sel_hi:[1,0]
	v_pk_mul_f32 v[166:167], v[88:89], 0.5 op_sel_hi:[1,0]
	v_pk_mul_f32 v[164:165], v[86:87], 0.5 op_sel_hi:[1,0]
	v_pk_mul_f32 v[162:163], v[108:109], 0.5 op_sel_hi:[1,0]
	v_pk_mul_f32 v[160:161], v[106:107], 0.5 op_sel_hi:[1,0]
	v_pk_mul_f32 v[158:159], v[100:101], 0.5 op_sel_hi:[1,0]
	v_pk_mul_f32 v[156:157], v[98:99], 0.5 op_sel_hi:[1,0]
	v_pk_mul_f32 v[154:155], v[80:81], 0.5 op_sel_hi:[1,0]
	v_pk_mul_f32 v[152:153], v[78:79], 0.5 op_sel_hi:[1,0]
	v_pk_mul_f32 v[150:151], v[76:77], 0.5 op_sel_hi:[1,0]
	v_pk_mul_f32 v[148:149], v[74:75], 0.5 op_sel_hi:[1,0]
	v_pk_mul_f32 v[144:145], v[92:93], 0.5 op_sel_hi:[1,0]
	v_pk_mul_f32 v[142:143], v[90:91], 0.5 op_sel_hi:[1,0]
	v_pk_mul_f32 v[140:141], v[84:85], 0.5 op_sel_hi:[1,0]
	v_pk_mul_f32 v[138:139], v[82:83], 0.5 op_sel_hi:[1,0]
	v_pk_mul_f32 v[136:137], v[72:73], 0.5 op_sel_hi:[1,0]
	v_pk_mul_f32 v[134:135], v[70:71], 0.5 op_sel_hi:[1,0]
	v_pk_mul_f32 v[128:129], v[68:69], 0.5 op_sel_hi:[1,0]
	v_pk_mul_f32 v[126:127], v[66:67], 0.5 op_sel_hi:[1,0]
	v_pk_mul_f32 v[122:123], v[64:65], 0.5 op_sel_hi:[1,0]
	v_pk_mul_f32 v[120:121], v[62:63], 0.5 op_sel_hi:[1,0]
	v_pk_mul_f32 v[118:119], v[60:61], 0.5 op_sel_hi:[1,0]
	v_pk_mul_f32 v[116:117], v[58:59], 0.5 op_sel_hi:[1,0]
	v_pk_mul_f32 v[112:113], v[48:49], 0.5 op_sel_hi:[1,0]
	v_pk_mul_f32 v[110:111], v[46:47], 0.5 op_sel_hi:[1,0]
	v_pk_mul_f32 v[108:109], v[40:41], 0.5 op_sel_hi:[1,0]
	v_pk_mul_f32 v[106:107], v[38:39], 0.5 op_sel_hi:[1,0]
	v_pk_mul_f32 v[104:105], v[56:57], 0.5 op_sel_hi:[1,0]
	v_pk_mul_f32 v[102:103], v[54:55], 0.5 op_sel_hi:[1,0]
	v_pk_mul_f32 v[100:101], v[52:53], 0.5 op_sel_hi:[1,0]
	v_pk_mul_f32 v[98:99], v[50:51], 0.5 op_sel_hi:[1,0]
	v_pk_mul_f32 v[96:97], v[32:33], 0.5 op_sel_hi:[1,0]
	v_pk_mul_f32 v[94:95], v[30:31], 0.5 op_sel_hi:[1,0]
	v_pk_mul_f32 v[92:93], v[24:25], 0.5 op_sel_hi:[1,0]
	v_pk_mul_f32 v[90:91], v[22:23], 0.5 op_sel_hi:[1,0]
	v_pk_mul_f32 v[88:89], v[44:45], 0.5 op_sel_hi:[1,0]
	v_pk_mul_f32 v[86:87], v[42:43], 0.5 op_sel_hi:[1,0]
	v_pk_mul_f32 v[84:85], v[36:37], 0.5 op_sel_hi:[1,0]
	v_pk_mul_f32 v[82:83], v[34:35], 0.5 op_sel_hi:[1,0]
	v_pk_mul_f32 v[80:81], v[16:17], 0.5 op_sel_hi:[1,0]
	v_pk_mul_f32 v[78:79], v[14:15], 0.5 op_sel_hi:[1,0]
	v_pk_mul_f32 v[76:77], v[12:13], 0.5 op_sel_hi:[1,0]
	v_pk_mul_f32 v[74:75], v[10:11], 0.5 op_sel_hi:[1,0]
	v_pk_mul_f32 v[72:73], v[28:29], 0.5 op_sel_hi:[1,0]
	v_pk_mul_f32 v[70:71], v[26:27], 0.5 op_sel_hi:[1,0]
	v_pk_mul_f32 v[68:69], v[20:21], 0.5 op_sel_hi:[1,0]
	v_pk_mul_f32 v[66:67], v[18:19], 0.5 op_sel_hi:[1,0]
	v_pk_mul_f32 v[64:65], v[8:9], 0.5 op_sel_hi:[1,0]
	v_pk_mul_f32 v[62:63], v[6:7], 0.5 op_sel_hi:[1,0]
	v_pk_mul_f32 v[60:61], v[4:5], 0.5 op_sel_hi:[1,0]
	v_pk_mul_f32 v[58:59], v[2:3], 0.5 op_sel_hi:[1,0]
	s_and_b64 vcc, exec, s[40:41]
	s_cbranch_vccz .LBB0_1522
